# adds GEMM mainloops: LDS-DMA groups issued in front of the fragment reads inside each load segment
# baseline (speedup 1.0000x reference)
; #define PG8_STAGE(bufoff, gbase, voff) do { _Pragma("unroll") for (int _i = 0; _i < 2; ++_i) \
;         __builtin_amdgcn_global_load_lds((const unsigned*)((const char*)(gbase) + (voff)[_i]), (PG8_LAS unsigned*)(lds + (bufoff) + ldsw + _i * 8192), 16, 0, 0); } while (0)
; #define PG8_LDA(dst, b, h) do { _Pragma("unroll") for (int m = 0; m < 4; ++m) _Pragma("unroll") for (int k = 0; k < 2; ++k) dst[m][k] = *(const PG8_LAS bf16x8*)(lds + PG8_SA(b, h) + aoff + m * 2048 + k * 1024); } while (0)
; #define PG8_LDB(dst, b, h) do { _Pragma("unroll") for (int n = 0; n < 2; ++n) _Pragma("unroll") for (int k = 0; k < 2; ++k) dst[n][k] = *(const PG8_LAS bf16x8*)(lds + PG8_SB(b, h) + boff + n * 2048 + k * 1024); } while (0)
; #define PG8_MMA(ai, bj, At, Bt) do { __builtin_amdgcn_s_setprio(1); _Pragma("unroll") for (int m = 0; m < 4; ++m) _Pragma("unroll") for (int n = 0; n < 2; ++n) _Pragma("unroll") for (int k = 0; k < 2; ++k) \
;         acc[ai][bj][m][n] = __builtin_amdgcn_mfma_f32_16x16x32_bf16(Bt[n][k], At[m][k], acc[ai][bj][m][n], 0, 0, 0); __builtin_amdgcn_s_setprio(0); } while (0)
; #define PG8_WAIT_V(n) asm volatile("s_waitcnt vmcnt(" #n ")" ::: "memory")
; #define PG8_WAIT_L(n) asm volatile("s_waitcnt lgkmcnt(" #n ")" ::: "memory")
; #define PG8_BAR __builtin_amdgcn_s_barrier()
; #define PG8_SCHED __builtin_amdgcn_sched_barrier(0)
; template <class Epi, class Sched, bool ALIGN_EPI = false, bool SP2 = false>
; __device__ __forceinline__ void gemm_phase(PG8_LAS unsigned char* lds, const Gemm g, const Sched& S, const Epi& E) {
;     ...
;             const char* a1 = cA + (size_t)(t + 1) * kstA;
;             const char* a2 = last ? nA : cA + (size_t)(t + 2) * kstA; const char* b2 = last ? nB : cB + (size_t)(t + 2) * kstep;
;             const char* a3 = a2 + kstA; const char* b3 = b2 + kstep;
;             if (last && has_next) S.a_ready(nxt);
;             if constexpr (SP2) {
;             PG8_LDB(B0, 0, 0); PG8_LDB(B1, 0, 1); PG8_SCHED; PG8_LDA(At, 0, 0); PG8_STAGE(PG8_SA(1, 1), a1 + hstepA, voffA);
;             PG8_WAIT_V(8); PG8_WAIT_L(0); PG8_BAR; PG8_MMA(0, 0, At, B0); PG8_MMA(0, 1, At, B1); PG8_BAR; PG8_SCHED;
;             PG8_LDA(At, 0, 1); PG8_STAGE(PG8_SB(0, 0), b2, voffB); PG8_STAGE(PG8_SB(0, 1), b2 + hstepB, voffB); PG8_STAGE(PG8_SA(0, 0), a2, voffA);
.LBB0_300:
	s_add_u32 s56, s50, 0xfff80080
	s_addc_u32 s57, s51, -1
	s_cmp_eq_u32 s61, 28
	s_cselect_b32 s59, s4, s57
	s_cselect_b32 s58, s5, s56
	s_cselect_b32 s57, s12, s43
	s_cselect_b32 s56, s13, s41
	v_lshl_add_u64 v[222:223], s[50:51], 0, v[142:143]
	s_add_i32 m0, s6, 0xc000
	s_nop 0
	global_load_lds_dwordx4 v[222:223], off
	v_lshl_add_u64 v[222:223], s[50:51], 0, v[144:145]
	s_add_i32 m0, s6, 0xe000
	s_nop 0
	global_load_lds_dwordx4 v[222:223], off
	ds_read_b128 v[156:159], v152
	ds_read_b128 v[160:163], v152 offset:1024
	ds_read_b128 v[164:167], v152 offset:2048
	ds_read_b128 v[168:171], v152 offset:3072
	ds_read_b128 v[172:175], v153
	ds_read_b128 v[176:179], v153 offset:1024
	ds_read_b128 v[180:183], v153 offset:2048
	ds_read_b128 v[186:189], v153 offset:3072
	ds_read_b128 v[190:193], v154
	ds_read_b128 v[194:197], v154 offset:1024
	ds_read_b128 v[198:201], v154 offset:2048
	ds_read_b128 v[202:205], v154 offset:3072
	ds_read_b128 v[206:209], v154 offset:4096
	ds_read_b128 v[210:213], v154 offset:5120
	ds_read_b128 v[214:217], v154 offset:6144
	ds_read_b128 v[218:221], v154 offset:7168
	s_waitcnt vmcnt(8)
	s_waitcnt lgkmcnt(0)
	s_setprio 1
	s_barrier
	v_mfma_f32_16x16x32_bf16 v[124:127], v[156:159], v[190:193], v[124:127]
	v_mfma_f32_16x16x32_bf16 v[120:123], v[164:167], v[190:193], v[120:123]
	v_mfma_f32_16x16x32_bf16 v[108:111], v[156:159], v[198:201], v[108:111]
	v_mfma_f32_16x16x32_bf16 v[104:107], v[164:167], v[198:201], v[104:107]
	v_mfma_f32_16x16x32_bf16 v[92:95], v[156:159], v[206:209], v[92:95]
	v_mfma_f32_16x16x32_bf16 v[88:91], v[164:167], v[206:209], v[88:91]
	v_mfma_f32_16x16x32_bf16 v[76:79], v[156:159], v[214:217], v[76:79]
	v_mfma_f32_16x16x32_bf16 v[72:75], v[164:167], v[214:217], v[72:75]
	v_mfma_f32_16x16x32_bf16 v[124:127], v[160:163], v[194:197], v[124:127]
	v_mfma_f32_16x16x32_bf16 v[120:123], v[168:171], v[194:197], v[120:123]
	v_mfma_f32_16x16x32_bf16 v[108:111], v[160:163], v[202:205], v[108:111]
	v_mfma_f32_16x16x32_bf16 v[104:107], v[168:171], v[202:205], v[104:107]
	v_mfma_f32_16x16x32_bf16 v[92:95], v[160:163], v[210:213], v[92:95]
	v_mfma_f32_16x16x32_bf16 v[88:91], v[168:171], v[210:213], v[88:91]
	v_mfma_f32_16x16x32_bf16 v[76:79], v[160:163], v[218:221], v[76:79]
	v_mfma_f32_16x16x32_bf16 v[72:75], v[168:171], v[218:221], v[72:75]
	s_setprio 0
	s_setprio 1
	v_mfma_f32_16x16x32_bf16 v[116:119], v[172:175], v[190:193], v[116:119]
	v_mfma_f32_16x16x32_bf16 v[112:115], v[180:183], v[190:193], v[112:115]
	v_mfma_f32_16x16x32_bf16 v[100:103], v[172:175], v[198:201], v[100:103]
	v_mfma_f32_16x16x32_bf16 v[96:99], v[180:183], v[198:201], v[96:99]
	v_mfma_f32_16x16x32_bf16 v[84:87], v[172:175], v[206:209], v[84:87]
	v_mfma_f32_16x16x32_bf16 v[80:83], v[180:183], v[206:209], v[80:83]
	v_mfma_f32_16x16x32_bf16 v[68:71], v[172:175], v[214:217], v[68:71]
	v_mfma_f32_16x16x32_bf16 v[64:67], v[180:183], v[214:217], v[64:67]
	v_mfma_f32_16x16x32_bf16 v[116:119], v[176:179], v[194:197], v[116:119]
	v_mfma_f32_16x16x32_bf16 v[112:115], v[186:189], v[194:197], v[112:115]
	v_mfma_f32_16x16x32_bf16 v[100:103], v[176:179], v[202:205], v[100:103]
	v_mfma_f32_16x16x32_bf16 v[96:99], v[186:189], v[202:205], v[96:99]
	v_mfma_f32_16x16x32_bf16 v[84:87], v[176:179], v[210:213], v[84:87]
	v_mfma_f32_16x16x32_bf16 v[80:83], v[186:189], v[210:213], v[80:83]
	v_mfma_f32_16x16x32_bf16 v[68:71], v[176:179], v[218:221], v[68:71]
	v_mfma_f32_16x16x32_bf16 v[64:67], v[186:189], v[218:221], v[64:67]
	s_barrier
	s_setprio 0
	s_add_i32 s62, s53, s3
	v_lshl_add_u64 v[222:223], s[56:57], 0, v[130:131]
	s_mov_b32 m0, s62
	s_nop 0
	global_load_lds_dwordx4 v[222:223], off
	s_add_i32 m0, s62, 0x2000
	s_add_u32 s62, s56, 0x80000
	v_lshl_add_u64 v[224:225], s[56:57], 0, v[134:135]
	s_addc_u32 s63, s57, 0
	s_add_i32 s64, s55, s3
	global_load_lds_dwordx4 v[224:225], off
	v_lshl_add_u64 v[226:227], s[62:63], 0, v[130:131]
	s_mov_b32 m0, s64
	v_lshl_add_u64 v[228:229], s[58:59], 0, v[132:133]
	global_load_lds_dwordx4 v[226:227], off
	v_lshl_add_u64 v[226:227], s[62:63], 0, v[134:135]
	s_add_i32 m0, s64, 0x2000
	s_nop 0
	global_load_lds_dwordx4 v[226:227], off
	v_lshl_add_u64 v[226:227], s[58:59], 0, v[128:129]
	s_mov_b32 m0, s6
	s_nop 0
	global_load_lds_dwordx4 v[226:227], off
	s_mov_b32 m0, s7
	s_nop 0
	global_load_lds_dwordx4 v[228:229], off
	ds_read_b128 v[190:193], v154 offset:16384
	ds_read_b128 v[194:197], v154 offset:17408
	ds_read_b128 v[198:201], v154 offset:18432
	ds_read_b128 v[202:205], v154 offset:19456
	ds_read_b128 v[206:209], v154 offset:20480
	ds_read_b128 v[210:213], v154 offset:21504
	ds_read_b128 v[214:217], v154 offset:22528
	ds_read_b128 v[218:221], v154 offset:23552
	s_waitcnt vmcnt(8)
	s_waitcnt lgkmcnt(0)
	s_setprio 1
	s_barrier
; #define PG8_STAGE(bufoff, gbase, voff) do { _Pragma("unroll") for (int _i = 0; _i < 2; ++_i) \
;         __builtin_amdgcn_global_load_lds((const unsigned*)((const char*)(gbase) + (voff)[_i]), (PG8_LAS unsigned*)(lds + (bufoff) + ldsw + _i * 8192), 16, 0, 0); } while (0)
; #define PG8_LDA(dst, b, h) do { _Pragma("unroll") for (int m = 0; m < 4; ++m) _Pragma("unroll") for (int k = 0; k < 2; ++k) dst[m][k] = *(const PG8_LAS bf16x8*)(lds + PG8_SA(b, h) + aoff + m * 2048 + k * 1024); } while (0)
; #define PG8_LDB(dst, b, h) do { _Pragma("unroll") for (int n = 0; n < 2; ++n) _Pragma("unroll") for (int k = 0; k < 2; ++k) dst[n][k] = *(const PG8_LAS bf16x8*)(lds + PG8_SB(b, h) + boff + n * 2048 + k * 1024); } while (0)
; #define PG8_MMA(ai, bj, At, Bt) do { __builtin_amdgcn_s_setprio(1); _Pragma("unroll") for (int m = 0; m < 4; ++m) _Pragma("unroll") for (int n = 0; n < 2; ++n) _Pragma("unroll") for (int k = 0; k < 2; ++k) \
;         acc[ai][bj][m][n] = __builtin_amdgcn_mfma_f32_16x16x32_bf16(Bt[n][k], At[m][k], acc[ai][bj][m][n], 0, 0, 0); __builtin_amdgcn_s_setprio(0); } while (0)
; #define PG8_WAIT_V(n) asm volatile("s_waitcnt vmcnt(" #n ")" ::: "memory")
; #define PG8_WAIT_L(n) asm volatile("s_waitcnt lgkmcnt(" #n ")" ::: "memory")
; #define PG8_BAR __builtin_amdgcn_s_barrier()
; #define PG8_SCHED __builtin_amdgcn_sched_barrier(0)
; template <class Epi, class Sched, bool ALIGN_EPI = false, bool SP2 = false>
; __device__ __forceinline__ void gemm_phase(PG8_LAS unsigned char* lds, const Gemm g, const Sched& S, const Epi& E) {
;     ...
;             PG8_WAIT_V(8); PG8_WAIT_L(0); PG8_BAR; PG8_MMA(1, 0, At, B0); PG8_MMA(1, 1, At, B1); PG8_BAR; PG8_SCHED;
;             PG8_LDB(B0, 1, 0); PG8_LDB(B1, 1, 1); PG8_SCHED; PG8_LDA(At, 1, 0); PG8_STAGE(PG8_SA(0, 1), a2 + hstepA, voffA);
;             PG8_WAIT_V(8); PG8_WAIT_L(0); PG8_BAR; PG8_MMA(0, 0, At, B0); PG8_MMA(0, 1, At, B1); PG8_BAR; PG8_SCHED;
	v_mfma_f32_16x16x32_bf16 v[60:63], v[156:159], v[190:193], v[60:63]
	v_mfma_f32_16x16x32_bf16 v[56:59], v[164:167], v[190:193], v[56:59]
	v_mfma_f32_16x16x32_bf16 v[44:47], v[156:159], v[198:201], v[44:47]
	v_mfma_f32_16x16x32_bf16 v[40:43], v[164:167], v[198:201], v[40:43]
	v_mfma_f32_16x16x32_bf16 v[28:31], v[156:159], v[206:209], v[28:31]
	v_mfma_f32_16x16x32_bf16 v[24:27], v[164:167], v[206:209], v[24:27]
	v_mfma_f32_16x16x32_bf16 v[12:15], v[156:159], v[214:217], v[12:15]
	v_mfma_f32_16x16x32_bf16 v[8:11], v[164:167], v[214:217], v[8:11]
	v_mfma_f32_16x16x32_bf16 v[60:63], v[160:163], v[194:197], v[60:63]
	v_mfma_f32_16x16x32_bf16 v[56:59], v[168:171], v[194:197], v[56:59]
	v_mfma_f32_16x16x32_bf16 v[44:47], v[160:163], v[202:205], v[44:47]
	v_mfma_f32_16x16x32_bf16 v[40:43], v[168:171], v[202:205], v[40:43]
	v_mfma_f32_16x16x32_bf16 v[28:31], v[160:163], v[210:213], v[28:31]
	v_mfma_f32_16x16x32_bf16 v[24:27], v[168:171], v[210:213], v[24:27]
	v_mfma_f32_16x16x32_bf16 v[12:15], v[160:163], v[218:221], v[12:15]
	v_mfma_f32_16x16x32_bf16 v[8:11], v[168:171], v[218:221], v[8:11]
	s_setprio 0
	s_setprio 1
	v_mfma_f32_16x16x32_bf16 v[52:55], v[172:175], v[190:193], v[52:55]
	v_mfma_f32_16x16x32_bf16 v[48:51], v[180:183], v[190:193], v[48:51]
	v_mfma_f32_16x16x32_bf16 v[36:39], v[172:175], v[198:201], v[36:39]
	v_mfma_f32_16x16x32_bf16 v[32:35], v[180:183], v[198:201], v[32:35]
	v_mfma_f32_16x16x32_bf16 v[20:23], v[172:175], v[206:209], v[20:23]
	v_mfma_f32_16x16x32_bf16 v[16:19], v[180:183], v[206:209], v[16:19]
	v_mfma_f32_16x16x32_bf16 v[4:7], v[172:175], v[214:217], v[4:7]
	v_mfma_f32_16x16x32_bf16 v[0:3], v[180:183], v[214:217], v[0:3]
	v_mfma_f32_16x16x32_bf16 v[52:55], v[176:179], v[194:197], v[52:55]
	v_mfma_f32_16x16x32_bf16 v[48:51], v[186:189], v[194:197], v[48:51]
	v_mfma_f32_16x16x32_bf16 v[36:39], v[176:179], v[202:205], v[36:39]
	v_mfma_f32_16x16x32_bf16 v[32:35], v[186:189], v[202:205], v[32:35]
	v_mfma_f32_16x16x32_bf16 v[20:23], v[176:179], v[210:213], v[20:23]
	v_mfma_f32_16x16x32_bf16 v[16:19], v[186:189], v[210:213], v[16:19]
	v_mfma_f32_16x16x32_bf16 v[4:7], v[176:179], v[218:221], v[4:7]
	v_mfma_f32_16x16x32_bf16 v[0:3], v[186:189], v[218:221], v[0:3]
	s_barrier
	s_setprio 0
	s_add_i32 s62, 0, 0x18000
	s_add_i32 s63, 0, 0x1c000
	s_add_u32 s58, s58, 0x80000
	s_addc_u32 s59, s59, 0
	s_mov_b32 m0, s8
	v_lshl_add_u64 v[230:231], s[58:59], 0, v[128:129]
	global_load_lds_dwordx4 v[230:231], off
	v_lshl_add_u64 v[230:231], s[58:59], 0, v[132:133]
	s_mov_b32 m0, s9
	s_nop 0
	global_load_lds_dwordx4 v[230:231], off
	v_add_u32_e32 v155, s62, v150
	ds_read_b128 v[156:159], v155
	ds_read_b128 v[160:163], v155 offset:1024
	ds_read_b128 v[164:167], v155 offset:2048
	ds_read_b128 v[168:171], v155 offset:3072
	v_add_u32_e32 v155, s63, v150
	ds_read_b128 v[172:175], v155
	ds_read_b128 v[176:179], v155 offset:1024
	ds_read_b128 v[180:183], v155 offset:2048
	ds_read_b128 v[186:189], v155 offset:3072
	ds_read_b128 v[190:193], v154 offset:32768
	ds_read_b128 v[194:197], v154 offset:33792
	ds_read_b128 v[198:201], v154 offset:34816
	ds_read_b128 v[202:205], v154 offset:35840
	ds_read_b128 v[206:209], v154 offset:36864
	ds_read_b128 v[210:213], v154 offset:37888
	ds_read_b128 v[214:217], v154 offset:38912
	ds_read_b128 v[218:221], v154 offset:39936
	s_waitcnt vmcnt(8)
	s_waitcnt lgkmcnt(0)
	s_setprio 1
	s_barrier
	v_mfma_f32_16x16x32_bf16 v[124:127], v[156:159], v[190:193], v[124:127]
	v_mfma_f32_16x16x32_bf16 v[120:123], v[164:167], v[190:193], v[120:123]
	v_mfma_f32_16x16x32_bf16 v[108:111], v[156:159], v[198:201], v[108:111]
	v_mfma_f32_16x16x32_bf16 v[104:107], v[164:167], v[198:201], v[104:107]
	v_mfma_f32_16x16x32_bf16 v[92:95], v[156:159], v[206:209], v[92:95]
	v_mfma_f32_16x16x32_bf16 v[88:91], v[164:167], v[206:209], v[88:91]
	v_mfma_f32_16x16x32_bf16 v[76:79], v[156:159], v[214:217], v[76:79]
	v_mfma_f32_16x16x32_bf16 v[72:75], v[164:167], v[214:217], v[72:75]
	v_mfma_f32_16x16x32_bf16 v[124:127], v[160:163], v[194:197], v[124:127]
	v_mfma_f32_16x16x32_bf16 v[120:123], v[168:171], v[194:197], v[120:123]
	v_mfma_f32_16x16x32_bf16 v[108:111], v[160:163], v[202:205], v[108:111]
	v_mfma_f32_16x16x32_bf16 v[104:107], v[168:171], v[202:205], v[104:107]
	v_mfma_f32_16x16x32_bf16 v[92:95], v[160:163], v[210:213], v[92:95]
	v_mfma_f32_16x16x32_bf16 v[88:91], v[168:171], v[210:213], v[88:91]
	v_mfma_f32_16x16x32_bf16 v[76:79], v[160:163], v[218:221], v[76:79]
	v_mfma_f32_16x16x32_bf16 v[72:75], v[168:171], v[218:221], v[72:75]
	s_setprio 0
	s_setprio 1
	v_mfma_f32_16x16x32_bf16 v[116:119], v[172:175], v[190:193], v[116:119]
	v_mfma_f32_16x16x32_bf16 v[112:115], v[180:183], v[190:193], v[112:115]
	v_mfma_f32_16x16x32_bf16 v[100:103], v[172:175], v[198:201], v[100:103]
	v_mfma_f32_16x16x32_bf16 v[96:99], v[180:183], v[198:201], v[96:99]
	v_mfma_f32_16x16x32_bf16 v[84:87], v[172:175], v[206:209], v[84:87]
	v_mfma_f32_16x16x32_bf16 v[80:83], v[180:183], v[206:209], v[80:83]
	v_mfma_f32_16x16x32_bf16 v[68:71], v[172:175], v[214:217], v[68:71]
	v_mfma_f32_16x16x32_bf16 v[64:67], v[180:183], v[214:217], v[64:67]
	v_mfma_f32_16x16x32_bf16 v[116:119], v[176:179], v[194:197], v[116:119]
	v_mfma_f32_16x16x32_bf16 v[112:115], v[186:189], v[194:197], v[112:115]
	v_mfma_f32_16x16x32_bf16 v[100:103], v[176:179], v[202:205], v[100:103]
	v_mfma_f32_16x16x32_bf16 v[96:99], v[186:189], v[202:205], v[96:99]
	v_mfma_f32_16x16x32_bf16 v[84:87], v[176:179], v[210:213], v[84:87]
	v_mfma_f32_16x16x32_bf16 v[80:83], v[186:189], v[210:213], v[80:83]
	v_mfma_f32_16x16x32_bf16 v[68:71], v[176:179], v[218:221], v[68:71]
	v_mfma_f32_16x16x32_bf16 v[64:67], v[186:189], v[218:221], v[64:67]
	s_barrier
; #define PG8_STAGE(bufoff, gbase, voff) do { _Pragma("unroll") for (int _i = 0; _i < 2; ++_i) \
;         __builtin_amdgcn_global_load_lds((const unsigned*)((const char*)(gbase) + (voff)[_i]), (PG8_LAS unsigned*)(lds + (bufoff) + ldsw + _i * 8192), 16, 0, 0); } while (0)
; #define PG8_LDA(dst, b, h) do { _Pragma("unroll") for (int m = 0; m < 4; ++m) _Pragma("unroll") for (int k = 0; k < 2; ++k) dst[m][k] = *(const PG8_LAS bf16x8*)(lds + PG8_SA(b, h) + aoff + m * 2048 + k * 1024); } while (0)
; #define PG8_MMA(ai, bj, At, Bt) do { __builtin_amdgcn_s_setprio(1); _Pragma("unroll") for (int m = 0; m < 4; ++m) _Pragma("unroll") for (int n = 0; n < 2; ++n) _Pragma("unroll") for (int k = 0; k < 2; ++k) \
;         acc[ai][bj][m][n] = __builtin_amdgcn_mfma_f32_16x16x32_bf16(Bt[n][k], At[m][k], acc[ai][bj][m][n], 0, 0, 0); __builtin_amdgcn_s_setprio(0); } while (0)
; #define PG8_WAIT_V(n) asm volatile("s_waitcnt vmcnt(" #n ")" ::: "memory")
; #define PG8_WAIT_L(n) asm volatile("s_waitcnt lgkmcnt(" #n ")" ::: "memory")
; #define PG8_BAR __builtin_amdgcn_s_barrier()
; #define PG8_SCHED __builtin_amdgcn_sched_barrier(0)
; template <class Epi, class Sched, bool ALIGN_EPI = false, bool SP2 = false>
; __device__ __forceinline__ void gemm_phase(PG8_LAS unsigned char* lds, const Gemm g, const Sched& S, const Epi& E) {
;     ...
;             PG8_LDA(At, 1, 1); PG8_STAGE(PG8_SB(1, 0), b3, voffB); PG8_STAGE(PG8_SB(1, 1), b3 + hstepB, voffB); PG8_STAGE(PG8_SA(1, 0), a3, voffA);
;             PG8_WAIT_V(8); PG8_WAIT_L(0); PG8_BAR; PG8_MMA(1, 0, At, B0); PG8_MMA(1, 1, At, B1); PG8_BAR; PG8_SCHED;
	s_setprio 0
	s_add_i32 s58, s62, s3
	v_lshl_add_u64 v[222:223], v[222:223], 0, s[36:37]
	s_mov_b32 m0, s58
	s_nop 0
	global_load_lds_dwordx4 v[222:223], off
	s_add_i32 m0, s58, 0x2000
	s_add_u32 s56, s56, 0x80080
	v_lshl_add_u64 v[222:223], v[224:225], 0, s[36:37]
	s_addc_u32 s57, s57, 0
	s_add_i32 s58, s63, s3
	global_load_lds_dwordx4 v[222:223], off
	v_lshl_add_u64 v[222:223], s[56:57], 0, v[130:131]
	s_mov_b32 m0, s58
	s_nop 0
	global_load_lds_dwordx4 v[222:223], off
	v_lshl_add_u64 v[222:223], s[56:57], 0, v[134:135]
	s_add_i32 m0, s58, 0x2000
	s_nop 0
	global_load_lds_dwordx4 v[222:223], off
	v_lshl_add_u64 v[222:223], v[226:227], 0, s[36:37]
	s_mov_b32 m0, s44
	s_nop 0
	global_load_lds_dwordx4 v[222:223], off
	v_lshl_add_u64 v[222:223], v[228:229], 0, s[36:37]
	s_mov_b32 m0, s45
	s_nop 0
	global_load_lds_dwordx4 v[222:223], off
	ds_read_b128 v[190:193], v154 offset:49152
	ds_read_b128 v[194:197], v154 offset:50176
	ds_read_b128 v[198:201], v154 offset:51200
	ds_read_b128 v[202:205], v154 offset:52224
	ds_read_b128 v[206:209], v154 offset:53248
	ds_read_b128 v[210:213], v154 offset:54272
	ds_read_b128 v[214:217], v154 offset:55296
	ds_read_b128 v[218:221], v154 offset:56320
	s_waitcnt vmcnt(8)
	s_waitcnt lgkmcnt(0)
	s_setprio 1
	s_barrier
	v_mfma_f32_16x16x32_bf16 v[60:63], v[156:159], v[190:193], v[60:63]
	v_mfma_f32_16x16x32_bf16 v[56:59], v[164:167], v[190:193], v[56:59]
	v_mfma_f32_16x16x32_bf16 v[44:47], v[156:159], v[198:201], v[44:47]
	v_mfma_f32_16x16x32_bf16 v[40:43], v[164:167], v[198:201], v[40:43]
	v_mfma_f32_16x16x32_bf16 v[28:31], v[156:159], v[206:209], v[28:31]
	v_mfma_f32_16x16x32_bf16 v[24:27], v[164:167], v[206:209], v[24:27]
	v_mfma_f32_16x16x32_bf16 v[12:15], v[156:159], v[214:217], v[12:15]
	v_mfma_f32_16x16x32_bf16 v[8:11], v[164:167], v[214:217], v[8:11]
	v_mfma_f32_16x16x32_bf16 v[60:63], v[160:163], v[194:197], v[60:63]
	v_mfma_f32_16x16x32_bf16 v[56:59], v[168:171], v[194:197], v[56:59]
	v_mfma_f32_16x16x32_bf16 v[44:47], v[160:163], v[202:205], v[44:47]
	v_mfma_f32_16x16x32_bf16 v[40:43], v[168:171], v[202:205], v[40:43]
	v_mfma_f32_16x16x32_bf16 v[28:31], v[160:163], v[210:213], v[28:31]
	v_mfma_f32_16x16x32_bf16 v[24:27], v[168:171], v[210:213], v[24:27]
	v_mfma_f32_16x16x32_bf16 v[12:15], v[160:163], v[218:221], v[12:15]
	v_mfma_f32_16x16x32_bf16 v[8:11], v[168:171], v[218:221], v[8:11]
	s_setprio 0
	s_setprio 1
	v_mfma_f32_16x16x32_bf16 v[52:55], v[172:175], v[190:193], v[52:55]
	v_mfma_f32_16x16x32_bf16 v[48:51], v[180:183], v[190:193], v[48:51]
	v_mfma_f32_16x16x32_bf16 v[36:39], v[172:175], v[198:201], v[36:39]
	v_mfma_f32_16x16x32_bf16 v[32:35], v[180:183], v[198:201], v[32:35]
	v_mfma_f32_16x16x32_bf16 v[20:23], v[172:175], v[206:209], v[20:23]
	v_mfma_f32_16x16x32_bf16 v[16:19], v[180:183], v[206:209], v[16:19]
	v_mfma_f32_16x16x32_bf16 v[4:7], v[172:175], v[214:217], v[4:7]
	v_mfma_f32_16x16x32_bf16 v[0:3], v[180:183], v[214:217], v[0:3]
	v_mfma_f32_16x16x32_bf16 v[52:55], v[176:179], v[194:197], v[52:55]
	v_mfma_f32_16x16x32_bf16 v[48:51], v[186:189], v[194:197], v[48:51]
	v_mfma_f32_16x16x32_bf16 v[36:39], v[176:179], v[202:205], v[36:39]
	v_mfma_f32_16x16x32_bf16 v[32:35], v[186:189], v[202:205], v[32:35]
	v_mfma_f32_16x16x32_bf16 v[20:23], v[176:179], v[210:213], v[20:23]
	v_mfma_f32_16x16x32_bf16 v[16:19], v[186:189], v[210:213], v[16:19]
	v_mfma_f32_16x16x32_bf16 v[4:7], v[176:179], v[218:221], v[4:7]
	v_mfma_f32_16x16x32_bf16 v[0:3], v[186:189], v[218:221], v[0:3]
	s_barrier
	s_setprio 0
	s_add_i32 s61, s61, 2
	s_add_u32 s50, s50, 0x100
	s_addc_u32 s51, s51, 0
	s_add_u32 s41, s41, 0x100
	s_addc_u32 s43, s43, 0
	s_cmp_gt_u32 s61, 29
	s_cbranch_scc0 .LBB0_300
	s_and_b64 vcc, exec, s[38:39]
	s_cbranch_vccz .LBB0_303
	s_barrier

; #define PG8_STAGE(bufoff, gbase, voff) do { _Pragma("unroll") for (int _i = 0; _i < 2; ++_i) \
;         __builtin_amdgcn_global_load_lds((const unsigned*)((const char*)(gbase) + (voff)[_i]), (PG8_LAS unsigned*)(lds + (bufoff) + ldsw + _i * 8192), 16, 0, 0); } while (0)
; #define PG8_LDA(dst, b, h) do { _Pragma("unroll") for (int m = 0; m < 4; ++m) _Pragma("unroll") for (int k = 0; k < 2; ++k) dst[m][k] = *(const PG8_LAS bf16x8*)(lds + PG8_SA(b, h) + aoff + m * 2048 + k * 1024); } while (0)
; #define PG8_LDB(dst, b, h) do { _Pragma("unroll") for (int n = 0; n < 2; ++n) _Pragma("unroll") for (int k = 0; k < 2; ++k) dst[n][k] = *(const PG8_LAS bf16x8*)(lds + PG8_SB(b, h) + boff + n * 2048 + k * 1024); } while (0)
; #define PG8_MMA(ai, bj, At, Bt) do { __builtin_amdgcn_s_setprio(1); _Pragma("unroll") for (int m = 0; m < 4; ++m) _Pragma("unroll") for (int n = 0; n < 2; ++n) _Pragma("unroll") for (int k = 0; k < 2; ++k) \
;         acc[ai][bj][m][n] = __builtin_amdgcn_mfma_f32_16x16x32_bf16(Bt[n][k], At[m][k], acc[ai][bj][m][n], 0, 0, 0); __builtin_amdgcn_s_setprio(0); } while (0)
; #define PG8_WAIT_V(n) asm volatile("s_waitcnt vmcnt(" #n ")" ::: "memory")
; #define PG8_WAIT_L(n) asm volatile("s_waitcnt lgkmcnt(" #n ")" ::: "memory")
; #define PG8_BAR __builtin_amdgcn_s_barrier()
; #define PG8_SCHED __builtin_amdgcn_sched_barrier(0)
; template <class Epi, class Sched, bool ALIGN_EPI = false, bool SP2 = false>
; __device__ __forceinline__ void gemm_phase(PG8_LAS unsigned char* lds, const Gemm g, const Sched& S, const Epi& E) {
;     ...
;         for (int t = 0; t < nt; t += 2) {
;             const bool last = (t == nt - 2);
;             const char* a1 = cA + (size_t)(t + 1) * kstA;
;             const char* a2 = last ? nA : cA + (size_t)(t + 2) * kstA; const char* b2 = last ? nB : cB + (size_t)(t + 2) * kstep;
;             const char* a3 = a2 + kstA; const char* b3 = b2 + kstep;
;             if (last && has_next) S.a_ready(nxt);
;             if constexpr (SP2) {
;             PG8_LDB(B0, 0, 0); PG8_LDB(B1, 0, 1); PG8_SCHED; PG8_LDA(At, 0, 0); PG8_STAGE(PG8_SA(1, 1), a1 + hstepA, voffA);
;             PG8_WAIT_V(8); PG8_WAIT_L(0); PG8_BAR; PG8_MMA(0, 0, At, B0); PG8_MMA(0, 1, At, B1); PG8_BAR; PG8_SCHED;
;             PG8_LDA(At, 0, 1); PG8_STAGE(PG8_SB(0, 0), b2, voffB); PG8_STAGE(PG8_SB(0, 1), b2 + hstepB, voffB); PG8_STAGE(PG8_SA(0, 0), a2, voffA);
.LBB0_397:
	s_or_b32 s42, s74, 1
	s_add_i32 s74, s74, 2
	s_mov_b32 s75, s43
	s_lshl_b64 s[4:5], s[42:43], 15
	s_lshl_b64 s[12:13], s[74:75], 15
	s_add_u32 s42, s38, s12
	s_addc_u32 s46, s39, s13
	s_and_b64 s[12:13], s[50:51], exec
	s_cselect_b32 s59, s46, s61
	s_cselect_b32 s58, s42, s60
	s_lshl_b64 s[12:13], s[74:75], 7
	s_add_u32 s42, s40, s12
	s_addc_u32 s46, s41, s13
	s_and_b64 s[12:13], s[50:51], exec
	s_cselect_b32 s53, s46, s63
	s_cselect_b32 s52, s42, s62
	s_add_u32 s50, s58, 0x8000
	s_addc_u32 s51, s59, 0
	s_add_u32 s4, s35, s4
	s_addc_u32 s5, s65, s5
	v_lshl_add_u64 v[174:175], s[4:5], 0, v[128:129]
	s_add_i32 m0, s66, 0xc000
	s_nop 0
	global_load_lds_dwordx4 v[174:175], off
	v_lshl_add_u64 v[174:175], s[4:5], 0, v[132:133]
	s_add_i32 m0, s66, 0xe000
	s_nop 0
	global_load_lds_dwordx4 v[174:175], off
	v_add_u32_e32 v170, s10, v177
	v_add_u32_e32 v174, s11, v177
	ds_read_b128 v[158:161], v170
	ds_read_b128 v[162:165], v170 offset:1024
	ds_read_b128 v[166:169], v170 offset:2048
	ds_read_b128 v[170:173], v170 offset:3072
	ds_read_b128 v[180:183], v174
	ds_read_b128 v[186:189], v174 offset:1024
	ds_read_b128 v[190:193], v174 offset:2048
	ds_read_b128 v[194:197], v174 offset:3072
	ds_read_b128 v[198:201], v179
	ds_read_b128 v[202:205], v179 offset:1024
	ds_read_b128 v[206:209], v179 offset:2048
	ds_read_b128 v[210:213], v179 offset:3072
	ds_read_b128 v[214:217], v179 offset:4096
	ds_read_b128 v[218:221], v179 offset:5120
	ds_read_b128 v[222:225], v179 offset:6144
	ds_read_b128 v[226:229], v179 offset:7168
	s_waitcnt vmcnt(8)
	s_waitcnt lgkmcnt(0)
	s_setprio 1
	s_barrier
	v_mfma_f32_16x16x32_bf16 v[124:127], v[158:161], v[198:201], v[124:127]
	v_mfma_f32_16x16x32_bf16 v[120:123], v[166:169], v[198:201], v[120:123]
	v_mfma_f32_16x16x32_bf16 v[116:119], v[158:161], v[206:209], v[116:119]
	v_mfma_f32_16x16x32_bf16 v[112:115], v[166:169], v[206:209], v[112:115]
	v_mfma_f32_16x16x32_bf16 v[108:111], v[158:161], v[214:217], v[108:111]
	v_mfma_f32_16x16x32_bf16 v[104:107], v[166:169], v[214:217], v[104:107]
	v_mfma_f32_16x16x32_bf16 v[100:103], v[158:161], v[222:225], v[100:103]
	v_mfma_f32_16x16x32_bf16 v[96:99], v[166:169], v[222:225], v[96:99]
	v_mfma_f32_16x16x32_bf16 v[124:127], v[162:165], v[202:205], v[124:127]
	v_mfma_f32_16x16x32_bf16 v[120:123], v[170:173], v[202:205], v[120:123]
	v_mfma_f32_16x16x32_bf16 v[116:119], v[162:165], v[210:213], v[116:119]
	v_mfma_f32_16x16x32_bf16 v[112:115], v[170:173], v[210:213], v[112:115]
	v_mfma_f32_16x16x32_bf16 v[108:111], v[162:165], v[218:221], v[108:111]
	v_mfma_f32_16x16x32_bf16 v[104:107], v[170:173], v[218:221], v[104:107]
	v_mfma_f32_16x16x32_bf16 v[100:103], v[162:165], v[226:229], v[100:103]
	v_mfma_f32_16x16x32_bf16 v[96:99], v[170:173], v[226:229], v[96:99]
	s_setprio 0
	s_setprio 1
	v_mfma_f32_16x16x32_bf16 v[92:95], v[180:183], v[198:201], v[92:95]
	v_mfma_f32_16x16x32_bf16 v[88:91], v[190:193], v[198:201], v[88:91]
	v_mfma_f32_16x16x32_bf16 v[84:87], v[180:183], v[206:209], v[84:87]
	v_mfma_f32_16x16x32_bf16 v[80:83], v[190:193], v[206:209], v[80:83]
	v_mfma_f32_16x16x32_bf16 v[76:79], v[180:183], v[214:217], v[76:79]
	v_mfma_f32_16x16x32_bf16 v[72:75], v[190:193], v[214:217], v[72:75]
	v_mfma_f32_16x16x32_bf16 v[68:71], v[180:183], v[222:225], v[68:71]
	v_mfma_f32_16x16x32_bf16 v[64:67], v[190:193], v[222:225], v[64:67]
	v_mfma_f32_16x16x32_bf16 v[92:95], v[186:189], v[202:205], v[92:95]
	v_mfma_f32_16x16x32_bf16 v[88:91], v[194:197], v[202:205], v[88:91]
	v_mfma_f32_16x16x32_bf16 v[84:87], v[186:189], v[210:213], v[84:87]
	v_mfma_f32_16x16x32_bf16 v[80:83], v[194:197], v[210:213], v[80:83]
	v_mfma_f32_16x16x32_bf16 v[76:79], v[186:189], v[218:221], v[76:79]
	v_mfma_f32_16x16x32_bf16 v[72:75], v[194:197], v[218:221], v[72:75]
	v_mfma_f32_16x16x32_bf16 v[68:71], v[186:189], v[226:229], v[68:71]
	v_mfma_f32_16x16x32_bf16 v[64:67], v[194:197], v[226:229], v[64:67]
	s_barrier
	s_setprio 0
	s_add_i32 s4, s10, s9
	v_lshl_add_u64 v[174:175], s[52:53], 0, v[130:131]
	s_mov_b32 m0, s4
	s_nop 0
	global_load_lds_dwordx4 v[174:175], off
	s_add_i32 m0, s4, 0x2000
	s_add_u32 s4, s52, 0x160000
	v_lshl_add_u64 v[230:231], s[52:53], 0, v[134:135]
	s_addc_u32 s5, s53, 0
	s_add_i32 s12, s11, s9
	global_load_lds_dwordx4 v[230:231], off
	v_lshl_add_u64 v[232:233], s[4:5], 0, v[130:131]
	s_mov_b32 m0, s12
	s_nop 0
	global_load_lds_dwordx4 v[232:233], off
	v_lshl_add_u64 v[232:233], s[4:5], 0, v[134:135]
	s_add_i32 m0, s12, 0x2000
	s_nop 0
	global_load_lds_dwordx4 v[232:233], off
	v_lshl_add_u64 v[232:233], s[58:59], 0, v[128:129]
	s_mov_b32 m0, s66
	s_nop 0
	global_load_lds_dwordx4 v[232:233], off
	v_lshl_add_u64 v[232:233], s[58:59], 0, v[132:133]
	s_mov_b32 m0, s67
	s_nop 0
	global_load_lds_dwordx4 v[232:233], off
	ds_read_b128 v[198:201], v179 offset:16384
	ds_read_b128 v[202:205], v179 offset:17408
	ds_read_b128 v[206:209], v179 offset:18432
	ds_read_b128 v[210:213], v179 offset:19456
	ds_read_b128 v[214:217], v179 offset:20480
	ds_read_b128 v[218:221], v179 offset:21504
	ds_read_b128 v[222:225], v179 offset:22528
	ds_read_b128 v[226:229], v179 offset:23552
	s_waitcnt vmcnt(8)
	s_waitcnt lgkmcnt(0)
	s_setprio 1
	s_barrier
; #define PG8_STAGE(bufoff, gbase, voff) do { _Pragma("unroll") for (int _i = 0; _i < 2; ++_i) \
;         __builtin_amdgcn_global_load_lds((const unsigned*)((const char*)(gbase) + (voff)[_i]), (PG8_LAS unsigned*)(lds + (bufoff) + ldsw + _i * 8192), 16, 0, 0); } while (0)
; #define PG8_LDA(dst, b, h) do { _Pragma("unroll") for (int m = 0; m < 4; ++m) _Pragma("unroll") for (int k = 0; k < 2; ++k) dst[m][k] = *(const PG8_LAS bf16x8*)(lds + PG8_SA(b, h) + aoff + m * 2048 + k * 1024); } while (0)
; #define PG8_LDB(dst, b, h) do { _Pragma("unroll") for (int n = 0; n < 2; ++n) _Pragma("unroll") for (int k = 0; k < 2; ++k) dst[n][k] = *(const PG8_LAS bf16x8*)(lds + PG8_SB(b, h) + boff + n * 2048 + k * 1024); } while (0)
; #define PG8_MMA(ai, bj, At, Bt) do { __builtin_amdgcn_s_setprio(1); _Pragma("unroll") for (int m = 0; m < 4; ++m) _Pragma("unroll") for (int n = 0; n < 2; ++n) _Pragma("unroll") for (int k = 0; k < 2; ++k) \
;         acc[ai][bj][m][n] = __builtin_amdgcn_mfma_f32_16x16x32_bf16(Bt[n][k], At[m][k], acc[ai][bj][m][n], 0, 0, 0); __builtin_amdgcn_s_setprio(0); } while (0)
; #define PG8_WAIT_V(n) asm volatile("s_waitcnt vmcnt(" #n ")" ::: "memory")
; #define PG8_WAIT_L(n) asm volatile("s_waitcnt lgkmcnt(" #n ")" ::: "memory")
; #define PG8_BAR __builtin_amdgcn_s_barrier()
; #define PG8_SCHED __builtin_amdgcn_sched_barrier(0)
; template <class Epi, class Sched, bool ALIGN_EPI = false, bool SP2 = false>
; __device__ __forceinline__ void gemm_phase(PG8_LAS unsigned char* lds, const Gemm g, const Sched& S, const Epi& E) {
;     ...
;             PG8_WAIT_V(8); PG8_WAIT_L(0); PG8_BAR; PG8_MMA(1, 0, At, B0); PG8_MMA(1, 1, At, B1); PG8_BAR; PG8_SCHED;
;             PG8_LDB(B0, 1, 0); PG8_LDB(B1, 1, 1); PG8_SCHED; PG8_LDA(At, 1, 0); PG8_STAGE(PG8_SA(0, 1), a2 + hstepA, voffA);
;             PG8_WAIT_V(8); PG8_WAIT_L(0); PG8_BAR; PG8_MMA(0, 0, At, B0); PG8_MMA(0, 1, At, B1); PG8_BAR; PG8_SCHED;
	v_mfma_f32_16x16x32_bf16 v[60:63], v[158:161], v[198:201], v[60:63]
	v_mfma_f32_16x16x32_bf16 v[56:59], v[166:169], v[198:201], v[56:59]
	v_mfma_f32_16x16x32_bf16 v[52:55], v[158:161], v[206:209], v[52:55]
	v_mfma_f32_16x16x32_bf16 v[48:51], v[166:169], v[206:209], v[48:51]
	v_mfma_f32_16x16x32_bf16 v[44:47], v[158:161], v[214:217], v[44:47]
	v_mfma_f32_16x16x32_bf16 v[40:43], v[166:169], v[214:217], v[40:43]
	v_mfma_f32_16x16x32_bf16 v[36:39], v[158:161], v[222:225], v[36:39]
	v_mfma_f32_16x16x32_bf16 v[32:35], v[166:169], v[222:225], v[32:35]
	v_mfma_f32_16x16x32_bf16 v[60:63], v[162:165], v[202:205], v[60:63]
	v_mfma_f32_16x16x32_bf16 v[56:59], v[170:173], v[202:205], v[56:59]
	v_mfma_f32_16x16x32_bf16 v[52:55], v[162:165], v[210:213], v[52:55]
	v_mfma_f32_16x16x32_bf16 v[48:51], v[170:173], v[210:213], v[48:51]
	v_mfma_f32_16x16x32_bf16 v[44:47], v[162:165], v[218:221], v[44:47]
	v_mfma_f32_16x16x32_bf16 v[40:43], v[170:173], v[218:221], v[40:43]
	v_mfma_f32_16x16x32_bf16 v[36:39], v[162:165], v[226:229], v[36:39]
	v_mfma_f32_16x16x32_bf16 v[32:35], v[170:173], v[226:229], v[32:35]
	s_setprio 0
	s_setprio 1
	v_mfma_f32_16x16x32_bf16 v[28:31], v[180:183], v[198:201], v[28:31]
	v_mfma_f32_16x16x32_bf16 v[24:27], v[190:193], v[198:201], v[24:27]
	v_mfma_f32_16x16x32_bf16 v[20:23], v[180:183], v[206:209], v[20:23]
	v_mfma_f32_16x16x32_bf16 v[16:19], v[190:193], v[206:209], v[16:19]
	v_mfma_f32_16x16x32_bf16 v[12:15], v[180:183], v[214:217], v[12:15]
	v_mfma_f32_16x16x32_bf16 v[8:11], v[190:193], v[214:217], v[8:11]
	v_mfma_f32_16x16x32_bf16 v[4:7], v[180:183], v[222:225], v[4:7]
	v_mfma_f32_16x16x32_bf16 v[0:3], v[190:193], v[222:225], v[0:3]
	v_mfma_f32_16x16x32_bf16 v[28:31], v[186:189], v[202:205], v[28:31]
	v_mfma_f32_16x16x32_bf16 v[24:27], v[194:197], v[202:205], v[24:27]
	v_mfma_f32_16x16x32_bf16 v[20:23], v[186:189], v[210:213], v[20:23]
	v_mfma_f32_16x16x32_bf16 v[16:19], v[194:197], v[210:213], v[16:19]
	v_mfma_f32_16x16x32_bf16 v[12:15], v[186:189], v[218:221], v[12:15]
	v_mfma_f32_16x16x32_bf16 v[8:11], v[194:197], v[218:221], v[8:11]
	v_mfma_f32_16x16x32_bf16 v[4:7], v[186:189], v[226:229], v[4:7]
	v_mfma_f32_16x16x32_bf16 v[0:3], v[194:197], v[226:229], v[0:3]
	s_barrier
	s_setprio 0
	s_add_i32 s12, 0, 0x18000
	s_add_i32 s13, 0, 0x1c000
	s_add_u32 s4, s58, 0x4000
	s_addc_u32 s5, s59, 0
	s_mov_b32 m0, s76
	v_lshl_add_u64 v[232:233], s[4:5], 0, v[128:129]
	global_load_lds_dwordx4 v[232:233], off
	v_lshl_add_u64 v[232:233], s[4:5], 0, v[132:133]
	s_mov_b32 m0, s77
	s_nop 0
	global_load_lds_dwordx4 v[232:233], off
	v_add_u32_e32 v170, s12, v177
	v_add_u32_e32 v185, s13, v177
	ds_read_b128 v[158:161], v170
	ds_read_b128 v[162:165], v170 offset:1024
	ds_read_b128 v[166:169], v170 offset:2048
	ds_read_b128 v[170:173], v170 offset:3072
	ds_read_b128 v[180:183], v185
	ds_read_b128 v[186:189], v185 offset:1024
	ds_read_b128 v[190:193], v185 offset:2048
	ds_read_b128 v[194:197], v185 offset:3072
	ds_read_b128 v[198:201], v179 offset:32768
	ds_read_b128 v[202:205], v179 offset:33792
	ds_read_b128 v[206:209], v179 offset:34816
	ds_read_b128 v[210:213], v179 offset:35840
	ds_read_b128 v[214:217], v179 offset:36864
	ds_read_b128 v[218:221], v179 offset:37888
	ds_read_b128 v[222:225], v179 offset:38912
	ds_read_b128 v[226:229], v179 offset:39936
	s_waitcnt vmcnt(8)
	s_waitcnt lgkmcnt(0)
	s_setprio 1
	s_barrier
	v_mfma_f32_16x16x32_bf16 v[124:127], v[158:161], v[198:201], v[124:127]
	v_mfma_f32_16x16x32_bf16 v[120:123], v[166:169], v[198:201], v[120:123]
	v_mfma_f32_16x16x32_bf16 v[116:119], v[158:161], v[206:209], v[116:119]
	v_mfma_f32_16x16x32_bf16 v[112:115], v[166:169], v[206:209], v[112:115]
	v_mfma_f32_16x16x32_bf16 v[108:111], v[158:161], v[214:217], v[108:111]
	v_mfma_f32_16x16x32_bf16 v[104:107], v[166:169], v[214:217], v[104:107]
	v_mfma_f32_16x16x32_bf16 v[100:103], v[158:161], v[222:225], v[100:103]
	v_mfma_f32_16x16x32_bf16 v[96:99], v[166:169], v[222:225], v[96:99]
	v_mfma_f32_16x16x32_bf16 v[124:127], v[162:165], v[202:205], v[124:127]
	v_mfma_f32_16x16x32_bf16 v[120:123], v[170:173], v[202:205], v[120:123]
	v_mfma_f32_16x16x32_bf16 v[116:119], v[162:165], v[210:213], v[116:119]
	v_mfma_f32_16x16x32_bf16 v[112:115], v[170:173], v[210:213], v[112:115]
	v_mfma_f32_16x16x32_bf16 v[108:111], v[162:165], v[218:221], v[108:111]
	v_mfma_f32_16x16x32_bf16 v[104:107], v[170:173], v[218:221], v[104:107]
	v_mfma_f32_16x16x32_bf16 v[100:103], v[162:165], v[226:229], v[100:103]
	v_mfma_f32_16x16x32_bf16 v[96:99], v[170:173], v[226:229], v[96:99]
	s_setprio 0
	s_setprio 1
	v_mfma_f32_16x16x32_bf16 v[92:95], v[180:183], v[198:201], v[92:95]
	v_mfma_f32_16x16x32_bf16 v[88:91], v[190:193], v[198:201], v[88:91]
	v_mfma_f32_16x16x32_bf16 v[84:87], v[180:183], v[206:209], v[84:87]
	v_mfma_f32_16x16x32_bf16 v[80:83], v[190:193], v[206:209], v[80:83]
	v_mfma_f32_16x16x32_bf16 v[76:79], v[180:183], v[214:217], v[76:79]
	v_mfma_f32_16x16x32_bf16 v[72:75], v[190:193], v[214:217], v[72:75]
	v_mfma_f32_16x16x32_bf16 v[68:71], v[180:183], v[222:225], v[68:71]
	v_mfma_f32_16x16x32_bf16 v[64:67], v[190:193], v[222:225], v[64:67]
	v_mfma_f32_16x16x32_bf16 v[92:95], v[186:189], v[202:205], v[92:95]
	v_mfma_f32_16x16x32_bf16 v[88:91], v[194:197], v[202:205], v[88:91]
	v_mfma_f32_16x16x32_bf16 v[84:87], v[186:189], v[210:213], v[84:87]
	v_mfma_f32_16x16x32_bf16 v[80:83], v[194:197], v[210:213], v[80:83]
	v_mfma_f32_16x16x32_bf16 v[76:79], v[186:189], v[218:221], v[76:79]
	v_mfma_f32_16x16x32_bf16 v[72:75], v[194:197], v[218:221], v[72:75]
	v_mfma_f32_16x16x32_bf16 v[68:71], v[186:189], v[226:229], v[68:71]
	v_mfma_f32_16x16x32_bf16 v[64:67], v[194:197], v[226:229], v[64:67]
	s_barrier
; #define PG8_STAGE(bufoff, gbase, voff) do { _Pragma("unroll") for (int _i = 0; _i < 2; ++_i) \
;         __builtin_amdgcn_global_load_lds((const unsigned*)((const char*)(gbase) + (voff)[_i]), (PG8_LAS unsigned*)(lds + (bufoff) + ldsw + _i * 8192), 16, 0, 0); } while (0)
; #define PG8_LDA(dst, b, h) do { _Pragma("unroll") for (int m = 0; m < 4; ++m) _Pragma("unroll") for (int k = 0; k < 2; ++k) dst[m][k] = *(const PG8_LAS bf16x8*)(lds + PG8_SA(b, h) + aoff + m * 2048 + k * 1024); } while (0)
; #define PG8_MMA(ai, bj, At, Bt) do { __builtin_amdgcn_s_setprio(1); _Pragma("unroll") for (int m = 0; m < 4; ++m) _Pragma("unroll") for (int n = 0; n < 2; ++n) _Pragma("unroll") for (int k = 0; k < 2; ++k) \
;         acc[ai][bj][m][n] = __builtin_amdgcn_mfma_f32_16x16x32_bf16(Bt[n][k], At[m][k], acc[ai][bj][m][n], 0, 0, 0); __builtin_amdgcn_s_setprio(0); } while (0)
; #define PG8_WAIT_V(n) asm volatile("s_waitcnt vmcnt(" #n ")" ::: "memory")
; #define PG8_WAIT_L(n) asm volatile("s_waitcnt lgkmcnt(" #n ")" ::: "memory")
; #define PG8_BAR __builtin_amdgcn_s_barrier()
; #define PG8_SCHED __builtin_amdgcn_sched_barrier(0)
; template <class Epi, class Sched, bool ALIGN_EPI = false, bool SP2 = false>
; __device__ __forceinline__ void gemm_phase(PG8_LAS unsigned char* lds, const Gemm g, const Sched& S, const Epi& E) {
;     ...
;             PG8_LDA(At, 1, 1); PG8_STAGE(PG8_SB(1, 0), b3, voffB); PG8_STAGE(PG8_SB(1, 1), b3 + hstepB, voffB); PG8_STAGE(PG8_SA(1, 0), a3, voffA);
;             PG8_WAIT_V(8); PG8_WAIT_L(0); PG8_BAR; PG8_MMA(1, 0, At, B0); PG8_MMA(1, 1, At, B1); PG8_BAR; PG8_SCHED;
	s_setprio 0
	s_add_i32 s4, s12, s9
	v_lshl_add_u64 v[174:175], v[174:175], 0, s[54:55]
	s_mov_b32 m0, s4
	s_nop 0
	global_load_lds_dwordx4 v[174:175], off
	s_add_i32 m0, s4, 0x2000
	s_add_u32 s4, s52, 0x160080
	v_lshl_add_u64 v[174:175], v[230:231], 0, s[54:55]
	s_addc_u32 s5, s53, 0
	s_add_i32 s12, s13, s9
	global_load_lds_dwordx4 v[174:175], off
	v_lshl_add_u64 v[174:175], s[4:5], 0, v[130:131]
	s_mov_b32 m0, s12
	s_nop 0
	global_load_lds_dwordx4 v[174:175], off
	v_lshl_add_u64 v[174:175], s[4:5], 0, v[134:135]
	s_add_i32 m0, s12, 0x2000
	s_nop 0
	global_load_lds_dwordx4 v[174:175], off
	v_lshl_add_u64 v[174:175], s[50:51], 0, v[128:129]
	s_mov_b32 m0, s45
	s_nop 0
	global_load_lds_dwordx4 v[174:175], off
	v_lshl_add_u64 v[174:175], s[50:51], 0, v[132:133]
	s_mov_b32 m0, s56
	s_nop 0
	global_load_lds_dwordx4 v[174:175], off
	ds_read_b128 v[198:201], v179 offset:49152
	ds_read_b128 v[202:205], v179 offset:50176
	ds_read_b128 v[206:209], v179 offset:51200
	ds_read_b128 v[210:213], v179 offset:52224
	ds_read_b128 v[214:217], v179 offset:53248
	ds_read_b128 v[218:221], v179 offset:54272
	ds_read_b128 v[222:225], v179 offset:55296
	ds_read_b128 v[226:229], v179 offset:56320
	s_waitcnt vmcnt(8)
	s_waitcnt lgkmcnt(0)
	s_setprio 1
	s_barrier
	v_mfma_f32_16x16x32_bf16 v[60:63], v[158:161], v[198:201], v[60:63]
	v_mfma_f32_16x16x32_bf16 v[56:59], v[166:169], v[198:201], v[56:59]
	v_mfma_f32_16x16x32_bf16 v[52:55], v[158:161], v[206:209], v[52:55]
	v_mfma_f32_16x16x32_bf16 v[48:51], v[166:169], v[206:209], v[48:51]
	v_mfma_f32_16x16x32_bf16 v[44:47], v[158:161], v[214:217], v[44:47]
	v_mfma_f32_16x16x32_bf16 v[40:43], v[166:169], v[214:217], v[40:43]
	v_mfma_f32_16x16x32_bf16 v[36:39], v[158:161], v[222:225], v[36:39]
	v_mfma_f32_16x16x32_bf16 v[32:35], v[166:169], v[222:225], v[32:35]
	v_mfma_f32_16x16x32_bf16 v[60:63], v[162:165], v[202:205], v[60:63]
	v_mfma_f32_16x16x32_bf16 v[56:59], v[170:173], v[202:205], v[56:59]
	v_mfma_f32_16x16x32_bf16 v[52:55], v[162:165], v[210:213], v[52:55]
	v_mfma_f32_16x16x32_bf16 v[48:51], v[170:173], v[210:213], v[48:51]
	v_mfma_f32_16x16x32_bf16 v[44:47], v[162:165], v[218:221], v[44:47]
	v_mfma_f32_16x16x32_bf16 v[40:43], v[170:173], v[218:221], v[40:43]
	v_mfma_f32_16x16x32_bf16 v[36:39], v[162:165], v[226:229], v[36:39]
	v_mfma_f32_16x16x32_bf16 v[32:35], v[170:173], v[226:229], v[32:35]
	s_setprio 0
	s_setprio 1
	v_mfma_f32_16x16x32_bf16 v[28:31], v[180:183], v[198:201], v[28:31]
	v_mfma_f32_16x16x32_bf16 v[24:27], v[190:193], v[198:201], v[24:27]
	v_mfma_f32_16x16x32_bf16 v[20:23], v[180:183], v[206:209], v[20:23]
	v_mfma_f32_16x16x32_bf16 v[16:19], v[190:193], v[206:209], v[16:19]
	v_mfma_f32_16x16x32_bf16 v[12:15], v[180:183], v[214:217], v[12:15]
	v_mfma_f32_16x16x32_bf16 v[8:11], v[190:193], v[214:217], v[8:11]
	v_mfma_f32_16x16x32_bf16 v[4:7], v[180:183], v[222:225], v[4:7]
	v_mfma_f32_16x16x32_bf16 v[0:3], v[190:193], v[222:225], v[0:3]
	v_mfma_f32_16x16x32_bf16 v[28:31], v[186:189], v[202:205], v[28:31]
	v_mfma_f32_16x16x32_bf16 v[24:27], v[194:197], v[202:205], v[24:27]
	v_mfma_f32_16x16x32_bf16 v[20:23], v[186:189], v[210:213], v[20:23]
	v_mfma_f32_16x16x32_bf16 v[16:19], v[194:197], v[210:213], v[16:19]
	v_mfma_f32_16x16x32_bf16 v[12:15], v[186:189], v[218:221], v[12:15]
	v_mfma_f32_16x16x32_bf16 v[8:11], v[194:197], v[218:221], v[8:11]
	v_mfma_f32_16x16x32_bf16 v[4:7], v[186:189], v[226:229], v[4:7]
	v_mfma_f32_16x16x32_bf16 v[0:3], v[194:197], v[226:229], v[0:3]
	s_barrier
	s_setprio 0
	s_cmp_ge_i32 s74, s57
	s_cbranch_scc1 .LBB0_409

; #define PG8_STAGE(bufoff, gbase, voff) do { _Pragma("unroll") for (int _i = 0; _i < 2; ++_i) \
;         __builtin_amdgcn_global_load_lds((const unsigned*)((const char*)(gbase) + (voff)[_i]), (PG8_LAS unsigned*)(lds + (bufoff) + ldsw + _i * 8192), 16, 0, 0); } while (0)
; #define PG8_LDA(dst, b, h) do { _Pragma("unroll") for (int m = 0; m < 4; ++m) _Pragma("unroll") for (int k = 0; k < 2; ++k) dst[m][k] = *(const PG8_LAS bf16x8*)(lds + PG8_SA(b, h) + aoff + m * 2048 + k * 1024); } while (0)
; #define PG8_LDB(dst, b, h) do { _Pragma("unroll") for (int n = 0; n < 2; ++n) _Pragma("unroll") for (int k = 0; k < 2; ++k) dst[n][k] = *(const PG8_LAS bf16x8*)(lds + PG8_SB(b, h) + boff + n * 2048 + k * 1024); } while (0)
; #define PG8_MMA(ai, bj, At, Bt) do { __builtin_amdgcn_s_setprio(1); _Pragma("unroll") for (int m = 0; m < 4; ++m) _Pragma("unroll") for (int n = 0; n < 2; ++n) _Pragma("unroll") for (int k = 0; k < 2; ++k) \
;         acc[ai][bj][m][n] = __builtin_amdgcn_mfma_f32_16x16x32_bf16(Bt[n][k], At[m][k], acc[ai][bj][m][n], 0, 0, 0); __builtin_amdgcn_s_setprio(0); } while (0)
; #define PG8_WAIT_V(n) asm volatile("s_waitcnt vmcnt(" #n ")" ::: "memory")
; #define PG8_WAIT_L(n) asm volatile("s_waitcnt lgkmcnt(" #n ")" ::: "memory")
; #define PG8_BAR __builtin_amdgcn_s_barrier()
; #define PG8_SCHED __builtin_amdgcn_sched_barrier(0)
; template <class Epi, class Sched, bool ALIGN_EPI = false, bool SP2 = false>
; __device__ __forceinline__ void gemm_phase(PG8_LAS unsigned char* lds, const Gemm g, const Sched& S, const Epi& E) {
;     ...
;             const char* a1 = cA + (size_t)(t + 1) * kstA;
;             const char* a2 = last ? nA : cA + (size_t)(t + 2) * kstA; const char* b2 = last ? nB : cB + (size_t)(t + 2) * kstep;
;             const char* a3 = a2 + kstA; const char* b3 = b2 + kstep;
;             if (last && has_next) S.a_ready(nxt);
;             if constexpr (SP2) {
;             PG8_LDB(B0, 0, 0); PG8_LDB(B1, 0, 1); PG8_SCHED; PG8_LDA(At, 0, 0); PG8_STAGE(PG8_SA(1, 1), a1 + hstepA, voffA);
;             PG8_WAIT_V(8); PG8_WAIT_L(0); PG8_BAR; PG8_MMA(0, 0, At, B0); PG8_MMA(0, 1, At, B1); PG8_BAR; PG8_SCHED;
;             PG8_LDA(At, 0, 1); PG8_STAGE(PG8_SB(0, 0), b2, voffB); PG8_STAGE(PG8_SB(0, 1), b2 + hstepB, voffB); PG8_STAGE(PG8_SA(0, 0), a2, voffA);
.LBB0_656:
	s_add_u32 s47, s50, 0xfff80080
	s_addc_u32 s52, s51, -1
	s_cmp_eq_u32 s46, 28
	s_cselect_b32 s59, s63, s52
	s_cselect_b32 s58, s62, s47
	s_cselect_b32 s53, s65, s5
	s_cselect_b32 s52, s64, s4
	v_lshl_add_u64 v[158:159], s[50:51], 0, v[152:153]
	s_add_i32 m0, s9, 0xc000
	s_nop 0
	global_load_lds_dwordx4 v[158:159], off
	v_lshl_add_u64 v[158:159], s[50:51], 0, v[154:155]
	s_add_i32 m0, s9, 0xe000
	s_nop 0
	global_load_lds_dwordx4 v[158:159], off
	ds_read_b128 v[166:169], v163
	ds_read_b128 v[170:173], v163 offset:1024
	ds_read_b128 v[174:177], v163 offset:2048
	ds_read_b128 v[178:181], v163 offset:3072
	ds_read_b128 v[186:189], v164
	ds_read_b128 v[190:193], v164 offset:1024
	ds_read_b128 v[194:197], v164 offset:2048
	ds_read_b128 v[198:201], v164 offset:3072
	ds_read_b128 v[202:205], v165
	ds_read_b128 v[206:209], v165 offset:1024
	ds_read_b128 v[210:213], v165 offset:2048
	ds_read_b128 v[214:217], v165 offset:3072
	ds_read_b128 v[218:221], v165 offset:4096
	ds_read_b128 v[222:225], v165 offset:5120
	ds_read_b128 v[226:229], v165 offset:6144
	ds_read_b128 v[230:233], v165 offset:7168
	s_waitcnt vmcnt(8)
	s_waitcnt lgkmcnt(0)
	s_setprio 1
	s_barrier
	v_mfma_f32_16x16x32_bf16 v[124:127], v[166:169], v[202:205], v[124:127]
	v_mfma_f32_16x16x32_bf16 v[120:123], v[174:177], v[202:205], v[120:123]
	v_mfma_f32_16x16x32_bf16 v[112:115], v[166:169], v[210:213], v[112:115]
	v_mfma_f32_16x16x32_bf16 v[104:107], v[174:177], v[210:213], v[104:107]
	v_mfma_f32_16x16x32_bf16 v[96:99], v[166:169], v[218:221], v[96:99]
	v_mfma_f32_16x16x32_bf16 v[88:91], v[174:177], v[218:221], v[88:91]
	v_mfma_f32_16x16x32_bf16 v[80:83], v[166:169], v[226:229], v[80:83]
	v_mfma_f32_16x16x32_bf16 v[72:75], v[174:177], v[226:229], v[72:75]
	v_mfma_f32_16x16x32_bf16 v[124:127], v[170:173], v[206:209], v[124:127]
	v_mfma_f32_16x16x32_bf16 v[120:123], v[178:181], v[206:209], v[120:123]
	v_mfma_f32_16x16x32_bf16 v[112:115], v[170:173], v[214:217], v[112:115]
	v_mfma_f32_16x16x32_bf16 v[104:107], v[178:181], v[214:217], v[104:107]
	v_mfma_f32_16x16x32_bf16 v[96:99], v[170:173], v[222:225], v[96:99]
	v_mfma_f32_16x16x32_bf16 v[88:91], v[178:181], v[222:225], v[88:91]
	v_mfma_f32_16x16x32_bf16 v[80:83], v[170:173], v[230:233], v[80:83]
	v_mfma_f32_16x16x32_bf16 v[72:75], v[178:181], v[230:233], v[72:75]
	s_setprio 0
	s_setprio 1
	v_mfma_f32_16x16x32_bf16 v[116:119], v[186:189], v[202:205], v[116:119]
	v_mfma_f32_16x16x32_bf16 v[108:111], v[194:197], v[202:205], v[108:111]
	v_mfma_f32_16x16x32_bf16 v[100:103], v[186:189], v[210:213], v[100:103]
	v_mfma_f32_16x16x32_bf16 v[92:95], v[194:197], v[210:213], v[92:95]
	v_mfma_f32_16x16x32_bf16 v[84:87], v[186:189], v[218:221], v[84:87]
	v_mfma_f32_16x16x32_bf16 v[76:79], v[194:197], v[218:221], v[76:79]
	v_mfma_f32_16x16x32_bf16 v[68:71], v[186:189], v[226:229], v[68:71]
	v_mfma_f32_16x16x32_bf16 v[64:67], v[194:197], v[226:229], v[64:67]
	v_mfma_f32_16x16x32_bf16 v[116:119], v[190:193], v[206:209], v[116:119]
	v_mfma_f32_16x16x32_bf16 v[108:111], v[198:201], v[206:209], v[108:111]
	v_mfma_f32_16x16x32_bf16 v[100:103], v[190:193], v[214:217], v[100:103]
	v_mfma_f32_16x16x32_bf16 v[92:95], v[198:201], v[214:217], v[92:95]
	v_mfma_f32_16x16x32_bf16 v[84:87], v[190:193], v[222:225], v[84:87]
	v_mfma_f32_16x16x32_bf16 v[76:79], v[198:201], v[222:225], v[76:79]
	v_mfma_f32_16x16x32_bf16 v[68:71], v[190:193], v[230:233], v[68:71]
	v_mfma_f32_16x16x32_bf16 v[64:67], v[198:201], v[230:233], v[64:67]
	s_barrier
	s_setprio 0
	s_add_i32 s47, s44, s8
	v_lshl_add_u64 v[158:159], s[52:53], 0, v[130:131]
	s_mov_b32 m0, s47
	s_nop 0
	global_load_lds_dwordx4 v[158:159], off
	s_add_i32 m0, s47, 0x2000
	s_add_u32 s66, s52, 0x80000
	v_lshl_add_u64 v[182:183], s[52:53], 0, v[134:135]
	s_addc_u32 s67, s53, 0
	s_add_i32 s47, s45, s8
	global_load_lds_dwordx4 v[182:183], off
	v_lshl_add_u64 v[234:235], s[66:67], 0, v[130:131]
	s_mov_b32 m0, s47
	v_lshl_add_u64 v[236:237], s[58:59], 0, v[132:133]
	global_load_lds_dwordx4 v[234:235], off
	v_lshl_add_u64 v[234:235], s[66:67], 0, v[134:135]
	s_add_i32 m0, s47, 0x2000
	s_nop 0
	global_load_lds_dwordx4 v[234:235], off
	v_lshl_add_u64 v[234:235], s[58:59], 0, v[128:129]
	s_mov_b32 m0, s9
	s_nop 0
	global_load_lds_dwordx4 v[234:235], off
	s_mov_b32 m0, s10
	s_nop 0
	global_load_lds_dwordx4 v[236:237], off
	ds_read_b128 v[202:205], v165 offset:16384
	ds_read_b128 v[206:209], v165 offset:17408
	ds_read_b128 v[210:213], v165 offset:18432
	ds_read_b128 v[214:217], v165 offset:19456
	ds_read_b128 v[218:221], v165 offset:20480
	ds_read_b128 v[222:225], v165 offset:21504
	ds_read_b128 v[226:229], v165 offset:22528
	ds_read_b128 v[230:233], v165 offset:23552
	s_waitcnt vmcnt(8)
	s_waitcnt lgkmcnt(0)
	s_setprio 1
	s_barrier
; #define PG8_STAGE(bufoff, gbase, voff) do { _Pragma("unroll") for (int _i = 0; _i < 2; ++_i) \
;         __builtin_amdgcn_global_load_lds((const unsigned*)((const char*)(gbase) + (voff)[_i]), (PG8_LAS unsigned*)(lds + (bufoff) + ldsw + _i * 8192), 16, 0, 0); } while (0)
; #define PG8_LDA(dst, b, h) do { _Pragma("unroll") for (int m = 0; m < 4; ++m) _Pragma("unroll") for (int k = 0; k < 2; ++k) dst[m][k] = *(const PG8_LAS bf16x8*)(lds + PG8_SA(b, h) + aoff + m * 2048 + k * 1024); } while (0)
; #define PG8_LDB(dst, b, h) do { _Pragma("unroll") for (int n = 0; n < 2; ++n) _Pragma("unroll") for (int k = 0; k < 2; ++k) dst[n][k] = *(const PG8_LAS bf16x8*)(lds + PG8_SB(b, h) + boff + n * 2048 + k * 1024); } while (0)
; #define PG8_MMA(ai, bj, At, Bt) do { __builtin_amdgcn_s_setprio(1); _Pragma("unroll") for (int m = 0; m < 4; ++m) _Pragma("unroll") for (int n = 0; n < 2; ++n) _Pragma("unroll") for (int k = 0; k < 2; ++k) \
;         acc[ai][bj][m][n] = __builtin_amdgcn_mfma_f32_16x16x32_bf16(Bt[n][k], At[m][k], acc[ai][bj][m][n], 0, 0, 0); __builtin_amdgcn_s_setprio(0); } while (0)
; #define PG8_WAIT_V(n) asm volatile("s_waitcnt vmcnt(" #n ")" ::: "memory")
; #define PG8_WAIT_L(n) asm volatile("s_waitcnt lgkmcnt(" #n ")" ::: "memory")
; #define PG8_BAR __builtin_amdgcn_s_barrier()
; #define PG8_SCHED __builtin_amdgcn_sched_barrier(0)
; template <class Epi, class Sched, bool ALIGN_EPI = false, bool SP2 = false>
; __device__ __forceinline__ void gemm_phase(PG8_LAS unsigned char* lds, const Gemm g, const Sched& S, const Epi& E) {
;     ...
;             PG8_WAIT_V(8); PG8_WAIT_L(0); PG8_BAR; PG8_MMA(1, 0, At, B0); PG8_MMA(1, 1, At, B1); PG8_BAR; PG8_SCHED;
;             PG8_LDB(B0, 1, 0); PG8_LDB(B1, 1, 1); PG8_SCHED; PG8_LDA(At, 1, 0); PG8_STAGE(PG8_SA(0, 1), a2 + hstepA, voffA);
;             PG8_WAIT_V(8); PG8_WAIT_L(0); PG8_BAR; PG8_MMA(0, 0, At, B0); PG8_MMA(0, 1, At, B1); PG8_BAR; PG8_SCHED;
	v_mfma_f32_16x16x32_bf16 v[60:63], v[166:169], v[202:205], v[60:63]
	v_mfma_f32_16x16x32_bf16 v[56:59], v[174:177], v[202:205], v[56:59]
	v_mfma_f32_16x16x32_bf16 v[48:51], v[166:169], v[210:213], v[48:51]
	v_mfma_f32_16x16x32_bf16 v[40:43], v[174:177], v[210:213], v[40:43]
	v_mfma_f32_16x16x32_bf16 v[32:35], v[166:169], v[218:221], v[32:35]
	v_mfma_f32_16x16x32_bf16 v[24:27], v[174:177], v[218:221], v[24:27]
	v_mfma_f32_16x16x32_bf16 v[16:19], v[166:169], v[226:229], v[16:19]
	v_mfma_f32_16x16x32_bf16 v[8:11], v[174:177], v[226:229], v[8:11]
	v_mfma_f32_16x16x32_bf16 v[60:63], v[170:173], v[206:209], v[60:63]
	v_mfma_f32_16x16x32_bf16 v[56:59], v[178:181], v[206:209], v[56:59]
	v_mfma_f32_16x16x32_bf16 v[48:51], v[170:173], v[214:217], v[48:51]
	v_mfma_f32_16x16x32_bf16 v[40:43], v[178:181], v[214:217], v[40:43]
	v_mfma_f32_16x16x32_bf16 v[32:35], v[170:173], v[222:225], v[32:35]
	v_mfma_f32_16x16x32_bf16 v[24:27], v[178:181], v[222:225], v[24:27]
	v_mfma_f32_16x16x32_bf16 v[16:19], v[170:173], v[230:233], v[16:19]
	v_mfma_f32_16x16x32_bf16 v[8:11], v[178:181], v[230:233], v[8:11]
	s_setprio 0
	s_setprio 1
	v_mfma_f32_16x16x32_bf16 v[52:55], v[186:189], v[202:205], v[52:55]
	v_mfma_f32_16x16x32_bf16 v[44:47], v[194:197], v[202:205], v[44:47]
	v_mfma_f32_16x16x32_bf16 v[36:39], v[186:189], v[210:213], v[36:39]
	v_mfma_f32_16x16x32_bf16 v[28:31], v[194:197], v[210:213], v[28:31]
	v_mfma_f32_16x16x32_bf16 v[20:23], v[186:189], v[218:221], v[20:23]
	v_mfma_f32_16x16x32_bf16 v[12:15], v[194:197], v[218:221], v[12:15]
	v_mfma_f32_16x16x32_bf16 v[4:7], v[186:189], v[226:229], v[4:7]
	v_mfma_f32_16x16x32_bf16 v[0:3], v[194:197], v[226:229], v[0:3]
	v_mfma_f32_16x16x32_bf16 v[52:55], v[190:193], v[206:209], v[52:55]
	v_mfma_f32_16x16x32_bf16 v[44:47], v[198:201], v[206:209], v[44:47]
	v_mfma_f32_16x16x32_bf16 v[36:39], v[190:193], v[214:217], v[36:39]
	v_mfma_f32_16x16x32_bf16 v[28:31], v[198:201], v[214:217], v[28:31]
	v_mfma_f32_16x16x32_bf16 v[20:23], v[190:193], v[222:225], v[20:23]
	v_mfma_f32_16x16x32_bf16 v[12:15], v[198:201], v[222:225], v[12:15]
	v_mfma_f32_16x16x32_bf16 v[4:7], v[190:193], v[230:233], v[4:7]
	v_mfma_f32_16x16x32_bf16 v[0:3], v[198:201], v[230:233], v[0:3]
	s_barrier
	s_setprio 0
	s_add_i32 s47, 0, 0x18000
	s_add_i32 s55, 0, 0x1c000
	s_add_u32 s58, s58, 0x80000
	s_addc_u32 s59, s59, 0
	s_mov_b32 m0, s11
	v_lshl_add_u64 v[238:239], s[58:59], 0, v[128:129]
	global_load_lds_dwordx4 v[238:239], off
	v_lshl_add_u64 v[238:239], s[58:59], 0, v[132:133]
	s_mov_b32 m0, s12
	s_nop 0
	global_load_lds_dwordx4 v[238:239], off
	v_add_u32_e32 v178, s47, v160
	v_add_u32_e32 v185, s55, v160
	ds_read_b128 v[166:169], v178
	ds_read_b128 v[170:173], v178 offset:1024
	ds_read_b128 v[174:177], v178 offset:2048
	ds_read_b128 v[178:181], v178 offset:3072
	ds_read_b128 v[186:189], v185
	ds_read_b128 v[190:193], v185 offset:1024
	ds_read_b128 v[194:197], v185 offset:2048
	ds_read_b128 v[198:201], v185 offset:3072
	ds_read_b128 v[202:205], v165 offset:32768
	ds_read_b128 v[206:209], v165 offset:33792
	ds_read_b128 v[210:213], v165 offset:34816
	ds_read_b128 v[214:217], v165 offset:35840
	ds_read_b128 v[218:221], v165 offset:36864
	ds_read_b128 v[222:225], v165 offset:37888
	ds_read_b128 v[226:229], v165 offset:38912
	ds_read_b128 v[230:233], v165 offset:39936
	s_waitcnt vmcnt(8)
	s_waitcnt lgkmcnt(0)
	s_setprio 1
	s_barrier
	v_mfma_f32_16x16x32_bf16 v[124:127], v[166:169], v[202:205], v[124:127]
	v_mfma_f32_16x16x32_bf16 v[120:123], v[174:177], v[202:205], v[120:123]
	v_mfma_f32_16x16x32_bf16 v[112:115], v[166:169], v[210:213], v[112:115]
	v_mfma_f32_16x16x32_bf16 v[104:107], v[174:177], v[210:213], v[104:107]
	v_mfma_f32_16x16x32_bf16 v[96:99], v[166:169], v[218:221], v[96:99]
	v_mfma_f32_16x16x32_bf16 v[88:91], v[174:177], v[218:221], v[88:91]
	v_mfma_f32_16x16x32_bf16 v[80:83], v[166:169], v[226:229], v[80:83]
	v_mfma_f32_16x16x32_bf16 v[72:75], v[174:177], v[226:229], v[72:75]
	v_mfma_f32_16x16x32_bf16 v[124:127], v[170:173], v[206:209], v[124:127]
	v_mfma_f32_16x16x32_bf16 v[120:123], v[178:181], v[206:209], v[120:123]
	v_mfma_f32_16x16x32_bf16 v[112:115], v[170:173], v[214:217], v[112:115]
	v_mfma_f32_16x16x32_bf16 v[104:107], v[178:181], v[214:217], v[104:107]
	v_mfma_f32_16x16x32_bf16 v[96:99], v[170:173], v[222:225], v[96:99]
	v_mfma_f32_16x16x32_bf16 v[88:91], v[178:181], v[222:225], v[88:91]
	v_mfma_f32_16x16x32_bf16 v[80:83], v[170:173], v[230:233], v[80:83]
	v_mfma_f32_16x16x32_bf16 v[72:75], v[178:181], v[230:233], v[72:75]
	s_setprio 0
	s_setprio 1
	v_mfma_f32_16x16x32_bf16 v[116:119], v[186:189], v[202:205], v[116:119]
	v_mfma_f32_16x16x32_bf16 v[108:111], v[194:197], v[202:205], v[108:111]
	v_mfma_f32_16x16x32_bf16 v[100:103], v[186:189], v[210:213], v[100:103]
	v_mfma_f32_16x16x32_bf16 v[92:95], v[194:197], v[210:213], v[92:95]
	v_mfma_f32_16x16x32_bf16 v[84:87], v[186:189], v[218:221], v[84:87]
	v_mfma_f32_16x16x32_bf16 v[76:79], v[194:197], v[218:221], v[76:79]
	v_mfma_f32_16x16x32_bf16 v[68:71], v[186:189], v[226:229], v[68:71]
	v_mfma_f32_16x16x32_bf16 v[64:67], v[194:197], v[226:229], v[64:67]
	v_mfma_f32_16x16x32_bf16 v[116:119], v[190:193], v[206:209], v[116:119]
	v_mfma_f32_16x16x32_bf16 v[108:111], v[198:201], v[206:209], v[108:111]
	v_mfma_f32_16x16x32_bf16 v[100:103], v[190:193], v[214:217], v[100:103]
	v_mfma_f32_16x16x32_bf16 v[92:95], v[198:201], v[214:217], v[92:95]
	v_mfma_f32_16x16x32_bf16 v[84:87], v[190:193], v[222:225], v[84:87]
	v_mfma_f32_16x16x32_bf16 v[76:79], v[198:201], v[222:225], v[76:79]
	v_mfma_f32_16x16x32_bf16 v[68:71], v[190:193], v[230:233], v[68:71]
	v_mfma_f32_16x16x32_bf16 v[64:67], v[198:201], v[230:233], v[64:67]
	s_barrier
; #define PG8_STAGE(bufoff, gbase, voff) do { _Pragma("unroll") for (int _i = 0; _i < 2; ++_i) \
;         __builtin_amdgcn_global_load_lds((const unsigned*)((const char*)(gbase) + (voff)[_i]), (PG8_LAS unsigned*)(lds + (bufoff) + ldsw + _i * 8192), 16, 0, 0); } while (0)
; #define PG8_LDA(dst, b, h) do { _Pragma("unroll") for (int m = 0; m < 4; ++m) _Pragma("unroll") for (int k = 0; k < 2; ++k) dst[m][k] = *(const PG8_LAS bf16x8*)(lds + PG8_SA(b, h) + aoff + m * 2048 + k * 1024); } while (0)
; #define PG8_MMA(ai, bj, At, Bt) do { __builtin_amdgcn_s_setprio(1); _Pragma("unroll") for (int m = 0; m < 4; ++m) _Pragma("unroll") for (int n = 0; n < 2; ++n) _Pragma("unroll") for (int k = 0; k < 2; ++k) \
;         acc[ai][bj][m][n] = __builtin_amdgcn_mfma_f32_16x16x32_bf16(Bt[n][k], At[m][k], acc[ai][bj][m][n], 0, 0, 0); __builtin_amdgcn_s_setprio(0); } while (0)
; #define PG8_WAIT_V(n) asm volatile("s_waitcnt vmcnt(" #n ")" ::: "memory")
; #define PG8_WAIT_L(n) asm volatile("s_waitcnt lgkmcnt(" #n ")" ::: "memory")
; #define PG8_BAR __builtin_amdgcn_s_barrier()
; #define PG8_SCHED __builtin_amdgcn_sched_barrier(0)
; template <class Epi, class Sched, bool ALIGN_EPI = false, bool SP2 = false>
; __device__ __forceinline__ void gemm_phase(PG8_LAS unsigned char* lds, const Gemm g, const Sched& S, const Epi& E) {
;     ...
;             PG8_LDA(At, 1, 1); PG8_STAGE(PG8_SB(1, 0), b3, voffB); PG8_STAGE(PG8_SB(1, 1), b3 + hstepB, voffB); PG8_STAGE(PG8_SA(1, 0), a3, voffA);
;             PG8_WAIT_V(8); PG8_WAIT_L(0); PG8_BAR; PG8_MMA(1, 0, At, B0); PG8_MMA(1, 1, At, B1); PG8_BAR; PG8_SCHED;
	s_setprio 0
	s_add_i32 s47, s47, s8
	v_lshl_add_u64 v[158:159], v[158:159], 0, s[38:39]
	s_mov_b32 m0, s47
	s_nop 0
	global_load_lds_dwordx4 v[158:159], off
	s_add_i32 m0, s47, 0x2000
	s_add_u32 s52, s52, 0x80080
	v_lshl_add_u64 v[158:159], v[182:183], 0, s[38:39]
	s_addc_u32 s53, s53, 0
	s_add_i32 s47, s55, s8
	global_load_lds_dwordx4 v[158:159], off
	v_lshl_add_u64 v[158:159], s[52:53], 0, v[130:131]
	s_mov_b32 m0, s47
	s_nop 0
	global_load_lds_dwordx4 v[158:159], off
	v_lshl_add_u64 v[158:159], s[52:53], 0, v[134:135]
	s_add_i32 m0, s47, 0x2000
	s_nop 0
	global_load_lds_dwordx4 v[158:159], off
	v_lshl_add_u64 v[158:159], v[234:235], 0, s[38:39]
	s_mov_b32 m0, s13
	s_nop 0
	global_load_lds_dwordx4 v[158:159], off
	v_lshl_add_u64 v[158:159], v[236:237], 0, s[38:39]
	s_mov_b32 m0, s33
	s_nop 0
	global_load_lds_dwordx4 v[158:159], off
	ds_read_b128 v[202:205], v165 offset:49152
	ds_read_b128 v[206:209], v165 offset:50176
	ds_read_b128 v[210:213], v165 offset:51200
	ds_read_b128 v[214:217], v165 offset:52224
	ds_read_b128 v[218:221], v165 offset:53248
	ds_read_b128 v[222:225], v165 offset:54272
	ds_read_b128 v[226:229], v165 offset:55296
	ds_read_b128 v[230:233], v165 offset:56320
	s_waitcnt vmcnt(8)
	s_waitcnt lgkmcnt(0)
	s_setprio 1
	s_barrier
	v_mfma_f32_16x16x32_bf16 v[60:63], v[166:169], v[202:205], v[60:63]
	v_mfma_f32_16x16x32_bf16 v[56:59], v[174:177], v[202:205], v[56:59]
	v_mfma_f32_16x16x32_bf16 v[48:51], v[166:169], v[210:213], v[48:51]
	v_mfma_f32_16x16x32_bf16 v[40:43], v[174:177], v[210:213], v[40:43]
	v_mfma_f32_16x16x32_bf16 v[32:35], v[166:169], v[218:221], v[32:35]
	v_mfma_f32_16x16x32_bf16 v[24:27], v[174:177], v[218:221], v[24:27]
	v_mfma_f32_16x16x32_bf16 v[16:19], v[166:169], v[226:229], v[16:19]
	v_mfma_f32_16x16x32_bf16 v[8:11], v[174:177], v[226:229], v[8:11]
	v_mfma_f32_16x16x32_bf16 v[60:63], v[170:173], v[206:209], v[60:63]
	v_mfma_f32_16x16x32_bf16 v[56:59], v[178:181], v[206:209], v[56:59]
	v_mfma_f32_16x16x32_bf16 v[48:51], v[170:173], v[214:217], v[48:51]
	v_mfma_f32_16x16x32_bf16 v[40:43], v[178:181], v[214:217], v[40:43]
	v_mfma_f32_16x16x32_bf16 v[32:35], v[170:173], v[222:225], v[32:35]
	v_mfma_f32_16x16x32_bf16 v[24:27], v[178:181], v[222:225], v[24:27]
	v_mfma_f32_16x16x32_bf16 v[16:19], v[170:173], v[230:233], v[16:19]
	v_mfma_f32_16x16x32_bf16 v[8:11], v[178:181], v[230:233], v[8:11]
	s_setprio 0
	s_setprio 1
	v_mfma_f32_16x16x32_bf16 v[52:55], v[186:189], v[202:205], v[52:55]
	v_mfma_f32_16x16x32_bf16 v[44:47], v[194:197], v[202:205], v[44:47]
	v_mfma_f32_16x16x32_bf16 v[36:39], v[186:189], v[210:213], v[36:39]
	v_mfma_f32_16x16x32_bf16 v[28:31], v[194:197], v[210:213], v[28:31]
	v_mfma_f32_16x16x32_bf16 v[20:23], v[186:189], v[218:221], v[20:23]
	v_mfma_f32_16x16x32_bf16 v[12:15], v[194:197], v[218:221], v[12:15]
	v_mfma_f32_16x16x32_bf16 v[4:7], v[186:189], v[226:229], v[4:7]
	v_mfma_f32_16x16x32_bf16 v[0:3], v[194:197], v[226:229], v[0:3]
	v_mfma_f32_16x16x32_bf16 v[52:55], v[190:193], v[206:209], v[52:55]
	v_mfma_f32_16x16x32_bf16 v[44:47], v[198:201], v[206:209], v[44:47]
	v_mfma_f32_16x16x32_bf16 v[36:39], v[190:193], v[214:217], v[36:39]
	v_mfma_f32_16x16x32_bf16 v[28:31], v[198:201], v[214:217], v[28:31]
	v_mfma_f32_16x16x32_bf16 v[20:23], v[190:193], v[222:225], v[20:23]
	v_mfma_f32_16x16x32_bf16 v[12:15], v[198:201], v[222:225], v[12:15]
	v_mfma_f32_16x16x32_bf16 v[4:7], v[190:193], v[230:233], v[4:7]
	v_mfma_f32_16x16x32_bf16 v[0:3], v[198:201], v[230:233], v[0:3]
	s_barrier
	s_setprio 0
	s_add_i32 s46, s46, 2
	s_add_u32 s50, s50, 0x100
	s_addc_u32 s51, s51, 0
	s_add_u32 s4, s4, 0x100
	s_addc_u32 s5, s5, 0
	s_cmp_gt_u32 s46, 29
	s_cbranch_scc0 .LBB0_656
	s_and_b64 vcc, exec, s[40:41]
	s_cbranch_vccz .LBB0_659
	s_barrier

; #define PG8_STAGE(bufoff, gbase, voff) do { _Pragma("unroll") for (int _i = 0; _i < 2; ++_i) \
;         __builtin_amdgcn_global_load_lds((const unsigned*)((const char*)(gbase) + (voff)[_i]), (PG8_LAS unsigned*)(lds + (bufoff) + ldsw + _i * 8192), 16, 0, 0); } while (0)
; #define PG8_LDA(dst, b, h) do { _Pragma("unroll") for (int m = 0; m < 4; ++m) _Pragma("unroll") for (int k = 0; k < 2; ++k) dst[m][k] = *(const PG8_LAS bf16x8*)(lds + PG8_SA(b, h) + aoff + m * 2048 + k * 1024); } while (0)
; #define PG8_LDB(dst, b, h) do { _Pragma("unroll") for (int n = 0; n < 2; ++n) _Pragma("unroll") for (int k = 0; k < 2; ++k) dst[n][k] = *(const PG8_LAS bf16x8*)(lds + PG8_SB(b, h) + boff + n * 2048 + k * 1024); } while (0)
; #define PG8_MMA(ai, bj, At, Bt) do { __builtin_amdgcn_s_setprio(1); _Pragma("unroll") for (int m = 0; m < 4; ++m) _Pragma("unroll") for (int n = 0; n < 2; ++n) _Pragma("unroll") for (int k = 0; k < 2; ++k) \
;         acc[ai][bj][m][n] = __builtin_amdgcn_mfma_f32_16x16x32_bf16(Bt[n][k], At[m][k], acc[ai][bj][m][n], 0, 0, 0); __builtin_amdgcn_s_setprio(0); } while (0)
; #define PG8_WAIT_V(n) asm volatile("s_waitcnt vmcnt(" #n ")" ::: "memory")
; #define PG8_WAIT_L(n) asm volatile("s_waitcnt lgkmcnt(" #n ")" ::: "memory")
; #define PG8_BAR __builtin_amdgcn_s_barrier()
; #define PG8_SCHED __builtin_amdgcn_sched_barrier(0)
; template <class Epi, class Sched, bool ALIGN_EPI = false, bool SP2 = false>
; __device__ __forceinline__ void gemm_phase(PG8_LAS unsigned char* lds, const Gemm g, const Sched& S, const Epi& E) {
;     ...
;         for (int t = 0; t < nt; t += 2) {
;             const bool last = (t == nt - 2);
;             const char* a1 = cA + (size_t)(t + 1) * kstA;
;             const char* a2 = last ? nA : cA + (size_t)(t + 2) * kstA; const char* b2 = last ? nB : cB + (size_t)(t + 2) * kstep;
;             const char* a3 = a2 + kstA; const char* b3 = b2 + kstep;
;             if (last && has_next) S.a_ready(nxt);
;             if constexpr (SP2) {
;             PG8_LDB(B0, 0, 0); PG8_LDB(B1, 0, 1); PG8_SCHED; PG8_LDA(At, 0, 0); PG8_STAGE(PG8_SA(1, 1), a1 + hstepA, voffA);
;             PG8_WAIT_V(8); PG8_WAIT_L(0); PG8_BAR; PG8_MMA(0, 0, At, B0); PG8_MMA(0, 1, At, B1); PG8_BAR; PG8_SCHED;
;             PG8_LDA(At, 0, 1); PG8_STAGE(PG8_SB(0, 0), b2, voffB); PG8_STAGE(PG8_SB(0, 1), b2 + hstepB, voffB); PG8_STAGE(PG8_SA(0, 0), a2, voffA);
.LBB0_1048:
	s_or_b32 s58, s66, 1
	s_add_i32 s66, s66, 2
	s_mov_b32 s67, s59
	s_lshl_b64 s[4:5], s[58:59], 7
	s_lshl_b64 s[6:7], s[66:67], 7
	s_add_u32 s46, s60, s6
	s_addc_u32 s47, s61, s7
	s_and_b64 s[12:13], s[76:77], exec
	s_cselect_b32 vcc_hi, s47, s49
	s_cselect_b32 vcc_lo, s46, s48
	s_add_u32 s12, s62, s6
	s_addc_u32 s13, s63, s7
	s_and_b64 s[6:7], s[76:77], exec
	s_cselect_b32 s77, s13, s55
	s_cselect_b32 s76, s12, s54
	s_add_u32 s4, s35, s4
	s_addc_u32 s5, s39, s5
	v_lshl_add_u64 v[182:183], s[4:5], 0, v[144:145]
	s_add_i32 m0, s21, 0xc000
	s_nop 0
	global_load_lds_dwordx4 v[182:183], off
	v_lshl_add_u64 v[182:183], s[4:5], 0, v[148:149]
	s_add_i32 m0, s21, 0xe000
	s_nop 0
	global_load_lds_dwordx4 v[182:183], off
	v_add_u32_e32 v140, s10, v179
	v_add_u32_e32 v182, s11, v179
	ds_read_b128 v[128:131], v140
	ds_read_b128 v[132:135], v140 offset:1024
	ds_read_b128 v[136:139], v140 offset:2048
	ds_read_b128 v[140:143], v140 offset:3072
	ds_read_b128 v[174:177], v182
	ds_read_b128 v[190:193], v182 offset:1024
	ds_read_b128 v[194:197], v182 offset:2048
	ds_read_b128 v[198:201], v182 offset:3072
	ds_read_b128 v[202:205], v181
	ds_read_b128 v[206:209], v181 offset:1024
	ds_read_b128 v[210:213], v181 offset:2048
	ds_read_b128 v[214:217], v181 offset:3072
	ds_read_b128 v[218:221], v181 offset:4096
	ds_read_b128 v[222:225], v181 offset:5120
	ds_read_b128 v[226:229], v181 offset:6144
	ds_read_b128 v[230:233], v181 offset:7168
	s_waitcnt vmcnt(8)
	s_waitcnt lgkmcnt(0)
	s_setprio 1
	s_barrier
	v_mfma_f32_16x16x32_bf16 v[124:127], v[128:131], v[202:205], v[124:127]
	v_mfma_f32_16x16x32_bf16 v[120:123], v[136:139], v[202:205], v[120:123]
	v_mfma_f32_16x16x32_bf16 v[116:119], v[128:131], v[210:213], v[116:119]
	v_mfma_f32_16x16x32_bf16 v[112:115], v[136:139], v[210:213], v[112:115]
	v_mfma_f32_16x16x32_bf16 v[108:111], v[128:131], v[218:221], v[108:111]
	v_mfma_f32_16x16x32_bf16 v[104:107], v[136:139], v[218:221], v[104:107]
	v_mfma_f32_16x16x32_bf16 v[100:103], v[128:131], v[226:229], v[100:103]
	v_mfma_f32_16x16x32_bf16 v[96:99], v[136:139], v[226:229], v[96:99]
	v_mfma_f32_16x16x32_bf16 v[124:127], v[132:135], v[206:209], v[124:127]
	v_mfma_f32_16x16x32_bf16 v[120:123], v[140:143], v[206:209], v[120:123]
	v_mfma_f32_16x16x32_bf16 v[116:119], v[132:135], v[214:217], v[116:119]
	v_mfma_f32_16x16x32_bf16 v[112:115], v[140:143], v[214:217], v[112:115]
	v_mfma_f32_16x16x32_bf16 v[108:111], v[132:135], v[222:225], v[108:111]
	v_mfma_f32_16x16x32_bf16 v[104:107], v[140:143], v[222:225], v[104:107]
	v_mfma_f32_16x16x32_bf16 v[100:103], v[132:135], v[230:233], v[100:103]
	v_mfma_f32_16x16x32_bf16 v[96:99], v[140:143], v[230:233], v[96:99]
	s_setprio 0
	s_setprio 1
	v_mfma_f32_16x16x32_bf16 v[92:95], v[174:177], v[202:205], v[92:95]
	v_mfma_f32_16x16x32_bf16 v[88:91], v[194:197], v[202:205], v[88:91]
	v_mfma_f32_16x16x32_bf16 v[84:87], v[174:177], v[210:213], v[84:87]
	v_mfma_f32_16x16x32_bf16 v[80:83], v[194:197], v[210:213], v[80:83]
	v_mfma_f32_16x16x32_bf16 v[76:79], v[174:177], v[218:221], v[76:79]
	v_mfma_f32_16x16x32_bf16 v[72:75], v[194:197], v[218:221], v[72:75]
	v_mfma_f32_16x16x32_bf16 v[68:71], v[174:177], v[226:229], v[68:71]
	v_mfma_f32_16x16x32_bf16 v[64:67], v[194:197], v[226:229], v[64:67]
	v_mfma_f32_16x16x32_bf16 v[92:95], v[190:193], v[206:209], v[92:95]
	v_mfma_f32_16x16x32_bf16 v[88:91], v[198:201], v[206:209], v[88:91]
	v_mfma_f32_16x16x32_bf16 v[84:87], v[190:193], v[214:217], v[84:87]
	v_mfma_f32_16x16x32_bf16 v[80:83], v[198:201], v[214:217], v[80:83]
	v_mfma_f32_16x16x32_bf16 v[76:79], v[190:193], v[222:225], v[76:79]
	v_mfma_f32_16x16x32_bf16 v[72:75], v[198:201], v[222:225], v[72:75]
	v_mfma_f32_16x16x32_bf16 v[68:71], v[190:193], v[230:233], v[68:71]
	v_mfma_f32_16x16x32_bf16 v[64:67], v[198:201], v[230:233], v[64:67]
	s_barrier
	s_setprio 0
	s_add_i32 s4, s10, s94
	v_lshl_add_u64 v[182:183], s[76:77], 0, v[146:147]
	s_mov_b32 m0, s4
	s_nop 0
	global_load_lds_dwordx4 v[182:183], off
	s_add_i32 m0, s4, 0x2000
	s_add_u32 s4, s76, 0x80000
	v_lshl_add_u64 v[234:235], s[76:77], 0, v[150:151]
	s_addc_u32 s5, s77, 0
	s_add_i32 s6, s11, s94
	global_load_lds_dwordx4 v[234:235], off
	v_lshl_add_u64 v[236:237], s[4:5], 0, v[146:147]
	s_mov_b32 m0, s6
	v_lshl_add_u64 v[238:239], vcc, 0, v[148:149]
	global_load_lds_dwordx4 v[236:237], off
	v_lshl_add_u64 v[236:237], s[4:5], 0, v[150:151]
	s_add_i32 m0, s6, 0x2000
	s_nop 0
	global_load_lds_dwordx4 v[236:237], off
	v_lshl_add_u64 v[236:237], vcc, 0, v[144:145]
	s_mov_b32 m0, s21
	s_nop 0
	global_load_lds_dwordx4 v[236:237], off
	s_mov_b32 m0, s95
	s_nop 0
	global_load_lds_dwordx4 v[238:239], off
	ds_read_b128 v[202:205], v181 offset:16384
	ds_read_b128 v[206:209], v181 offset:17408
	ds_read_b128 v[210:213], v181 offset:18432
	ds_read_b128 v[214:217], v181 offset:19456
	ds_read_b128 v[218:221], v181 offset:20480
	ds_read_b128 v[222:225], v181 offset:21504
	ds_read_b128 v[226:229], v181 offset:22528
	ds_read_b128 v[230:233], v181 offset:23552
	s_waitcnt vmcnt(8)
	s_waitcnt lgkmcnt(0)
	s_setprio 1
	s_barrier
; #define PG8_STAGE(bufoff, gbase, voff) do { _Pragma("unroll") for (int _i = 0; _i < 2; ++_i) \
;         __builtin_amdgcn_global_load_lds((const unsigned*)((const char*)(gbase) + (voff)[_i]), (PG8_LAS unsigned*)(lds + (bufoff) + ldsw + _i * 8192), 16, 0, 0); } while (0)
; #define PG8_LDA(dst, b, h) do { _Pragma("unroll") for (int m = 0; m < 4; ++m) _Pragma("unroll") for (int k = 0; k < 2; ++k) dst[m][k] = *(const PG8_LAS bf16x8*)(lds + PG8_SA(b, h) + aoff + m * 2048 + k * 1024); } while (0)
; #define PG8_LDB(dst, b, h) do { _Pragma("unroll") for (int n = 0; n < 2; ++n) _Pragma("unroll") for (int k = 0; k < 2; ++k) dst[n][k] = *(const PG8_LAS bf16x8*)(lds + PG8_SB(b, h) + boff + n * 2048 + k * 1024); } while (0)
; #define PG8_MMA(ai, bj, At, Bt) do { __builtin_amdgcn_s_setprio(1); _Pragma("unroll") for (int m = 0; m < 4; ++m) _Pragma("unroll") for (int n = 0; n < 2; ++n) _Pragma("unroll") for (int k = 0; k < 2; ++k) \
;         acc[ai][bj][m][n] = __builtin_amdgcn_mfma_f32_16x16x32_bf16(Bt[n][k], At[m][k], acc[ai][bj][m][n], 0, 0, 0); __builtin_amdgcn_s_setprio(0); } while (0)
; #define PG8_WAIT_V(n) asm volatile("s_waitcnt vmcnt(" #n ")" ::: "memory")
; #define PG8_WAIT_L(n) asm volatile("s_waitcnt lgkmcnt(" #n ")" ::: "memory")
; #define PG8_BAR __builtin_amdgcn_s_barrier()
; #define PG8_SCHED __builtin_amdgcn_sched_barrier(0)
; template <class Epi, class Sched, bool ALIGN_EPI = false, bool SP2 = false>
; __device__ __forceinline__ void gemm_phase(PG8_LAS unsigned char* lds, const Gemm g, const Sched& S, const Epi& E) {
;     ...
;             PG8_WAIT_V(8); PG8_WAIT_L(0); PG8_BAR; PG8_MMA(1, 0, At, B0); PG8_MMA(1, 1, At, B1); PG8_BAR; PG8_SCHED;
;             PG8_LDB(B0, 1, 0); PG8_LDB(B1, 1, 1); PG8_SCHED; PG8_LDA(At, 1, 0); PG8_STAGE(PG8_SA(0, 1), a2 + hstepA, voffA);
;             PG8_WAIT_V(8); PG8_WAIT_L(0); PG8_BAR; PG8_MMA(0, 0, At, B0); PG8_MMA(0, 1, At, B1); PG8_BAR; PG8_SCHED;
	v_mfma_f32_16x16x32_bf16 v[60:63], v[128:131], v[202:205], v[60:63]
	v_mfma_f32_16x16x32_bf16 v[56:59], v[136:139], v[202:205], v[56:59]
	v_mfma_f32_16x16x32_bf16 v[52:55], v[128:131], v[210:213], v[52:55]
	v_mfma_f32_16x16x32_bf16 v[48:51], v[136:139], v[210:213], v[48:51]
	v_mfma_f32_16x16x32_bf16 v[44:47], v[128:131], v[218:221], v[44:47]
	v_mfma_f32_16x16x32_bf16 v[40:43], v[136:139], v[218:221], v[40:43]
	v_mfma_f32_16x16x32_bf16 v[36:39], v[128:131], v[226:229], v[36:39]
	v_mfma_f32_16x16x32_bf16 v[32:35], v[136:139], v[226:229], v[32:35]
	v_mfma_f32_16x16x32_bf16 v[60:63], v[132:135], v[206:209], v[60:63]
	v_mfma_f32_16x16x32_bf16 v[56:59], v[140:143], v[206:209], v[56:59]
	v_mfma_f32_16x16x32_bf16 v[52:55], v[132:135], v[214:217], v[52:55]
	v_mfma_f32_16x16x32_bf16 v[48:51], v[140:143], v[214:217], v[48:51]
	v_mfma_f32_16x16x32_bf16 v[44:47], v[132:135], v[222:225], v[44:47]
	v_mfma_f32_16x16x32_bf16 v[40:43], v[140:143], v[222:225], v[40:43]
	v_mfma_f32_16x16x32_bf16 v[36:39], v[132:135], v[230:233], v[36:39]
	v_mfma_f32_16x16x32_bf16 v[32:35], v[140:143], v[230:233], v[32:35]
	s_setprio 0
	s_setprio 1
	v_mfma_f32_16x16x32_bf16 v[28:31], v[174:177], v[202:205], v[28:31]
	v_mfma_f32_16x16x32_bf16 v[24:27], v[194:197], v[202:205], v[24:27]
	v_mfma_f32_16x16x32_bf16 v[20:23], v[174:177], v[210:213], v[20:23]
	v_mfma_f32_16x16x32_bf16 v[16:19], v[194:197], v[210:213], v[16:19]
	v_mfma_f32_16x16x32_bf16 v[12:15], v[174:177], v[218:221], v[12:15]
	v_mfma_f32_16x16x32_bf16 v[8:11], v[194:197], v[218:221], v[8:11]
	v_mfma_f32_16x16x32_bf16 v[4:7], v[174:177], v[226:229], v[4:7]
	v_mfma_f32_16x16x32_bf16 v[0:3], v[194:197], v[226:229], v[0:3]
	v_mfma_f32_16x16x32_bf16 v[28:31], v[190:193], v[206:209], v[28:31]
	v_mfma_f32_16x16x32_bf16 v[24:27], v[198:201], v[206:209], v[24:27]
	v_mfma_f32_16x16x32_bf16 v[20:23], v[190:193], v[214:217], v[20:23]
	v_mfma_f32_16x16x32_bf16 v[16:19], v[198:201], v[214:217], v[16:19]
	v_mfma_f32_16x16x32_bf16 v[12:15], v[190:193], v[222:225], v[12:15]
	v_mfma_f32_16x16x32_bf16 v[8:11], v[198:201], v[222:225], v[8:11]
	v_mfma_f32_16x16x32_bf16 v[4:7], v[190:193], v[230:233], v[4:7]
	v_mfma_f32_16x16x32_bf16 v[0:3], v[198:201], v[230:233], v[0:3]
	s_barrier
	s_setprio 0
	s_add_i32 s6, 0, 0x18000
	s_add_i32 s7, 0, 0x1c000
	s_add_u32 s4, vcc_lo, 0x80000
	s_addc_u32 s5, vcc_hi, 0
	s_mov_b32 m0, s96
	v_lshl_add_u64 v[240:241], s[4:5], 0, v[144:145]
	global_load_lds_dwordx4 v[240:241], off
	v_lshl_add_u64 v[240:241], s[4:5], 0, v[148:149]
	s_mov_b32 m0, s97
	s_nop 0
	global_load_lds_dwordx4 v[240:241], off
	v_add_u32_e32 v140, s6, v179
	v_add_u32_e32 v198, s7, v179
	ds_read_b128 v[128:131], v140
	ds_read_b128 v[132:135], v140 offset:1024
	ds_read_b128 v[136:139], v140 offset:2048
	ds_read_b128 v[140:143], v140 offset:3072
	ds_read_b128 v[174:177], v198
	ds_read_b128 v[190:193], v198 offset:1024
	ds_read_b128 v[194:197], v198 offset:2048
	ds_read_b128 v[198:201], v198 offset:3072
	ds_read_b128 v[202:205], v181 offset:32768
	ds_read_b128 v[206:209], v181 offset:33792
	ds_read_b128 v[210:213], v181 offset:34816
	ds_read_b128 v[214:217], v181 offset:35840
	ds_read_b128 v[218:221], v181 offset:36864
	ds_read_b128 v[222:225], v181 offset:37888
	ds_read_b128 v[226:229], v181 offset:38912
	ds_read_b128 v[230:233], v181 offset:39936
	s_waitcnt vmcnt(8)
	s_waitcnt lgkmcnt(0)
	s_setprio 1
	s_barrier
	v_mfma_f32_16x16x32_bf16 v[124:127], v[128:131], v[202:205], v[124:127]
	v_mfma_f32_16x16x32_bf16 v[120:123], v[136:139], v[202:205], v[120:123]
	v_mfma_f32_16x16x32_bf16 v[116:119], v[128:131], v[210:213], v[116:119]
	v_mfma_f32_16x16x32_bf16 v[112:115], v[136:139], v[210:213], v[112:115]
	v_mfma_f32_16x16x32_bf16 v[108:111], v[128:131], v[218:221], v[108:111]
	v_mfma_f32_16x16x32_bf16 v[104:107], v[136:139], v[218:221], v[104:107]
	v_mfma_f32_16x16x32_bf16 v[100:103], v[128:131], v[226:229], v[100:103]
	v_mfma_f32_16x16x32_bf16 v[96:99], v[136:139], v[226:229], v[96:99]
	v_mfma_f32_16x16x32_bf16 v[124:127], v[132:135], v[206:209], v[124:127]
	v_mfma_f32_16x16x32_bf16 v[120:123], v[140:143], v[206:209], v[120:123]
	v_mfma_f32_16x16x32_bf16 v[116:119], v[132:135], v[214:217], v[116:119]
	v_mfma_f32_16x16x32_bf16 v[112:115], v[140:143], v[214:217], v[112:115]
	v_mfma_f32_16x16x32_bf16 v[108:111], v[132:135], v[222:225], v[108:111]
	v_mfma_f32_16x16x32_bf16 v[104:107], v[140:143], v[222:225], v[104:107]
	v_mfma_f32_16x16x32_bf16 v[100:103], v[132:135], v[230:233], v[100:103]
	v_mfma_f32_16x16x32_bf16 v[96:99], v[140:143], v[230:233], v[96:99]
	s_setprio 0
	s_setprio 1
	v_mfma_f32_16x16x32_bf16 v[92:95], v[174:177], v[202:205], v[92:95]
	v_mfma_f32_16x16x32_bf16 v[88:91], v[194:197], v[202:205], v[88:91]
	v_mfma_f32_16x16x32_bf16 v[84:87], v[174:177], v[210:213], v[84:87]
	v_mfma_f32_16x16x32_bf16 v[80:83], v[194:197], v[210:213], v[80:83]
	v_mfma_f32_16x16x32_bf16 v[76:79], v[174:177], v[218:221], v[76:79]
	v_mfma_f32_16x16x32_bf16 v[72:75], v[194:197], v[218:221], v[72:75]
	v_mfma_f32_16x16x32_bf16 v[68:71], v[174:177], v[226:229], v[68:71]
	v_mfma_f32_16x16x32_bf16 v[64:67], v[194:197], v[226:229], v[64:67]
	v_mfma_f32_16x16x32_bf16 v[92:95], v[190:193], v[206:209], v[92:95]
	v_mfma_f32_16x16x32_bf16 v[88:91], v[198:201], v[206:209], v[88:91]
	v_mfma_f32_16x16x32_bf16 v[84:87], v[190:193], v[214:217], v[84:87]
	v_mfma_f32_16x16x32_bf16 v[80:83], v[198:201], v[214:217], v[80:83]
	v_mfma_f32_16x16x32_bf16 v[76:79], v[190:193], v[222:225], v[76:79]
	v_mfma_f32_16x16x32_bf16 v[72:75], v[198:201], v[222:225], v[72:75]
	v_mfma_f32_16x16x32_bf16 v[68:71], v[190:193], v[230:233], v[68:71]
	v_mfma_f32_16x16x32_bf16 v[64:67], v[198:201], v[230:233], v[64:67]
	s_barrier
; #define PG8_STAGE(bufoff, gbase, voff) do { _Pragma("unroll") for (int _i = 0; _i < 2; ++_i) \
;         __builtin_amdgcn_global_load_lds((const unsigned*)((const char*)(gbase) + (voff)[_i]), (PG8_LAS unsigned*)(lds + (bufoff) + ldsw + _i * 8192), 16, 0, 0); } while (0)
; #define PG8_LDA(dst, b, h) do { _Pragma("unroll") for (int m = 0; m < 4; ++m) _Pragma("unroll") for (int k = 0; k < 2; ++k) dst[m][k] = *(const PG8_LAS bf16x8*)(lds + PG8_SA(b, h) + aoff + m * 2048 + k * 1024); } while (0)
; #define PG8_MMA(ai, bj, At, Bt) do { __builtin_amdgcn_s_setprio(1); _Pragma("unroll") for (int m = 0; m < 4; ++m) _Pragma("unroll") for (int n = 0; n < 2; ++n) _Pragma("unroll") for (int k = 0; k < 2; ++k) \
;         acc[ai][bj][m][n] = __builtin_amdgcn_mfma_f32_16x16x32_bf16(Bt[n][k], At[m][k], acc[ai][bj][m][n], 0, 0, 0); __builtin_amdgcn_s_setprio(0); } while (0)
; #define PG8_WAIT_V(n) asm volatile("s_waitcnt vmcnt(" #n ")" ::: "memory")
; #define PG8_WAIT_L(n) asm volatile("s_waitcnt lgkmcnt(" #n ")" ::: "memory")
; #define PG8_BAR __builtin_amdgcn_s_barrier()
; #define PG8_SCHED __builtin_amdgcn_sched_barrier(0)
; template <class Epi, class Sched, bool ALIGN_EPI = false, bool SP2 = false>
; __device__ __forceinline__ void gemm_phase(PG8_LAS unsigned char* lds, const Gemm g, const Sched& S, const Epi& E) {
;     ...
;             PG8_LDA(At, 1, 1); PG8_STAGE(PG8_SB(1, 0), b3, voffB); PG8_STAGE(PG8_SB(1, 1), b3 + hstepB, voffB); PG8_STAGE(PG8_SA(1, 0), a3, voffA);
;             PG8_WAIT_V(8); PG8_WAIT_L(0); PG8_BAR; PG8_MMA(1, 0, At, B0); PG8_MMA(1, 1, At, B1); PG8_BAR; PG8_SCHED;
	s_setprio 0
	s_add_i32 s4, s6, s94
	v_lshl_add_u64 v[182:183], v[182:183], 0, s[70:71]
	s_mov_b32 m0, s4
	s_nop 0
	global_load_lds_dwordx4 v[182:183], off
	s_add_i32 m0, s4, 0x2000
	s_add_u32 s4, s76, 0x80080
	v_lshl_add_u64 v[182:183], v[234:235], 0, s[70:71]
	s_addc_u32 s5, s77, 0
	s_add_i32 s6, s7, s94
	global_load_lds_dwordx4 v[182:183], off
	v_lshl_add_u64 v[182:183], s[4:5], 0, v[146:147]
	s_mov_b32 m0, s6
	s_nop 0
	global_load_lds_dwordx4 v[182:183], off
	v_lshl_add_u64 v[182:183], s[4:5], 0, v[150:151]
	s_add_i32 m0, s6, 0x2000
	s_nop 0
	global_load_lds_dwordx4 v[182:183], off
	v_lshl_add_u64 v[182:183], v[236:237], 0, s[70:71]
	s_mov_b32 m0, s56
	s_nop 0
	global_load_lds_dwordx4 v[182:183], off
	v_lshl_add_u64 v[182:183], v[238:239], 0, s[70:71]
	s_mov_b32 m0, s57
	s_nop 0
	global_load_lds_dwordx4 v[182:183], off
	ds_read_b128 v[202:205], v181 offset:49152
	ds_read_b128 v[206:209], v181 offset:50176
	ds_read_b128 v[210:213], v181 offset:51200
	ds_read_b128 v[214:217], v181 offset:52224
	ds_read_b128 v[218:221], v181 offset:53248
	ds_read_b128 v[222:225], v181 offset:54272
	ds_read_b128 v[226:229], v181 offset:55296
	ds_read_b128 v[230:233], v181 offset:56320
	s_waitcnt vmcnt(8)
	s_waitcnt lgkmcnt(0)
	s_setprio 1
	s_barrier
	v_mfma_f32_16x16x32_bf16 v[60:63], v[128:131], v[202:205], v[60:63]
	v_mfma_f32_16x16x32_bf16 v[56:59], v[136:139], v[202:205], v[56:59]
	v_mfma_f32_16x16x32_bf16 v[52:55], v[128:131], v[210:213], v[52:55]
	v_mfma_f32_16x16x32_bf16 v[48:51], v[136:139], v[210:213], v[48:51]
	v_mfma_f32_16x16x32_bf16 v[44:47], v[128:131], v[218:221], v[44:47]
	v_mfma_f32_16x16x32_bf16 v[40:43], v[136:139], v[218:221], v[40:43]
	v_mfma_f32_16x16x32_bf16 v[36:39], v[128:131], v[226:229], v[36:39]
	v_mfma_f32_16x16x32_bf16 v[32:35], v[136:139], v[226:229], v[32:35]
	v_mfma_f32_16x16x32_bf16 v[60:63], v[132:135], v[206:209], v[60:63]
	v_mfma_f32_16x16x32_bf16 v[56:59], v[140:143], v[206:209], v[56:59]
	v_mfma_f32_16x16x32_bf16 v[52:55], v[132:135], v[214:217], v[52:55]
	v_mfma_f32_16x16x32_bf16 v[48:51], v[140:143], v[214:217], v[48:51]
	v_mfma_f32_16x16x32_bf16 v[44:47], v[132:135], v[222:225], v[44:47]
	v_mfma_f32_16x16x32_bf16 v[40:43], v[140:143], v[222:225], v[40:43]
	v_mfma_f32_16x16x32_bf16 v[36:39], v[132:135], v[230:233], v[36:39]
	v_mfma_f32_16x16x32_bf16 v[32:35], v[140:143], v[230:233], v[32:35]
	s_setprio 0
	s_setprio 1
	v_mfma_f32_16x16x32_bf16 v[28:31], v[174:177], v[202:205], v[28:31]
	v_mfma_f32_16x16x32_bf16 v[24:27], v[194:197], v[202:205], v[24:27]
	v_mfma_f32_16x16x32_bf16 v[20:23], v[174:177], v[210:213], v[20:23]
	v_mfma_f32_16x16x32_bf16 v[16:19], v[194:197], v[210:213], v[16:19]
	v_mfma_f32_16x16x32_bf16 v[12:15], v[174:177], v[218:221], v[12:15]
	v_mfma_f32_16x16x32_bf16 v[8:11], v[194:197], v[218:221], v[8:11]
	v_mfma_f32_16x16x32_bf16 v[4:7], v[174:177], v[226:229], v[4:7]
	v_mfma_f32_16x16x32_bf16 v[0:3], v[194:197], v[226:229], v[0:3]
	v_mfma_f32_16x16x32_bf16 v[28:31], v[190:193], v[206:209], v[28:31]
	v_mfma_f32_16x16x32_bf16 v[24:27], v[198:201], v[206:209], v[24:27]
	v_mfma_f32_16x16x32_bf16 v[20:23], v[190:193], v[214:217], v[20:23]
	v_mfma_f32_16x16x32_bf16 v[16:19], v[198:201], v[214:217], v[16:19]
	v_mfma_f32_16x16x32_bf16 v[12:15], v[190:193], v[222:225], v[12:15]
	v_mfma_f32_16x16x32_bf16 v[8:11], v[198:201], v[222:225], v[8:11]
	v_mfma_f32_16x16x32_bf16 v[4:7], v[190:193], v[230:233], v[4:7]
	v_mfma_f32_16x16x32_bf16 v[0:3], v[198:201], v[230:233], v[0:3]
	s_barrier
	s_setprio 0
	s_cmp_ge_i32 s66, s44
	s_cbranch_scc1 .LBB0_1066

; #define PG8_STAGE(bufoff, gbase, voff) do { _Pragma("unroll") for (int _i = 0; _i < 2; ++_i) \
;         __builtin_amdgcn_global_load_lds((const unsigned*)((const char*)(gbase) + (voff)[_i]), (PG8_LAS unsigned*)(lds + (bufoff) + ldsw + _i * 8192), 16, 0, 0); } while (0)
; #define PG8_LDA(dst, b, h) do { _Pragma("unroll") for (int m = 0; m < 4; ++m) _Pragma("unroll") for (int k = 0; k < 2; ++k) dst[m][k] = *(const PG8_LAS bf16x8*)(lds + PG8_SA(b, h) + aoff + m * 2048 + k * 1024); } while (0)
; #define PG8_LDB(dst, b, h) do { _Pragma("unroll") for (int n = 0; n < 2; ++n) _Pragma("unroll") for (int k = 0; k < 2; ++k) dst[n][k] = *(const PG8_LAS bf16x8*)(lds + PG8_SB(b, h) + boff + n * 2048 + k * 1024); } while (0)
; #define PG8_MMA(ai, bj, At, Bt) do { __builtin_amdgcn_s_setprio(1); _Pragma("unroll") for (int m = 0; m < 4; ++m) _Pragma("unroll") for (int n = 0; n < 2; ++n) _Pragma("unroll") for (int k = 0; k < 2; ++k) \
;         acc[ai][bj][m][n] = __builtin_amdgcn_mfma_f32_16x16x32_bf16(Bt[n][k], At[m][k], acc[ai][bj][m][n], 0, 0, 0); __builtin_amdgcn_s_setprio(0); } while (0)
; #define PG8_WAIT_V(n) asm volatile("s_waitcnt vmcnt(" #n ")" ::: "memory")
; #define PG8_WAIT_L(n) asm volatile("s_waitcnt lgkmcnt(" #n ")" ::: "memory")
; #define PG8_BAR __builtin_amdgcn_s_barrier()
; #define PG8_SCHED __builtin_amdgcn_sched_barrier(0)
; template <class Epi, class Sched, bool ALIGN_EPI = false, bool SP2 = false>
; __device__ __forceinline__ void gemm_phase(PG8_LAS unsigned char* lds, const Gemm g, const Sched& S, const Epi& E) {
;     ...
;             const char* a1 = cA + (size_t)(t + 1) * kstA;
;             const char* a2 = last ? nA : cA + (size_t)(t + 2) * kstA; const char* b2 = last ? nB : cB + (size_t)(t + 2) * kstep;
;             const char* a3 = a2 + kstA; const char* b3 = b2 + kstep;
;             if (last && has_next) S.a_ready(nxt);
;             if constexpr (SP2) {
;             PG8_LDB(B0, 0, 0); PG8_LDB(B1, 0, 1); PG8_SCHED; PG8_LDA(At, 0, 0); PG8_STAGE(PG8_SA(1, 1), a1 + hstepA, voffA);
;             PG8_WAIT_V(8); PG8_WAIT_L(0); PG8_BAR; PG8_MMA(0, 0, At, B0); PG8_MMA(0, 1, At, B1); PG8_BAR; PG8_SCHED;
;             PG8_LDA(At, 0, 1); PG8_STAGE(PG8_SB(0, 0), b2, voffB); PG8_STAGE(PG8_SB(0, 1), b2 + hstepB, voffB); PG8_STAGE(PG8_SA(0, 0), a2, voffA);
.LBB0_1307:
	s_add_u32 s52, s50, 0xfff80080
	s_addc_u32 s53, s51, -1
	s_cmp_eq_u32 s63, 28
	s_cselect_b32 s59, s4, s53
	s_cselect_b32 s58, s5, s52
	s_cselect_b32 s53, s12, s41
	s_cselect_b32 s52, s13, s39
	v_lshl_add_u64 v[226:227], s[50:51], 0, v[142:143]
	s_add_i32 m0, s7, 0xc000
	s_nop 0
	global_load_lds_dwordx4 v[226:227], off
	v_lshl_add_u64 v[226:227], s[50:51], 0, v[144:145]
	s_add_i32 m0, s7, 0xe000
	s_nop 0
	global_load_lds_dwordx4 v[226:227], off
	ds_read_b128 v[156:159], v152
	ds_read_b128 v[160:163], v152 offset:1024
	ds_read_b128 v[164:167], v152 offset:2048
	ds_read_b128 v[168:171], v152 offset:3072
	ds_read_b128 v[172:175], v153
	ds_read_b128 v[176:179], v153 offset:1024
	ds_read_b128 v[180:183], v153 offset:2048
	ds_read_b128 v[190:193], v153 offset:3072
	ds_read_b128 v[194:197], v154
	ds_read_b128 v[198:201], v154 offset:1024
	ds_read_b128 v[202:205], v154 offset:2048
	ds_read_b128 v[206:209], v154 offset:3072
	ds_read_b128 v[210:213], v154 offset:4096
	ds_read_b128 v[214:217], v154 offset:5120
	ds_read_b128 v[218:221], v154 offset:6144
	ds_read_b128 v[222:225], v154 offset:7168
	s_waitcnt vmcnt(8)
	s_waitcnt lgkmcnt(0)
	s_setprio 1
	s_barrier
	v_mfma_f32_16x16x32_bf16 v[124:127], v[156:159], v[194:197], v[124:127]
	v_mfma_f32_16x16x32_bf16 v[120:123], v[164:167], v[194:197], v[120:123]
	v_mfma_f32_16x16x32_bf16 v[108:111], v[156:159], v[202:205], v[108:111]
	v_mfma_f32_16x16x32_bf16 v[104:107], v[164:167], v[202:205], v[104:107]
	v_mfma_f32_16x16x32_bf16 v[92:95], v[156:159], v[210:213], v[92:95]
	v_mfma_f32_16x16x32_bf16 v[88:91], v[164:167], v[210:213], v[88:91]
	v_mfma_f32_16x16x32_bf16 v[76:79], v[156:159], v[218:221], v[76:79]
	v_mfma_f32_16x16x32_bf16 v[72:75], v[164:167], v[218:221], v[72:75]
	v_mfma_f32_16x16x32_bf16 v[124:127], v[160:163], v[198:201], v[124:127]
	v_mfma_f32_16x16x32_bf16 v[120:123], v[168:171], v[198:201], v[120:123]
	v_mfma_f32_16x16x32_bf16 v[108:111], v[160:163], v[206:209], v[108:111]
	v_mfma_f32_16x16x32_bf16 v[104:107], v[168:171], v[206:209], v[104:107]
	v_mfma_f32_16x16x32_bf16 v[92:95], v[160:163], v[214:217], v[92:95]
	v_mfma_f32_16x16x32_bf16 v[88:91], v[168:171], v[214:217], v[88:91]
	v_mfma_f32_16x16x32_bf16 v[76:79], v[160:163], v[222:225], v[76:79]
	v_mfma_f32_16x16x32_bf16 v[72:75], v[168:171], v[222:225], v[72:75]
	s_setprio 0
	s_setprio 1
	v_mfma_f32_16x16x32_bf16 v[116:119], v[172:175], v[194:197], v[116:119]
	v_mfma_f32_16x16x32_bf16 v[112:115], v[180:183], v[194:197], v[112:115]
	v_mfma_f32_16x16x32_bf16 v[100:103], v[172:175], v[202:205], v[100:103]
	v_mfma_f32_16x16x32_bf16 v[96:99], v[180:183], v[202:205], v[96:99]
	v_mfma_f32_16x16x32_bf16 v[84:87], v[172:175], v[210:213], v[84:87]
	v_mfma_f32_16x16x32_bf16 v[80:83], v[180:183], v[210:213], v[80:83]
	v_mfma_f32_16x16x32_bf16 v[68:71], v[172:175], v[218:221], v[68:71]
	v_mfma_f32_16x16x32_bf16 v[64:67], v[180:183], v[218:221], v[64:67]
	v_mfma_f32_16x16x32_bf16 v[116:119], v[176:179], v[198:201], v[116:119]
	v_mfma_f32_16x16x32_bf16 v[112:115], v[190:193], v[198:201], v[112:115]
	v_mfma_f32_16x16x32_bf16 v[100:103], v[176:179], v[206:209], v[100:103]
	v_mfma_f32_16x16x32_bf16 v[96:99], v[190:193], v[206:209], v[96:99]
	v_mfma_f32_16x16x32_bf16 v[84:87], v[176:179], v[214:217], v[84:87]
	v_mfma_f32_16x16x32_bf16 v[80:83], v[190:193], v[214:217], v[80:83]
	v_mfma_f32_16x16x32_bf16 v[68:71], v[176:179], v[222:225], v[68:71]
	v_mfma_f32_16x16x32_bf16 v[64:67], v[190:193], v[222:225], v[64:67]
	s_barrier
	s_setprio 0
	s_add_i32 s64, s57, s6
	v_lshl_add_u64 v[226:227], s[52:53], 0, v[130:131]
	s_mov_b32 m0, s64
	s_nop 0
	global_load_lds_dwordx4 v[226:227], off
	s_add_i32 m0, s64, 0x2000
	s_add_u32 s64, s52, 0x80000
	v_lshl_add_u64 v[228:229], s[52:53], 0, v[134:135]
	s_addc_u32 s65, s53, 0
	s_add_i32 s66, s61, s6
	global_load_lds_dwordx4 v[228:229], off
	v_lshl_add_u64 v[230:231], s[64:65], 0, v[130:131]
	s_mov_b32 m0, s66
	v_lshl_add_u64 v[232:233], s[58:59], 0, v[132:133]
	global_load_lds_dwordx4 v[230:231], off
	v_lshl_add_u64 v[230:231], s[64:65], 0, v[134:135]
	s_add_i32 m0, s66, 0x2000
	s_nop 0
	global_load_lds_dwordx4 v[230:231], off
	v_lshl_add_u64 v[230:231], s[58:59], 0, v[128:129]
	s_mov_b32 m0, s7
	s_nop 0
	global_load_lds_dwordx4 v[230:231], off
	s_mov_b32 m0, s8
	s_nop 0
	global_load_lds_dwordx4 v[232:233], off
	ds_read_b128 v[194:197], v154 offset:16384
	ds_read_b128 v[198:201], v154 offset:17408
	ds_read_b128 v[202:205], v154 offset:18432
	ds_read_b128 v[206:209], v154 offset:19456
	ds_read_b128 v[210:213], v154 offset:20480
	ds_read_b128 v[214:217], v154 offset:21504
	ds_read_b128 v[218:221], v154 offset:22528
	ds_read_b128 v[222:225], v154 offset:23552
	s_waitcnt vmcnt(8)
	s_waitcnt lgkmcnt(0)
	s_setprio 1
	s_barrier
; #define PG8_STAGE(bufoff, gbase, voff) do { _Pragma("unroll") for (int _i = 0; _i < 2; ++_i) \
;         __builtin_amdgcn_global_load_lds((const unsigned*)((const char*)(gbase) + (voff)[_i]), (PG8_LAS unsigned*)(lds + (bufoff) + ldsw + _i * 8192), 16, 0, 0); } while (0)
; #define PG8_LDA(dst, b, h) do { _Pragma("unroll") for (int m = 0; m < 4; ++m) _Pragma("unroll") for (int k = 0; k < 2; ++k) dst[m][k] = *(const PG8_LAS bf16x8*)(lds + PG8_SA(b, h) + aoff + m * 2048 + k * 1024); } while (0)
; #define PG8_LDB(dst, b, h) do { _Pragma("unroll") for (int n = 0; n < 2; ++n) _Pragma("unroll") for (int k = 0; k < 2; ++k) dst[n][k] = *(const PG8_LAS bf16x8*)(lds + PG8_SB(b, h) + boff + n * 2048 + k * 1024); } while (0)
; #define PG8_MMA(ai, bj, At, Bt) do { __builtin_amdgcn_s_setprio(1); _Pragma("unroll") for (int m = 0; m < 4; ++m) _Pragma("unroll") for (int n = 0; n < 2; ++n) _Pragma("unroll") for (int k = 0; k < 2; ++k) \
;         acc[ai][bj][m][n] = __builtin_amdgcn_mfma_f32_16x16x32_bf16(Bt[n][k], At[m][k], acc[ai][bj][m][n], 0, 0, 0); __builtin_amdgcn_s_setprio(0); } while (0)
; #define PG8_WAIT_V(n) asm volatile("s_waitcnt vmcnt(" #n ")" ::: "memory")
; #define PG8_WAIT_L(n) asm volatile("s_waitcnt lgkmcnt(" #n ")" ::: "memory")
; #define PG8_BAR __builtin_amdgcn_s_barrier()
; #define PG8_SCHED __builtin_amdgcn_sched_barrier(0)
; template <class Epi, class Sched, bool ALIGN_EPI = false, bool SP2 = false>
; __device__ __forceinline__ void gemm_phase(PG8_LAS unsigned char* lds, const Gemm g, const Sched& S, const Epi& E) {
;     ...
;             PG8_WAIT_V(8); PG8_WAIT_L(0); PG8_BAR; PG8_MMA(1, 0, At, B0); PG8_MMA(1, 1, At, B1); PG8_BAR; PG8_SCHED;
;             PG8_LDB(B0, 1, 0); PG8_LDB(B1, 1, 1); PG8_SCHED; PG8_LDA(At, 1, 0); PG8_STAGE(PG8_SA(0, 1), a2 + hstepA, voffA);
;             PG8_WAIT_V(8); PG8_WAIT_L(0); PG8_BAR; PG8_MMA(0, 0, At, B0); PG8_MMA(0, 1, At, B1); PG8_BAR; PG8_SCHED;
	v_mfma_f32_16x16x32_bf16 v[60:63], v[156:159], v[194:197], v[60:63]
	v_mfma_f32_16x16x32_bf16 v[56:59], v[164:167], v[194:197], v[56:59]
	v_mfma_f32_16x16x32_bf16 v[44:47], v[156:159], v[202:205], v[44:47]
	v_mfma_f32_16x16x32_bf16 v[40:43], v[164:167], v[202:205], v[40:43]
	v_mfma_f32_16x16x32_bf16 v[28:31], v[156:159], v[210:213], v[28:31]
	v_mfma_f32_16x16x32_bf16 v[24:27], v[164:167], v[210:213], v[24:27]
	v_mfma_f32_16x16x32_bf16 v[12:15], v[156:159], v[218:221], v[12:15]
	v_mfma_f32_16x16x32_bf16 v[8:11], v[164:167], v[218:221], v[8:11]
	v_mfma_f32_16x16x32_bf16 v[60:63], v[160:163], v[198:201], v[60:63]
	v_mfma_f32_16x16x32_bf16 v[56:59], v[168:171], v[198:201], v[56:59]
	v_mfma_f32_16x16x32_bf16 v[44:47], v[160:163], v[206:209], v[44:47]
	v_mfma_f32_16x16x32_bf16 v[40:43], v[168:171], v[206:209], v[40:43]
	v_mfma_f32_16x16x32_bf16 v[28:31], v[160:163], v[214:217], v[28:31]
	v_mfma_f32_16x16x32_bf16 v[24:27], v[168:171], v[214:217], v[24:27]
	v_mfma_f32_16x16x32_bf16 v[12:15], v[160:163], v[222:225], v[12:15]
	v_mfma_f32_16x16x32_bf16 v[8:11], v[168:171], v[222:225], v[8:11]
	s_setprio 0
	s_setprio 1
	v_mfma_f32_16x16x32_bf16 v[52:55], v[172:175], v[194:197], v[52:55]
	v_mfma_f32_16x16x32_bf16 v[48:51], v[180:183], v[194:197], v[48:51]
	v_mfma_f32_16x16x32_bf16 v[36:39], v[172:175], v[202:205], v[36:39]
	v_mfma_f32_16x16x32_bf16 v[32:35], v[180:183], v[202:205], v[32:35]
	v_mfma_f32_16x16x32_bf16 v[20:23], v[172:175], v[210:213], v[20:23]
	v_mfma_f32_16x16x32_bf16 v[16:19], v[180:183], v[210:213], v[16:19]
	v_mfma_f32_16x16x32_bf16 v[4:7], v[172:175], v[218:221], v[4:7]
	v_mfma_f32_16x16x32_bf16 v[0:3], v[180:183], v[218:221], v[0:3]
	v_mfma_f32_16x16x32_bf16 v[52:55], v[176:179], v[198:201], v[52:55]
	v_mfma_f32_16x16x32_bf16 v[48:51], v[190:193], v[198:201], v[48:51]
	v_mfma_f32_16x16x32_bf16 v[36:39], v[176:179], v[206:209], v[36:39]
	v_mfma_f32_16x16x32_bf16 v[32:35], v[190:193], v[206:209], v[32:35]
	v_mfma_f32_16x16x32_bf16 v[20:23], v[176:179], v[214:217], v[20:23]
	v_mfma_f32_16x16x32_bf16 v[16:19], v[190:193], v[214:217], v[16:19]
	v_mfma_f32_16x16x32_bf16 v[4:7], v[176:179], v[222:225], v[4:7]
	v_mfma_f32_16x16x32_bf16 v[0:3], v[190:193], v[222:225], v[0:3]
	s_barrier
	s_setprio 0
	s_add_i32 s64, 0, 0x18000
	s_add_i32 s65, 0, 0x1c000
	s_add_u32 s58, s58, 0x80000
	s_addc_u32 s59, s59, 0
	s_mov_b32 m0, s9
	v_lshl_add_u64 v[234:235], s[58:59], 0, v[128:129]
	global_load_lds_dwordx4 v[234:235], off
	v_lshl_add_u64 v[234:235], s[58:59], 0, v[132:133]
	s_mov_b32 m0, s11
	s_nop 0
	global_load_lds_dwordx4 v[234:235], off
	v_add_u32_e32 v155, s64, v150
	ds_read_b128 v[156:159], v155
	ds_read_b128 v[160:163], v155 offset:1024
	ds_read_b128 v[164:167], v155 offset:2048
	ds_read_b128 v[168:171], v155 offset:3072
	v_add_u32_e32 v155, s65, v150
	ds_read_b128 v[172:175], v155
	ds_read_b128 v[176:179], v155 offset:1024
	ds_read_b128 v[180:183], v155 offset:2048
	ds_read_b128 v[190:193], v155 offset:3072
	ds_read_b128 v[194:197], v154 offset:32768
	ds_read_b128 v[198:201], v154 offset:33792
	ds_read_b128 v[202:205], v154 offset:34816
	ds_read_b128 v[206:209], v154 offset:35840
	ds_read_b128 v[210:213], v154 offset:36864
	ds_read_b128 v[214:217], v154 offset:37888
	ds_read_b128 v[218:221], v154 offset:38912
	ds_read_b128 v[222:225], v154 offset:39936
	s_waitcnt vmcnt(8)
	s_waitcnt lgkmcnt(0)
	s_setprio 1
	s_barrier
	v_mfma_f32_16x16x32_bf16 v[124:127], v[156:159], v[194:197], v[124:127]
	v_mfma_f32_16x16x32_bf16 v[120:123], v[164:167], v[194:197], v[120:123]
	v_mfma_f32_16x16x32_bf16 v[108:111], v[156:159], v[202:205], v[108:111]
	v_mfma_f32_16x16x32_bf16 v[104:107], v[164:167], v[202:205], v[104:107]
	v_mfma_f32_16x16x32_bf16 v[92:95], v[156:159], v[210:213], v[92:95]
	v_mfma_f32_16x16x32_bf16 v[88:91], v[164:167], v[210:213], v[88:91]
	v_mfma_f32_16x16x32_bf16 v[76:79], v[156:159], v[218:221], v[76:79]
	v_mfma_f32_16x16x32_bf16 v[72:75], v[164:167], v[218:221], v[72:75]
	v_mfma_f32_16x16x32_bf16 v[124:127], v[160:163], v[198:201], v[124:127]
	v_mfma_f32_16x16x32_bf16 v[120:123], v[168:171], v[198:201], v[120:123]
	v_mfma_f32_16x16x32_bf16 v[108:111], v[160:163], v[206:209], v[108:111]
	v_mfma_f32_16x16x32_bf16 v[104:107], v[168:171], v[206:209], v[104:107]
	v_mfma_f32_16x16x32_bf16 v[92:95], v[160:163], v[214:217], v[92:95]
	v_mfma_f32_16x16x32_bf16 v[88:91], v[168:171], v[214:217], v[88:91]
	v_mfma_f32_16x16x32_bf16 v[76:79], v[160:163], v[222:225], v[76:79]
	v_mfma_f32_16x16x32_bf16 v[72:75], v[168:171], v[222:225], v[72:75]
	s_setprio 0
	s_setprio 1
	v_mfma_f32_16x16x32_bf16 v[116:119], v[172:175], v[194:197], v[116:119]
	v_mfma_f32_16x16x32_bf16 v[112:115], v[180:183], v[194:197], v[112:115]
	v_mfma_f32_16x16x32_bf16 v[100:103], v[172:175], v[202:205], v[100:103]
	v_mfma_f32_16x16x32_bf16 v[96:99], v[180:183], v[202:205], v[96:99]
	v_mfma_f32_16x16x32_bf16 v[84:87], v[172:175], v[210:213], v[84:87]
	v_mfma_f32_16x16x32_bf16 v[80:83], v[180:183], v[210:213], v[80:83]
	v_mfma_f32_16x16x32_bf16 v[68:71], v[172:175], v[218:221], v[68:71]
	v_mfma_f32_16x16x32_bf16 v[64:67], v[180:183], v[218:221], v[64:67]
	v_mfma_f32_16x16x32_bf16 v[116:119], v[176:179], v[198:201], v[116:119]
	v_mfma_f32_16x16x32_bf16 v[112:115], v[190:193], v[198:201], v[112:115]
	v_mfma_f32_16x16x32_bf16 v[100:103], v[176:179], v[206:209], v[100:103]
	v_mfma_f32_16x16x32_bf16 v[96:99], v[190:193], v[206:209], v[96:99]
	v_mfma_f32_16x16x32_bf16 v[84:87], v[176:179], v[214:217], v[84:87]
	v_mfma_f32_16x16x32_bf16 v[80:83], v[190:193], v[214:217], v[80:83]
	v_mfma_f32_16x16x32_bf16 v[68:71], v[176:179], v[222:225], v[68:71]
	v_mfma_f32_16x16x32_bf16 v[64:67], v[190:193], v[222:225], v[64:67]
	s_barrier
; #define PG8_STAGE(bufoff, gbase, voff) do { _Pragma("unroll") for (int _i = 0; _i < 2; ++_i) \
;         __builtin_amdgcn_global_load_lds((const unsigned*)((const char*)(gbase) + (voff)[_i]), (PG8_LAS unsigned*)(lds + (bufoff) + ldsw + _i * 8192), 16, 0, 0); } while (0)
; #define PG8_LDA(dst, b, h) do { _Pragma("unroll") for (int m = 0; m < 4; ++m) _Pragma("unroll") for (int k = 0; k < 2; ++k) dst[m][k] = *(const PG8_LAS bf16x8*)(lds + PG8_SA(b, h) + aoff + m * 2048 + k * 1024); } while (0)
; #define PG8_MMA(ai, bj, At, Bt) do { __builtin_amdgcn_s_setprio(1); _Pragma("unroll") for (int m = 0; m < 4; ++m) _Pragma("unroll") for (int n = 0; n < 2; ++n) _Pragma("unroll") for (int k = 0; k < 2; ++k) \
;         acc[ai][bj][m][n] = __builtin_amdgcn_mfma_f32_16x16x32_bf16(Bt[n][k], At[m][k], acc[ai][bj][m][n], 0, 0, 0); __builtin_amdgcn_s_setprio(0); } while (0)
; #define PG8_WAIT_V(n) asm volatile("s_waitcnt vmcnt(" #n ")" ::: "memory")
; #define PG8_WAIT_L(n) asm volatile("s_waitcnt lgkmcnt(" #n ")" ::: "memory")
; #define PG8_BAR __builtin_amdgcn_s_barrier()
; #define PG8_SCHED __builtin_amdgcn_sched_barrier(0)
; template <class Epi, class Sched, bool ALIGN_EPI = false, bool SP2 = false>
; __device__ __forceinline__ void gemm_phase(PG8_LAS unsigned char* lds, const Gemm g, const Sched& S, const Epi& E) {
;     ...
;             PG8_LDA(At, 1, 1); PG8_STAGE(PG8_SB(1, 0), b3, voffB); PG8_STAGE(PG8_SB(1, 1), b3 + hstepB, voffB); PG8_STAGE(PG8_SA(1, 0), a3, voffA);
;             PG8_WAIT_V(8); PG8_WAIT_L(0); PG8_BAR; PG8_MMA(1, 0, At, B0); PG8_MMA(1, 1, At, B1); PG8_BAR; PG8_SCHED;
	s_setprio 0
	s_add_i32 s58, s64, s6
	v_lshl_add_u64 v[226:227], v[226:227], 0, s[20:21]
	s_mov_b32 m0, s58
	s_nop 0
	global_load_lds_dwordx4 v[226:227], off
	s_add_i32 m0, s58, 0x2000
	s_add_u32 s52, s52, 0x80080
	v_lshl_add_u64 v[226:227], v[228:229], 0, s[20:21]
	s_addc_u32 s53, s53, 0
	s_add_i32 s58, s65, s6
	global_load_lds_dwordx4 v[226:227], off
	v_lshl_add_u64 v[226:227], s[52:53], 0, v[130:131]
	s_mov_b32 m0, s58
	s_nop 0
	global_load_lds_dwordx4 v[226:227], off
	v_lshl_add_u64 v[226:227], s[52:53], 0, v[134:135]
	s_add_i32 m0, s58, 0x2000
	s_nop 0
	global_load_lds_dwordx4 v[226:227], off
	v_lshl_add_u64 v[226:227], v[230:231], 0, s[20:21]
	s_mov_b32 m0, s55
	s_nop 0
	global_load_lds_dwordx4 v[226:227], off
	v_lshl_add_u64 v[226:227], v[232:233], 0, s[20:21]
	s_mov_b32 m0, s56
	s_nop 0
	global_load_lds_dwordx4 v[226:227], off
	ds_read_b128 v[194:197], v154 offset:49152
	ds_read_b128 v[198:201], v154 offset:50176
	ds_read_b128 v[202:205], v154 offset:51200
	ds_read_b128 v[206:209], v154 offset:52224
	ds_read_b128 v[210:213], v154 offset:53248
	ds_read_b128 v[214:217], v154 offset:54272
	ds_read_b128 v[218:221], v154 offset:55296
	ds_read_b128 v[222:225], v154 offset:56320
	s_waitcnt vmcnt(8)
	s_waitcnt lgkmcnt(0)
	s_setprio 1
	s_barrier
	v_mfma_f32_16x16x32_bf16 v[60:63], v[156:159], v[194:197], v[60:63]
	v_mfma_f32_16x16x32_bf16 v[56:59], v[164:167], v[194:197], v[56:59]
	v_mfma_f32_16x16x32_bf16 v[44:47], v[156:159], v[202:205], v[44:47]
	v_mfma_f32_16x16x32_bf16 v[40:43], v[164:167], v[202:205], v[40:43]
	v_mfma_f32_16x16x32_bf16 v[28:31], v[156:159], v[210:213], v[28:31]
	v_mfma_f32_16x16x32_bf16 v[24:27], v[164:167], v[210:213], v[24:27]
	v_mfma_f32_16x16x32_bf16 v[12:15], v[156:159], v[218:221], v[12:15]
	v_mfma_f32_16x16x32_bf16 v[8:11], v[164:167], v[218:221], v[8:11]
	v_mfma_f32_16x16x32_bf16 v[60:63], v[160:163], v[198:201], v[60:63]
	v_mfma_f32_16x16x32_bf16 v[56:59], v[168:171], v[198:201], v[56:59]
	v_mfma_f32_16x16x32_bf16 v[44:47], v[160:163], v[206:209], v[44:47]
	v_mfma_f32_16x16x32_bf16 v[40:43], v[168:171], v[206:209], v[40:43]
	v_mfma_f32_16x16x32_bf16 v[28:31], v[160:163], v[214:217], v[28:31]
	v_mfma_f32_16x16x32_bf16 v[24:27], v[168:171], v[214:217], v[24:27]
	v_mfma_f32_16x16x32_bf16 v[12:15], v[160:163], v[222:225], v[12:15]
	v_mfma_f32_16x16x32_bf16 v[8:11], v[168:171], v[222:225], v[8:11]
	s_setprio 0
	s_setprio 1
	v_mfma_f32_16x16x32_bf16 v[52:55], v[172:175], v[194:197], v[52:55]
	v_mfma_f32_16x16x32_bf16 v[48:51], v[180:183], v[194:197], v[48:51]
	v_mfma_f32_16x16x32_bf16 v[36:39], v[172:175], v[202:205], v[36:39]
	v_mfma_f32_16x16x32_bf16 v[32:35], v[180:183], v[202:205], v[32:35]
	v_mfma_f32_16x16x32_bf16 v[20:23], v[172:175], v[210:213], v[20:23]
	v_mfma_f32_16x16x32_bf16 v[16:19], v[180:183], v[210:213], v[16:19]
	v_mfma_f32_16x16x32_bf16 v[4:7], v[172:175], v[218:221], v[4:7]
	v_mfma_f32_16x16x32_bf16 v[0:3], v[180:183], v[218:221], v[0:3]
	v_mfma_f32_16x16x32_bf16 v[52:55], v[176:179], v[198:201], v[52:55]
	v_mfma_f32_16x16x32_bf16 v[48:51], v[190:193], v[198:201], v[48:51]
	v_mfma_f32_16x16x32_bf16 v[36:39], v[176:179], v[206:209], v[36:39]
	v_mfma_f32_16x16x32_bf16 v[32:35], v[190:193], v[206:209], v[32:35]
	v_mfma_f32_16x16x32_bf16 v[20:23], v[176:179], v[214:217], v[20:23]
	v_mfma_f32_16x16x32_bf16 v[16:19], v[190:193], v[214:217], v[16:19]
	v_mfma_f32_16x16x32_bf16 v[4:7], v[176:179], v[222:225], v[4:7]
	v_mfma_f32_16x16x32_bf16 v[0:3], v[190:193], v[222:225], v[0:3]
	s_barrier
	s_setprio 0
	s_add_i32 s63, s63, 2
	s_add_u32 s50, s50, 0x100
	s_addc_u32 s51, s51, 0
	s_add_u32 s39, s39, 0x100
	s_addc_u32 s41, s41, 0
	s_cmp_gt_u32 s63, 29
	s_cbranch_scc0 .LBB0_1307
	s_and_b64 vcc, exec, s[34:35]
	s_cbranch_vccz .LBB0_1310
	s_barrier

; #define PG8_STAGE(bufoff, gbase, voff) do { _Pragma("unroll") for (int _i = 0; _i < 2; ++_i) \
;         __builtin_amdgcn_global_load_lds((const unsigned*)((const char*)(gbase) + (voff)[_i]), (PG8_LAS unsigned*)(lds + (bufoff) + ldsw + _i * 8192), 16, 0, 0); } while (0)
; #define PG8_LDA(dst, b, h) do { _Pragma("unroll") for (int m = 0; m < 4; ++m) _Pragma("unroll") for (int k = 0; k < 2; ++k) dst[m][k] = *(const PG8_LAS bf16x8*)(lds + PG8_SA(b, h) + aoff + m * 2048 + k * 1024); } while (0)
; #define PG8_LDB(dst, b, h) do { _Pragma("unroll") for (int n = 0; n < 2; ++n) _Pragma("unroll") for (int k = 0; k < 2; ++k) dst[n][k] = *(const PG8_LAS bf16x8*)(lds + PG8_SB(b, h) + boff + n * 2048 + k * 1024); } while (0)
; #define PG8_MMA(ai, bj, At, Bt) do { __builtin_amdgcn_s_setprio(1); _Pragma("unroll") for (int m = 0; m < 4; ++m) _Pragma("unroll") for (int n = 0; n < 2; ++n) _Pragma("unroll") for (int k = 0; k < 2; ++k) \
;         acc[ai][bj][m][n] = __builtin_amdgcn_mfma_f32_16x16x32_bf16(Bt[n][k], At[m][k], acc[ai][bj][m][n], 0, 0, 0); __builtin_amdgcn_s_setprio(0); } while (0)
; #define PG8_WAIT_V(n) asm volatile("s_waitcnt vmcnt(" #n ")" ::: "memory")
; #define PG8_BAR __builtin_amdgcn_s_barrier()
; template <class Epi, class Sched, bool ALIGN_EPI = false, bool SP2 = false>
; __device__ __forceinline__ void gemm_phase(PG8_LAS unsigned char* lds, const Gemm g, const Sched& S, const Epi& E) {
;     ...
;         for (int t = 0; t < nt; t += 2) {
;             const bool last = (t == nt - 2);
;             const char* a1 = cA + (size_t)(t + 1) * kstA;
;             const char* a2 = last ? nA : cA + (size_t)(t + 2) * kstA; const char* b2 = last ? nB : cB + (size_t)(t + 2) * kstep;
;             const char* a3 = a2 + kstA; const char* b3 = b2 + kstep;
;             if (last && has_next) S.a_ready(nxt);
;             if constexpr (SP2) {
;             PG8_LDB(B0, 0, 0); PG8_LDB(B1, 0, 1); PG8_SCHED; PG8_LDA(At, 0, 0); PG8_STAGE(PG8_SA(1, 1), a1 + hstepA, voffA);
;             PG8_WAIT_V(8); PG8_WAIT_L(0); PG8_BAR; PG8_MMA(0, 0, At, B0); PG8_MMA(0, 1, At, B1); PG8_BAR; PG8_SCHED;
;             PG8_LDA(At, 0, 1); PG8_STAGE(PG8_SB(0, 0), b2, voffB); PG8_STAGE(PG8_SB(0, 1), b2 + hstepB, voffB); PG8_STAGE(PG8_SA(0, 0), a2, voffA);
;             PG8_WAIT_V(8); PG8_WAIT_L(0); PG8_BAR; PG8_MMA(1, 0, At, B0); PG8_MMA(1, 1, At, B1); PG8_BAR; PG8_SCHED;
.LBB0_1404:
	s_or_b32 s48, s68, 1
	s_add_i32 s68, s68, 2
	s_mov_b32 s69, s49
	s_lshl_b64 s[4:5], s[48:49], 15
	s_lshl_b64 s[6:7], s[68:69], 15
	s_add_u32 s12, s34, s6
	s_addc_u32 s13, s35, s7
	s_and_b64 s[6:7], s[50:51], exec
	s_cselect_b32 s59, s13, s61
	s_cselect_b32 s58, s12, s60
	s_lshl_b64 s[6:7], s[68:69], 7
	s_add_u32 s12, s40, s6
	s_addc_u32 s13, s41, s7
	s_and_b64 s[6:7], s[50:51], exec
	s_cselect_b32 s53, s13, s63
	s_cselect_b32 s52, s12, s62
	s_add_u32 s50, s58, 0x8000
	s_addc_u32 s51, s59, 0
	s_add_u32 s4, s21, s4
	s_addc_u32 s5, s39, s5
	v_lshl_add_u64 v[174:175], s[4:5], 0, v[128:129]
	s_add_i32 m0, s74, 0xc000
	s_nop 0
	global_load_lds_dwordx4 v[174:175], off
	v_lshl_add_u64 v[174:175], s[4:5], 0, v[132:133]
	s_add_i32 m0, s74, 0xe000
	s_nop 0
	global_load_lds_dwordx4 v[174:175], off
	v_add_u32_e32 v170, s10, v177
	v_add_u32_e32 v174, s11, v177
	ds_read_b128 v[158:161], v170
	ds_read_b128 v[162:165], v170 offset:1024
	ds_read_b128 v[166:169], v170 offset:2048
	ds_read_b128 v[170:173], v170 offset:3072
	ds_read_b128 v[180:183], v174
	ds_read_b128 v[190:193], v174 offset:1024
	ds_read_b128 v[194:197], v174 offset:2048
	ds_read_b128 v[198:201], v174 offset:3072
	ds_read_b128 v[202:205], v179
	ds_read_b128 v[206:209], v179 offset:1024
	ds_read_b128 v[210:213], v179 offset:2048
	ds_read_b128 v[214:217], v179 offset:3072
	ds_read_b128 v[218:221], v179 offset:4096
	ds_read_b128 v[222:225], v179 offset:5120
	ds_read_b128 v[226:229], v179 offset:6144
	ds_read_b128 v[230:233], v179 offset:7168
	s_waitcnt vmcnt(8)
	s_waitcnt lgkmcnt(0)
	s_setprio 1
	s_barrier
	v_mfma_f32_16x16x32_bf16 v[124:127], v[158:161], v[202:205], v[124:127]
	v_mfma_f32_16x16x32_bf16 v[120:123], v[166:169], v[202:205], v[120:123]
	v_mfma_f32_16x16x32_bf16 v[116:119], v[158:161], v[210:213], v[116:119]
	v_mfma_f32_16x16x32_bf16 v[112:115], v[166:169], v[210:213], v[112:115]
	v_mfma_f32_16x16x32_bf16 v[108:111], v[158:161], v[218:221], v[108:111]
	v_mfma_f32_16x16x32_bf16 v[104:107], v[166:169], v[218:221], v[104:107]
	v_mfma_f32_16x16x32_bf16 v[100:103], v[158:161], v[226:229], v[100:103]
	v_mfma_f32_16x16x32_bf16 v[96:99], v[166:169], v[226:229], v[96:99]
	v_mfma_f32_16x16x32_bf16 v[124:127], v[162:165], v[206:209], v[124:127]
	v_mfma_f32_16x16x32_bf16 v[120:123], v[170:173], v[206:209], v[120:123]
	v_mfma_f32_16x16x32_bf16 v[116:119], v[162:165], v[214:217], v[116:119]
	v_mfma_f32_16x16x32_bf16 v[112:115], v[170:173], v[214:217], v[112:115]
	v_mfma_f32_16x16x32_bf16 v[108:111], v[162:165], v[222:225], v[108:111]
	v_mfma_f32_16x16x32_bf16 v[104:107], v[170:173], v[222:225], v[104:107]
	v_mfma_f32_16x16x32_bf16 v[100:103], v[162:165], v[230:233], v[100:103]
	v_mfma_f32_16x16x32_bf16 v[96:99], v[170:173], v[230:233], v[96:99]
	s_setprio 0
	s_setprio 1
	v_mfma_f32_16x16x32_bf16 v[92:95], v[180:183], v[202:205], v[92:95]
	v_mfma_f32_16x16x32_bf16 v[88:91], v[194:197], v[202:205], v[88:91]
	v_mfma_f32_16x16x32_bf16 v[84:87], v[180:183], v[210:213], v[84:87]
	v_mfma_f32_16x16x32_bf16 v[80:83], v[194:197], v[210:213], v[80:83]
	v_mfma_f32_16x16x32_bf16 v[76:79], v[180:183], v[218:221], v[76:79]
	v_mfma_f32_16x16x32_bf16 v[72:75], v[194:197], v[218:221], v[72:75]
	v_mfma_f32_16x16x32_bf16 v[68:71], v[180:183], v[226:229], v[68:71]
	v_mfma_f32_16x16x32_bf16 v[64:67], v[194:197], v[226:229], v[64:67]
	v_mfma_f32_16x16x32_bf16 v[92:95], v[190:193], v[206:209], v[92:95]
	v_mfma_f32_16x16x32_bf16 v[88:91], v[198:201], v[206:209], v[88:91]
	v_mfma_f32_16x16x32_bf16 v[84:87], v[190:193], v[214:217], v[84:87]
	v_mfma_f32_16x16x32_bf16 v[80:83], v[198:201], v[214:217], v[80:83]
	v_mfma_f32_16x16x32_bf16 v[76:79], v[190:193], v[222:225], v[76:79]
	v_mfma_f32_16x16x32_bf16 v[72:75], v[198:201], v[222:225], v[72:75]
	v_mfma_f32_16x16x32_bf16 v[68:71], v[190:193], v[230:233], v[68:71]
	v_mfma_f32_16x16x32_bf16 v[64:67], v[198:201], v[230:233], v[64:67]
	s_barrier
	s_setprio 0
	s_add_i32 s4, s10, s77
	v_lshl_add_u64 v[174:175], s[52:53], 0, v[130:131]
	s_mov_b32 m0, s4
	s_nop 0
	global_load_lds_dwordx4 v[174:175], off
	s_add_i32 m0, s4, 0x2000
	s_add_u32 s4, s52, 0x160000
	v_lshl_add_u64 v[234:235], s[52:53], 0, v[134:135]
	s_addc_u32 s5, s53, 0
	s_add_i32 s6, s11, s77
	global_load_lds_dwordx4 v[234:235], off
	v_lshl_add_u64 v[236:237], s[4:5], 0, v[130:131]
	s_mov_b32 m0, s6
	s_nop 0
	global_load_lds_dwordx4 v[236:237], off
	v_lshl_add_u64 v[236:237], s[4:5], 0, v[134:135]
	s_add_i32 m0, s6, 0x2000
	s_nop 0
	global_load_lds_dwordx4 v[236:237], off
	v_lshl_add_u64 v[236:237], s[58:59], 0, v[128:129]
	s_mov_b32 m0, s74
	s_nop 0
	global_load_lds_dwordx4 v[236:237], off
	v_lshl_add_u64 v[236:237], s[58:59], 0, v[132:133]
	s_mov_b32 m0, s96
	s_nop 0
	global_load_lds_dwordx4 v[236:237], off
	ds_read_b128 v[202:205], v179 offset:16384
	ds_read_b128 v[206:209], v179 offset:17408
	ds_read_b128 v[210:213], v179 offset:18432
	ds_read_b128 v[214:217], v179 offset:19456
	ds_read_b128 v[218:221], v179 offset:20480
	ds_read_b128 v[222:225], v179 offset:21504
	ds_read_b128 v[226:229], v179 offset:22528
	ds_read_b128 v[230:233], v179 offset:23552
	s_waitcnt vmcnt(8)
	s_waitcnt lgkmcnt(0)
	s_setprio 1
	s_barrier
; #define PG8_STAGE(bufoff, gbase, voff) do { _Pragma("unroll") for (int _i = 0; _i < 2; ++_i) \
;         __builtin_amdgcn_global_load_lds((const unsigned*)((const char*)(gbase) + (voff)[_i]), (PG8_LAS unsigned*)(lds + (bufoff) + ldsw + _i * 8192), 16, 0, 0); } while (0)
; #define PG8_LDA(dst, b, h) do { _Pragma("unroll") for (int m = 0; m < 4; ++m) _Pragma("unroll") for (int k = 0; k < 2; ++k) dst[m][k] = *(const PG8_LAS bf16x8*)(lds + PG8_SA(b, h) + aoff + m * 2048 + k * 1024); } while (0)
; #define PG8_LDB(dst, b, h) do { _Pragma("unroll") for (int n = 0; n < 2; ++n) _Pragma("unroll") for (int k = 0; k < 2; ++k) dst[n][k] = *(const PG8_LAS bf16x8*)(lds + PG8_SB(b, h) + boff + n * 2048 + k * 1024); } while (0)
; #define PG8_MMA(ai, bj, At, Bt) do { __builtin_amdgcn_s_setprio(1); _Pragma("unroll") for (int m = 0; m < 4; ++m) _Pragma("unroll") for (int n = 0; n < 2; ++n) _Pragma("unroll") for (int k = 0; k < 2; ++k) \
;         acc[ai][bj][m][n] = __builtin_amdgcn_mfma_f32_16x16x32_bf16(Bt[n][k], At[m][k], acc[ai][bj][m][n], 0, 0, 0); __builtin_amdgcn_s_setprio(0); } while (0)
; #define PG8_WAIT_V(n) asm volatile("s_waitcnt vmcnt(" #n ")" ::: "memory")
; #define PG8_WAIT_L(n) asm volatile("s_waitcnt lgkmcnt(" #n ")" ::: "memory")
; #define PG8_BAR __builtin_amdgcn_s_barrier()
; #define PG8_SCHED __builtin_amdgcn_sched_barrier(0)
; template <class Epi, class Sched, bool ALIGN_EPI = false, bool SP2 = false>
; __device__ __forceinline__ void gemm_phase(PG8_LAS unsigned char* lds, const Gemm g, const Sched& S, const Epi& E) {
;     ...
;             PG8_WAIT_V(8); PG8_WAIT_L(0); PG8_BAR; PG8_MMA(1, 0, At, B0); PG8_MMA(1, 1, At, B1); PG8_BAR; PG8_SCHED;
;             PG8_LDB(B0, 1, 0); PG8_LDB(B1, 1, 1); PG8_SCHED; PG8_LDA(At, 1, 0); PG8_STAGE(PG8_SA(0, 1), a2 + hstepA, voffA);
;             PG8_WAIT_V(8); PG8_WAIT_L(0); PG8_BAR; PG8_MMA(0, 0, At, B0); PG8_MMA(0, 1, At, B1); PG8_BAR; PG8_SCHED;
	v_mfma_f32_16x16x32_bf16 v[60:63], v[158:161], v[202:205], v[60:63]
	v_mfma_f32_16x16x32_bf16 v[56:59], v[166:169], v[202:205], v[56:59]
	v_mfma_f32_16x16x32_bf16 v[52:55], v[158:161], v[210:213], v[52:55]
	v_mfma_f32_16x16x32_bf16 v[48:51], v[166:169], v[210:213], v[48:51]
	v_mfma_f32_16x16x32_bf16 v[44:47], v[158:161], v[218:221], v[44:47]
	v_mfma_f32_16x16x32_bf16 v[40:43], v[166:169], v[218:221], v[40:43]
	v_mfma_f32_16x16x32_bf16 v[36:39], v[158:161], v[226:229], v[36:39]
	v_mfma_f32_16x16x32_bf16 v[32:35], v[166:169], v[226:229], v[32:35]
	v_mfma_f32_16x16x32_bf16 v[60:63], v[162:165], v[206:209], v[60:63]
	v_mfma_f32_16x16x32_bf16 v[56:59], v[170:173], v[206:209], v[56:59]
	v_mfma_f32_16x16x32_bf16 v[52:55], v[162:165], v[214:217], v[52:55]
	v_mfma_f32_16x16x32_bf16 v[48:51], v[170:173], v[214:217], v[48:51]
	v_mfma_f32_16x16x32_bf16 v[44:47], v[162:165], v[222:225], v[44:47]
	v_mfma_f32_16x16x32_bf16 v[40:43], v[170:173], v[222:225], v[40:43]
	v_mfma_f32_16x16x32_bf16 v[36:39], v[162:165], v[230:233], v[36:39]
	v_mfma_f32_16x16x32_bf16 v[32:35], v[170:173], v[230:233], v[32:35]
	s_setprio 0
	s_setprio 1
	v_mfma_f32_16x16x32_bf16 v[28:31], v[180:183], v[202:205], v[28:31]
	v_mfma_f32_16x16x32_bf16 v[24:27], v[194:197], v[202:205], v[24:27]
	v_mfma_f32_16x16x32_bf16 v[20:23], v[180:183], v[210:213], v[20:23]
	v_mfma_f32_16x16x32_bf16 v[16:19], v[194:197], v[210:213], v[16:19]
	v_mfma_f32_16x16x32_bf16 v[12:15], v[180:183], v[218:221], v[12:15]
	v_mfma_f32_16x16x32_bf16 v[8:11], v[194:197], v[218:221], v[8:11]
	v_mfma_f32_16x16x32_bf16 v[4:7], v[180:183], v[226:229], v[4:7]
	v_mfma_f32_16x16x32_bf16 v[0:3], v[194:197], v[226:229], v[0:3]
	v_mfma_f32_16x16x32_bf16 v[28:31], v[190:193], v[206:209], v[28:31]
	v_mfma_f32_16x16x32_bf16 v[24:27], v[198:201], v[206:209], v[24:27]
	v_mfma_f32_16x16x32_bf16 v[20:23], v[190:193], v[214:217], v[20:23]
	v_mfma_f32_16x16x32_bf16 v[16:19], v[198:201], v[214:217], v[16:19]
	v_mfma_f32_16x16x32_bf16 v[12:15], v[190:193], v[222:225], v[12:15]
	v_mfma_f32_16x16x32_bf16 v[8:11], v[198:201], v[222:225], v[8:11]
	v_mfma_f32_16x16x32_bf16 v[4:7], v[190:193], v[230:233], v[4:7]
	v_mfma_f32_16x16x32_bf16 v[0:3], v[198:201], v[230:233], v[0:3]
	s_barrier
	s_setprio 0
	s_add_i32 s6, 0, 0x18000
	s_add_i32 s7, 0, 0x1c000
	s_add_u32 s4, s58, 0x4000
	s_addc_u32 s5, s59, 0
	s_mov_b32 m0, s97
	v_lshl_add_u64 v[236:237], s[4:5], 0, v[128:129]
	global_load_lds_dwordx4 v[236:237], off
	v_lshl_add_u64 v[236:237], s[4:5], 0, v[132:133]
	s_mov_b32 m0, s75
	s_nop 0
	global_load_lds_dwordx4 v[236:237], off
	v_add_u32_e32 v170, s6, v177
	v_add_u32_e32 v198, s7, v177
	ds_read_b128 v[158:161], v170
	ds_read_b128 v[162:165], v170 offset:1024
	ds_read_b128 v[166:169], v170 offset:2048
	ds_read_b128 v[170:173], v170 offset:3072
	ds_read_b128 v[180:183], v198
	ds_read_b128 v[190:193], v198 offset:1024
	ds_read_b128 v[194:197], v198 offset:2048
	ds_read_b128 v[198:201], v198 offset:3072
	ds_read_b128 v[202:205], v179 offset:32768
	ds_read_b128 v[206:209], v179 offset:33792
	ds_read_b128 v[210:213], v179 offset:34816
	ds_read_b128 v[214:217], v179 offset:35840
	ds_read_b128 v[218:221], v179 offset:36864
	ds_read_b128 v[222:225], v179 offset:37888
	ds_read_b128 v[226:229], v179 offset:38912
	ds_read_b128 v[230:233], v179 offset:39936
	s_waitcnt vmcnt(8)
	s_waitcnt lgkmcnt(0)
	s_setprio 1
	s_barrier
	v_mfma_f32_16x16x32_bf16 v[124:127], v[158:161], v[202:205], v[124:127]
	v_mfma_f32_16x16x32_bf16 v[120:123], v[166:169], v[202:205], v[120:123]
	v_mfma_f32_16x16x32_bf16 v[116:119], v[158:161], v[210:213], v[116:119]
	v_mfma_f32_16x16x32_bf16 v[112:115], v[166:169], v[210:213], v[112:115]
	v_mfma_f32_16x16x32_bf16 v[108:111], v[158:161], v[218:221], v[108:111]
	v_mfma_f32_16x16x32_bf16 v[104:107], v[166:169], v[218:221], v[104:107]
	v_mfma_f32_16x16x32_bf16 v[100:103], v[158:161], v[226:229], v[100:103]
	v_mfma_f32_16x16x32_bf16 v[96:99], v[166:169], v[226:229], v[96:99]
	v_mfma_f32_16x16x32_bf16 v[124:127], v[162:165], v[206:209], v[124:127]
	v_mfma_f32_16x16x32_bf16 v[120:123], v[170:173], v[206:209], v[120:123]
	v_mfma_f32_16x16x32_bf16 v[116:119], v[162:165], v[214:217], v[116:119]
	v_mfma_f32_16x16x32_bf16 v[112:115], v[170:173], v[214:217], v[112:115]
	v_mfma_f32_16x16x32_bf16 v[108:111], v[162:165], v[222:225], v[108:111]
	v_mfma_f32_16x16x32_bf16 v[104:107], v[170:173], v[222:225], v[104:107]
	v_mfma_f32_16x16x32_bf16 v[100:103], v[162:165], v[230:233], v[100:103]
	v_mfma_f32_16x16x32_bf16 v[96:99], v[170:173], v[230:233], v[96:99]
	s_setprio 0
	s_setprio 1
	v_mfma_f32_16x16x32_bf16 v[92:95], v[180:183], v[202:205], v[92:95]
	v_mfma_f32_16x16x32_bf16 v[88:91], v[194:197], v[202:205], v[88:91]
	v_mfma_f32_16x16x32_bf16 v[84:87], v[180:183], v[210:213], v[84:87]
	v_mfma_f32_16x16x32_bf16 v[80:83], v[194:197], v[210:213], v[80:83]
	v_mfma_f32_16x16x32_bf16 v[76:79], v[180:183], v[218:221], v[76:79]
	v_mfma_f32_16x16x32_bf16 v[72:75], v[194:197], v[218:221], v[72:75]
	v_mfma_f32_16x16x32_bf16 v[68:71], v[180:183], v[226:229], v[68:71]
	v_mfma_f32_16x16x32_bf16 v[64:67], v[194:197], v[226:229], v[64:67]
	v_mfma_f32_16x16x32_bf16 v[92:95], v[190:193], v[206:209], v[92:95]
	v_mfma_f32_16x16x32_bf16 v[88:91], v[198:201], v[206:209], v[88:91]
	v_mfma_f32_16x16x32_bf16 v[84:87], v[190:193], v[214:217], v[84:87]
	v_mfma_f32_16x16x32_bf16 v[80:83], v[198:201], v[214:217], v[80:83]
	v_mfma_f32_16x16x32_bf16 v[76:79], v[190:193], v[222:225], v[76:79]
	v_mfma_f32_16x16x32_bf16 v[72:75], v[198:201], v[222:225], v[72:75]
	v_mfma_f32_16x16x32_bf16 v[68:71], v[190:193], v[230:233], v[68:71]
	v_mfma_f32_16x16x32_bf16 v[64:67], v[198:201], v[230:233], v[64:67]
	s_barrier
; #define PG8_STAGE(bufoff, gbase, voff) do { _Pragma("unroll") for (int _i = 0; _i < 2; ++_i) \
;         __builtin_amdgcn_global_load_lds((const unsigned*)((const char*)(gbase) + (voff)[_i]), (PG8_LAS unsigned*)(lds + (bufoff) + ldsw + _i * 8192), 16, 0, 0); } while (0)
; #define PG8_LDA(dst, b, h) do { _Pragma("unroll") for (int m = 0; m < 4; ++m) _Pragma("unroll") for (int k = 0; k < 2; ++k) dst[m][k] = *(const PG8_LAS bf16x8*)(lds + PG8_SA(b, h) + aoff + m * 2048 + k * 1024); } while (0)
; #define PG8_MMA(ai, bj, At, Bt) do { __builtin_amdgcn_s_setprio(1); _Pragma("unroll") for (int m = 0; m < 4; ++m) _Pragma("unroll") for (int n = 0; n < 2; ++n) _Pragma("unroll") for (int k = 0; k < 2; ++k) \
;         acc[ai][bj][m][n] = __builtin_amdgcn_mfma_f32_16x16x32_bf16(Bt[n][k], At[m][k], acc[ai][bj][m][n], 0, 0, 0); __builtin_amdgcn_s_setprio(0); } while (0)
; #define PG8_WAIT_V(n) asm volatile("s_waitcnt vmcnt(" #n ")" ::: "memory")
; #define PG8_WAIT_L(n) asm volatile("s_waitcnt lgkmcnt(" #n ")" ::: "memory")
; #define PG8_BAR __builtin_amdgcn_s_barrier()
; #define PG8_SCHED __builtin_amdgcn_sched_barrier(0)
; template <class Epi, class Sched, bool ALIGN_EPI = false, bool SP2 = false>
; __device__ __forceinline__ void gemm_phase(PG8_LAS unsigned char* lds, const Gemm g, const Sched& S, const Epi& E) {
;     ...
;         for (int t = 0; t < nt; t += 2) {
;     ...
;             PG8_LDA(At, 1, 1); PG8_STAGE(PG8_SB(1, 0), b3, voffB); PG8_STAGE(PG8_SB(1, 1), b3 + hstepB, voffB); PG8_STAGE(PG8_SA(1, 0), a3, voffA);
;             PG8_WAIT_V(8); PG8_WAIT_L(0); PG8_BAR; PG8_MMA(1, 0, At, B0); PG8_MMA(1, 1, At, B1); PG8_BAR; PG8_SCHED;
	s_setprio 0
	s_add_i32 s4, s6, s77
	v_lshl_add_u64 v[174:175], v[174:175], 0, s[64:65]
	s_mov_b32 m0, s4
	s_nop 0
	global_load_lds_dwordx4 v[174:175], off
	s_add_i32 m0, s4, 0x2000
	s_add_u32 s4, s52, 0x160080
	v_lshl_add_u64 v[174:175], v[234:235], 0, s[64:65]
	s_addc_u32 s5, s53, 0
	s_add_i32 s6, s7, s77
	global_load_lds_dwordx4 v[174:175], off
	v_lshl_add_u64 v[174:175], s[4:5], 0, v[130:131]
	s_mov_b32 m0, s6
	s_nop 0
	global_load_lds_dwordx4 v[174:175], off
	v_lshl_add_u64 v[174:175], s[4:5], 0, v[134:135]
	s_add_i32 m0, s6, 0x2000
	s_nop 0
	global_load_lds_dwordx4 v[174:175], off
	v_lshl_add_u64 v[174:175], s[50:51], 0, v[128:129]
	s_mov_b32 m0, s43
	s_nop 0
	global_load_lds_dwordx4 v[174:175], off
	v_lshl_add_u64 v[174:175], s[50:51], 0, v[132:133]
	s_mov_b32 m0, s56
	s_nop 0
	global_load_lds_dwordx4 v[174:175], off
	ds_read_b128 v[202:205], v179 offset:49152
	ds_read_b128 v[206:209], v179 offset:50176
	ds_read_b128 v[210:213], v179 offset:51200
	ds_read_b128 v[214:217], v179 offset:52224
	ds_read_b128 v[218:221], v179 offset:53248
	ds_read_b128 v[222:225], v179 offset:54272
	ds_read_b128 v[226:229], v179 offset:55296
	ds_read_b128 v[230:233], v179 offset:56320
	s_waitcnt vmcnt(8)
	s_waitcnt lgkmcnt(0)
	s_setprio 1
	s_barrier
	v_mfma_f32_16x16x32_bf16 v[60:63], v[158:161], v[202:205], v[60:63]
	v_mfma_f32_16x16x32_bf16 v[56:59], v[166:169], v[202:205], v[56:59]
	v_mfma_f32_16x16x32_bf16 v[52:55], v[158:161], v[210:213], v[52:55]
	v_mfma_f32_16x16x32_bf16 v[48:51], v[166:169], v[210:213], v[48:51]
	v_mfma_f32_16x16x32_bf16 v[44:47], v[158:161], v[218:221], v[44:47]
	v_mfma_f32_16x16x32_bf16 v[40:43], v[166:169], v[218:221], v[40:43]
	v_mfma_f32_16x16x32_bf16 v[36:39], v[158:161], v[226:229], v[36:39]
	v_mfma_f32_16x16x32_bf16 v[32:35], v[166:169], v[226:229], v[32:35]
	v_mfma_f32_16x16x32_bf16 v[60:63], v[162:165], v[206:209], v[60:63]
	v_mfma_f32_16x16x32_bf16 v[56:59], v[170:173], v[206:209], v[56:59]
	v_mfma_f32_16x16x32_bf16 v[52:55], v[162:165], v[214:217], v[52:55]
	v_mfma_f32_16x16x32_bf16 v[48:51], v[170:173], v[214:217], v[48:51]
	v_mfma_f32_16x16x32_bf16 v[44:47], v[162:165], v[222:225], v[44:47]
	v_mfma_f32_16x16x32_bf16 v[40:43], v[170:173], v[222:225], v[40:43]
	v_mfma_f32_16x16x32_bf16 v[36:39], v[162:165], v[230:233], v[36:39]
	v_mfma_f32_16x16x32_bf16 v[32:35], v[170:173], v[230:233], v[32:35]
	s_setprio 0
	s_setprio 1
	v_mfma_f32_16x16x32_bf16 v[28:31], v[180:183], v[202:205], v[28:31]
	v_mfma_f32_16x16x32_bf16 v[24:27], v[194:197], v[202:205], v[24:27]
	v_mfma_f32_16x16x32_bf16 v[20:23], v[180:183], v[210:213], v[20:23]
	v_mfma_f32_16x16x32_bf16 v[16:19], v[194:197], v[210:213], v[16:19]
	v_mfma_f32_16x16x32_bf16 v[12:15], v[180:183], v[218:221], v[12:15]
	v_mfma_f32_16x16x32_bf16 v[8:11], v[194:197], v[218:221], v[8:11]
	v_mfma_f32_16x16x32_bf16 v[4:7], v[180:183], v[226:229], v[4:7]
	v_mfma_f32_16x16x32_bf16 v[0:3], v[194:197], v[226:229], v[0:3]
	v_mfma_f32_16x16x32_bf16 v[28:31], v[190:193], v[206:209], v[28:31]
	v_mfma_f32_16x16x32_bf16 v[24:27], v[198:201], v[206:209], v[24:27]
	v_mfma_f32_16x16x32_bf16 v[20:23], v[190:193], v[214:217], v[20:23]
	v_mfma_f32_16x16x32_bf16 v[16:19], v[198:201], v[214:217], v[16:19]
	v_mfma_f32_16x16x32_bf16 v[12:15], v[190:193], v[222:225], v[12:15]
	v_mfma_f32_16x16x32_bf16 v[8:11], v[198:201], v[222:225], v[8:11]
	v_mfma_f32_16x16x32_bf16 v[4:7], v[190:193], v[230:233], v[4:7]
	v_mfma_f32_16x16x32_bf16 v[0:3], v[198:201], v[230:233], v[0:3]
	s_barrier
	s_setprio 0
	s_cmp_ge_i32 s68, s57
	s_cbranch_scc1 .LBB0_1416

; #define PG8_STAGE(bufoff, gbase, voff) do { _Pragma("unroll") for (int _i = 0; _i < 2; ++_i) \
;         __builtin_amdgcn_global_load_lds((const unsigned*)((const char*)(gbase) + (voff)[_i]), (PG8_LAS unsigned*)(lds + (bufoff) + ldsw + _i * 8192), 16, 0, 0); } while (0)
; #define PG8_LDA(dst, b, h) do { _Pragma("unroll") for (int m = 0; m < 4; ++m) _Pragma("unroll") for (int k = 0; k < 2; ++k) dst[m][k] = *(const PG8_LAS bf16x8*)(lds + PG8_SA(b, h) + aoff + m * 2048 + k * 1024); } while (0)
; #define PG8_LDB(dst, b, h) do { _Pragma("unroll") for (int n = 0; n < 2; ++n) _Pragma("unroll") for (int k = 0; k < 2; ++k) dst[n][k] = *(const PG8_LAS bf16x8*)(lds + PG8_SB(b, h) + boff + n * 2048 + k * 1024); } while (0)
; #define PG8_MMA(ai, bj, At, Bt) do { __builtin_amdgcn_s_setprio(1); _Pragma("unroll") for (int m = 0; m < 4; ++m) _Pragma("unroll") for (int n = 0; n < 2; ++n) _Pragma("unroll") for (int k = 0; k < 2; ++k) \
;         acc[ai][bj][m][n] = __builtin_amdgcn_mfma_f32_16x16x32_bf16(Bt[n][k], At[m][k], acc[ai][bj][m][n], 0, 0, 0); __builtin_amdgcn_s_setprio(0); } while (0)
; #define PG8_WAIT_V(n) asm volatile("s_waitcnt vmcnt(" #n ")" ::: "memory")
; #define PG8_BAR __builtin_amdgcn_s_barrier()
; template <class Epi, class Sched, bool ALIGN_EPI = false, bool SP2 = false>
; __device__ __forceinline__ void gemm_phase(PG8_LAS unsigned char* lds, const Gemm g, const Sched& S, const Epi& E) {
;     ...
;         for (int t = 0; t < nt; t += 2) {
;             const bool last = (t == nt - 2);
;             const char* a1 = cA + (size_t)(t + 1) * kstA;
;             const char* a2 = last ? nA : cA + (size_t)(t + 2) * kstA; const char* b2 = last ? nB : cB + (size_t)(t + 2) * kstep;
;             const char* a3 = a2 + kstA; const char* b3 = b2 + kstep;
;             if (last && has_next) S.a_ready(nxt);
;             if constexpr (SP2) {
;             PG8_LDB(B0, 0, 0); PG8_LDB(B1, 0, 1); PG8_SCHED; PG8_LDA(At, 0, 0); PG8_STAGE(PG8_SA(1, 1), a1 + hstepA, voffA);
;             PG8_WAIT_V(8); PG8_WAIT_L(0); PG8_BAR; PG8_MMA(0, 0, At, B0); PG8_MMA(0, 1, At, B1); PG8_BAR; PG8_SCHED;
;             PG8_LDA(At, 0, 1); PG8_STAGE(PG8_SB(0, 0), b2, voffB); PG8_STAGE(PG8_SB(0, 1), b2 + hstepB, voffB); PG8_STAGE(PG8_SA(0, 0), a2, voffA);
;             PG8_WAIT_V(8); PG8_WAIT_L(0); PG8_BAR; PG8_MMA(1, 0, At, B0); PG8_MMA(1, 1, At, B1); PG8_BAR; PG8_SCHED;
.LBB0_1657:
	s_add_u32 s52, s50, 0xfff80080
	s_addc_u32 s53, s51, -1
	s_cmp_eq_u32 s63, 28
	s_cselect_b32 s59, s4, s53
	s_cselect_b32 s58, s5, s52
	s_cselect_b32 s53, s12, s41
	s_cselect_b32 s52, s13, s39
	v_lshl_add_u64 v[226:227], s[50:51], 0, v[142:143]
	s_add_i32 m0, s7, 0xc000
	s_nop 0
	global_load_lds_dwordx4 v[226:227], off
	v_lshl_add_u64 v[226:227], s[50:51], 0, v[144:145]
	s_add_i32 m0, s7, 0xe000
	s_nop 0
	global_load_lds_dwordx4 v[226:227], off
	ds_read_b128 v[156:159], v152
	ds_read_b128 v[160:163], v152 offset:1024
	ds_read_b128 v[164:167], v152 offset:2048
	ds_read_b128 v[168:171], v152 offset:3072
	ds_read_b128 v[172:175], v153
	ds_read_b128 v[176:179], v153 offset:1024
	ds_read_b128 v[180:183], v153 offset:2048
	ds_read_b128 v[190:193], v153 offset:3072
	ds_read_b128 v[194:197], v154
	ds_read_b128 v[198:201], v154 offset:1024
	ds_read_b128 v[202:205], v154 offset:2048
	ds_read_b128 v[206:209], v154 offset:3072
	ds_read_b128 v[210:213], v154 offset:4096
	ds_read_b128 v[214:217], v154 offset:5120
	ds_read_b128 v[218:221], v154 offset:6144
	ds_read_b128 v[222:225], v154 offset:7168
	s_waitcnt vmcnt(8)
	s_waitcnt lgkmcnt(0)
	s_setprio 1
	s_barrier
	v_mfma_f32_16x16x32_bf16 v[124:127], v[156:159], v[194:197], v[124:127]
	v_mfma_f32_16x16x32_bf16 v[120:123], v[164:167], v[194:197], v[120:123]
	v_mfma_f32_16x16x32_bf16 v[108:111], v[156:159], v[202:205], v[108:111]
	v_mfma_f32_16x16x32_bf16 v[104:107], v[164:167], v[202:205], v[104:107]
	v_mfma_f32_16x16x32_bf16 v[92:95], v[156:159], v[210:213], v[92:95]
	v_mfma_f32_16x16x32_bf16 v[88:91], v[164:167], v[210:213], v[88:91]
	v_mfma_f32_16x16x32_bf16 v[76:79], v[156:159], v[218:221], v[76:79]
	v_mfma_f32_16x16x32_bf16 v[72:75], v[164:167], v[218:221], v[72:75]
	v_mfma_f32_16x16x32_bf16 v[124:127], v[160:163], v[198:201], v[124:127]
	v_mfma_f32_16x16x32_bf16 v[120:123], v[168:171], v[198:201], v[120:123]
	v_mfma_f32_16x16x32_bf16 v[108:111], v[160:163], v[206:209], v[108:111]
	v_mfma_f32_16x16x32_bf16 v[104:107], v[168:171], v[206:209], v[104:107]
	v_mfma_f32_16x16x32_bf16 v[92:95], v[160:163], v[214:217], v[92:95]
	v_mfma_f32_16x16x32_bf16 v[88:91], v[168:171], v[214:217], v[88:91]
	v_mfma_f32_16x16x32_bf16 v[76:79], v[160:163], v[222:225], v[76:79]
	v_mfma_f32_16x16x32_bf16 v[72:75], v[168:171], v[222:225], v[72:75]
	s_setprio 0
	s_setprio 1
	v_mfma_f32_16x16x32_bf16 v[116:119], v[172:175], v[194:197], v[116:119]
	v_mfma_f32_16x16x32_bf16 v[112:115], v[180:183], v[194:197], v[112:115]
	v_mfma_f32_16x16x32_bf16 v[100:103], v[172:175], v[202:205], v[100:103]
	v_mfma_f32_16x16x32_bf16 v[96:99], v[180:183], v[202:205], v[96:99]
	v_mfma_f32_16x16x32_bf16 v[84:87], v[172:175], v[210:213], v[84:87]
	v_mfma_f32_16x16x32_bf16 v[80:83], v[180:183], v[210:213], v[80:83]
	v_mfma_f32_16x16x32_bf16 v[68:71], v[172:175], v[218:221], v[68:71]
	v_mfma_f32_16x16x32_bf16 v[64:67], v[180:183], v[218:221], v[64:67]
	v_mfma_f32_16x16x32_bf16 v[116:119], v[176:179], v[198:201], v[116:119]
	v_mfma_f32_16x16x32_bf16 v[112:115], v[190:193], v[198:201], v[112:115]
	v_mfma_f32_16x16x32_bf16 v[100:103], v[176:179], v[206:209], v[100:103]
	v_mfma_f32_16x16x32_bf16 v[96:99], v[190:193], v[206:209], v[96:99]
	v_mfma_f32_16x16x32_bf16 v[84:87], v[176:179], v[214:217], v[84:87]
	v_mfma_f32_16x16x32_bf16 v[80:83], v[190:193], v[214:217], v[80:83]
	v_mfma_f32_16x16x32_bf16 v[68:71], v[176:179], v[222:225], v[68:71]
	v_mfma_f32_16x16x32_bf16 v[64:67], v[190:193], v[222:225], v[64:67]
	s_barrier
	s_setprio 0
	s_add_i32 s64, s56, s6
	v_lshl_add_u64 v[226:227], s[52:53], 0, v[130:131]
	s_mov_b32 m0, s64
	s_nop 0
	global_load_lds_dwordx4 v[226:227], off
	s_add_i32 m0, s64, 0x2000
	s_add_u32 s64, s52, 0x80000
	v_lshl_add_u64 v[228:229], s[52:53], 0, v[134:135]
	s_addc_u32 s65, s53, 0
	s_add_i32 s66, s57, s6
	global_load_lds_dwordx4 v[228:229], off
	v_lshl_add_u64 v[230:231], s[64:65], 0, v[130:131]
	s_mov_b32 m0, s66
	v_lshl_add_u64 v[232:233], s[58:59], 0, v[132:133]
	global_load_lds_dwordx4 v[230:231], off
	v_lshl_add_u64 v[230:231], s[64:65], 0, v[134:135]
	s_add_i32 m0, s66, 0x2000
	s_nop 0
	global_load_lds_dwordx4 v[230:231], off
	v_lshl_add_u64 v[230:231], s[58:59], 0, v[128:129]
	s_mov_b32 m0, s7
	s_nop 0
	global_load_lds_dwordx4 v[230:231], off
	s_mov_b32 m0, s8
	s_nop 0
	global_load_lds_dwordx4 v[232:233], off
	ds_read_b128 v[194:197], v154 offset:16384
	ds_read_b128 v[198:201], v154 offset:17408
	ds_read_b128 v[202:205], v154 offset:18432
	ds_read_b128 v[206:209], v154 offset:19456
	ds_read_b128 v[210:213], v154 offset:20480
	ds_read_b128 v[214:217], v154 offset:21504
	ds_read_b128 v[218:221], v154 offset:22528
	ds_read_b128 v[222:225], v154 offset:23552
	s_waitcnt vmcnt(8)
	s_waitcnt lgkmcnt(0)
	s_setprio 1
	s_barrier
; #define PG8_STAGE(bufoff, gbase, voff) do { _Pragma("unroll") for (int _i = 0; _i < 2; ++_i) \
;         __builtin_amdgcn_global_load_lds((const unsigned*)((const char*)(gbase) + (voff)[_i]), (PG8_LAS unsigned*)(lds + (bufoff) + ldsw + _i * 8192), 16, 0, 0); } while (0)
; #define PG8_LDA(dst, b, h) do { _Pragma("unroll") for (int m = 0; m < 4; ++m) _Pragma("unroll") for (int k = 0; k < 2; ++k) dst[m][k] = *(const PG8_LAS bf16x8*)(lds + PG8_SA(b, h) + aoff + m * 2048 + k * 1024); } while (0)
; #define PG8_LDB(dst, b, h) do { _Pragma("unroll") for (int n = 0; n < 2; ++n) _Pragma("unroll") for (int k = 0; k < 2; ++k) dst[n][k] = *(const PG8_LAS bf16x8*)(lds + PG8_SB(b, h) + boff + n * 2048 + k * 1024); } while (0)
; #define PG8_MMA(ai, bj, At, Bt) do { __builtin_amdgcn_s_setprio(1); _Pragma("unroll") for (int m = 0; m < 4; ++m) _Pragma("unroll") for (int n = 0; n < 2; ++n) _Pragma("unroll") for (int k = 0; k < 2; ++k) \
;         acc[ai][bj][m][n] = __builtin_amdgcn_mfma_f32_16x16x32_bf16(Bt[n][k], At[m][k], acc[ai][bj][m][n], 0, 0, 0); __builtin_amdgcn_s_setprio(0); } while (0)
; #define PG8_WAIT_V(n) asm volatile("s_waitcnt vmcnt(" #n ")" ::: "memory")
; #define PG8_WAIT_L(n) asm volatile("s_waitcnt lgkmcnt(" #n ")" ::: "memory")
; #define PG8_BAR __builtin_amdgcn_s_barrier()
; #define PG8_SCHED __builtin_amdgcn_sched_barrier(0)
; template <class Epi, class Sched, bool ALIGN_EPI = false, bool SP2 = false>
; __device__ __forceinline__ void gemm_phase(PG8_LAS unsigned char* lds, const Gemm g, const Sched& S, const Epi& E) {
;     ...
;             PG8_WAIT_V(8); PG8_WAIT_L(0); PG8_BAR; PG8_MMA(1, 0, At, B0); PG8_MMA(1, 1, At, B1); PG8_BAR; PG8_SCHED;
;             PG8_LDB(B0, 1, 0); PG8_LDB(B1, 1, 1); PG8_SCHED; PG8_LDA(At, 1, 0); PG8_STAGE(PG8_SA(0, 1), a2 + hstepA, voffA);
;             PG8_WAIT_V(8); PG8_WAIT_L(0); PG8_BAR; PG8_MMA(0, 0, At, B0); PG8_MMA(0, 1, At, B1); PG8_BAR; PG8_SCHED;
	v_mfma_f32_16x16x32_bf16 v[60:63], v[156:159], v[194:197], v[60:63]
	v_mfma_f32_16x16x32_bf16 v[56:59], v[164:167], v[194:197], v[56:59]
	v_mfma_f32_16x16x32_bf16 v[44:47], v[156:159], v[202:205], v[44:47]
	v_mfma_f32_16x16x32_bf16 v[40:43], v[164:167], v[202:205], v[40:43]
	v_mfma_f32_16x16x32_bf16 v[28:31], v[156:159], v[210:213], v[28:31]
	v_mfma_f32_16x16x32_bf16 v[24:27], v[164:167], v[210:213], v[24:27]
	v_mfma_f32_16x16x32_bf16 v[12:15], v[156:159], v[218:221], v[12:15]
	v_mfma_f32_16x16x32_bf16 v[8:11], v[164:167], v[218:221], v[8:11]
	v_mfma_f32_16x16x32_bf16 v[60:63], v[160:163], v[198:201], v[60:63]
	v_mfma_f32_16x16x32_bf16 v[56:59], v[168:171], v[198:201], v[56:59]
	v_mfma_f32_16x16x32_bf16 v[44:47], v[160:163], v[206:209], v[44:47]
	v_mfma_f32_16x16x32_bf16 v[40:43], v[168:171], v[206:209], v[40:43]
	v_mfma_f32_16x16x32_bf16 v[28:31], v[160:163], v[214:217], v[28:31]
	v_mfma_f32_16x16x32_bf16 v[24:27], v[168:171], v[214:217], v[24:27]
	v_mfma_f32_16x16x32_bf16 v[12:15], v[160:163], v[222:225], v[12:15]
	v_mfma_f32_16x16x32_bf16 v[8:11], v[168:171], v[222:225], v[8:11]
	s_setprio 0
	s_setprio 1
	v_mfma_f32_16x16x32_bf16 v[52:55], v[172:175], v[194:197], v[52:55]
	v_mfma_f32_16x16x32_bf16 v[48:51], v[180:183], v[194:197], v[48:51]
	v_mfma_f32_16x16x32_bf16 v[36:39], v[172:175], v[202:205], v[36:39]
	v_mfma_f32_16x16x32_bf16 v[32:35], v[180:183], v[202:205], v[32:35]
	v_mfma_f32_16x16x32_bf16 v[20:23], v[172:175], v[210:213], v[20:23]
	v_mfma_f32_16x16x32_bf16 v[16:19], v[180:183], v[210:213], v[16:19]
	v_mfma_f32_16x16x32_bf16 v[4:7], v[172:175], v[218:221], v[4:7]
	v_mfma_f32_16x16x32_bf16 v[0:3], v[180:183], v[218:221], v[0:3]
	v_mfma_f32_16x16x32_bf16 v[52:55], v[176:179], v[198:201], v[52:55]
	v_mfma_f32_16x16x32_bf16 v[48:51], v[190:193], v[198:201], v[48:51]
	v_mfma_f32_16x16x32_bf16 v[36:39], v[176:179], v[206:209], v[36:39]
	v_mfma_f32_16x16x32_bf16 v[32:35], v[190:193], v[206:209], v[32:35]
	v_mfma_f32_16x16x32_bf16 v[20:23], v[176:179], v[214:217], v[20:23]
	v_mfma_f32_16x16x32_bf16 v[16:19], v[190:193], v[214:217], v[16:19]
	v_mfma_f32_16x16x32_bf16 v[4:7], v[176:179], v[222:225], v[4:7]
	v_mfma_f32_16x16x32_bf16 v[0:3], v[190:193], v[222:225], v[0:3]
	s_barrier
	s_setprio 0
	s_add_i32 s64, 0, 0x18000
	s_add_i32 s65, 0, 0x1c000
	s_add_u32 s58, s58, 0x80000
	s_addc_u32 s59, s59, 0
	s_mov_b32 m0, s9
	v_lshl_add_u64 v[234:235], s[58:59], 0, v[128:129]
	global_load_lds_dwordx4 v[234:235], off
	v_lshl_add_u64 v[234:235], s[58:59], 0, v[132:133]
	s_mov_b32 m0, s11
	s_nop 0
	global_load_lds_dwordx4 v[234:235], off
	v_add_u32_e32 v155, s64, v150
	ds_read_b128 v[156:159], v155
	ds_read_b128 v[160:163], v155 offset:1024
	ds_read_b128 v[164:167], v155 offset:2048
	ds_read_b128 v[168:171], v155 offset:3072
	v_add_u32_e32 v155, s65, v150
	ds_read_b128 v[172:175], v155
	ds_read_b128 v[176:179], v155 offset:1024
	ds_read_b128 v[180:183], v155 offset:2048
	ds_read_b128 v[190:193], v155 offset:3072
	ds_read_b128 v[194:197], v154 offset:32768
	ds_read_b128 v[198:201], v154 offset:33792
	ds_read_b128 v[202:205], v154 offset:34816
	ds_read_b128 v[206:209], v154 offset:35840
	ds_read_b128 v[210:213], v154 offset:36864
	ds_read_b128 v[214:217], v154 offset:37888
	ds_read_b128 v[218:221], v154 offset:38912
	ds_read_b128 v[222:225], v154 offset:39936
	s_waitcnt vmcnt(8)
	s_waitcnt lgkmcnt(0)
	s_setprio 1
	s_barrier
	v_mfma_f32_16x16x32_bf16 v[124:127], v[156:159], v[194:197], v[124:127]
	v_mfma_f32_16x16x32_bf16 v[120:123], v[164:167], v[194:197], v[120:123]
	v_mfma_f32_16x16x32_bf16 v[108:111], v[156:159], v[202:205], v[108:111]
	v_mfma_f32_16x16x32_bf16 v[104:107], v[164:167], v[202:205], v[104:107]
	v_mfma_f32_16x16x32_bf16 v[92:95], v[156:159], v[210:213], v[92:95]
	v_mfma_f32_16x16x32_bf16 v[88:91], v[164:167], v[210:213], v[88:91]
	v_mfma_f32_16x16x32_bf16 v[76:79], v[156:159], v[218:221], v[76:79]
	v_mfma_f32_16x16x32_bf16 v[72:75], v[164:167], v[218:221], v[72:75]
	v_mfma_f32_16x16x32_bf16 v[124:127], v[160:163], v[198:201], v[124:127]
	v_mfma_f32_16x16x32_bf16 v[120:123], v[168:171], v[198:201], v[120:123]
	v_mfma_f32_16x16x32_bf16 v[108:111], v[160:163], v[206:209], v[108:111]
	v_mfma_f32_16x16x32_bf16 v[104:107], v[168:171], v[206:209], v[104:107]
	v_mfma_f32_16x16x32_bf16 v[92:95], v[160:163], v[214:217], v[92:95]
	v_mfma_f32_16x16x32_bf16 v[88:91], v[168:171], v[214:217], v[88:91]
	v_mfma_f32_16x16x32_bf16 v[76:79], v[160:163], v[222:225], v[76:79]
	v_mfma_f32_16x16x32_bf16 v[72:75], v[168:171], v[222:225], v[72:75]
	s_setprio 0
	s_setprio 1
	v_mfma_f32_16x16x32_bf16 v[116:119], v[172:175], v[194:197], v[116:119]
	v_mfma_f32_16x16x32_bf16 v[112:115], v[180:183], v[194:197], v[112:115]
	v_mfma_f32_16x16x32_bf16 v[100:103], v[172:175], v[202:205], v[100:103]
	v_mfma_f32_16x16x32_bf16 v[96:99], v[180:183], v[202:205], v[96:99]
	v_mfma_f32_16x16x32_bf16 v[84:87], v[172:175], v[210:213], v[84:87]
	v_mfma_f32_16x16x32_bf16 v[80:83], v[180:183], v[210:213], v[80:83]
	v_mfma_f32_16x16x32_bf16 v[68:71], v[172:175], v[218:221], v[68:71]
	v_mfma_f32_16x16x32_bf16 v[64:67], v[180:183], v[218:221], v[64:67]
	v_mfma_f32_16x16x32_bf16 v[116:119], v[176:179], v[198:201], v[116:119]
	v_mfma_f32_16x16x32_bf16 v[112:115], v[190:193], v[198:201], v[112:115]
	v_mfma_f32_16x16x32_bf16 v[100:103], v[176:179], v[206:209], v[100:103]
	v_mfma_f32_16x16x32_bf16 v[96:99], v[190:193], v[206:209], v[96:99]
	v_mfma_f32_16x16x32_bf16 v[84:87], v[176:179], v[214:217], v[84:87]
	v_mfma_f32_16x16x32_bf16 v[80:83], v[190:193], v[214:217], v[80:83]
	v_mfma_f32_16x16x32_bf16 v[68:71], v[176:179], v[222:225], v[68:71]
	v_mfma_f32_16x16x32_bf16 v[64:67], v[190:193], v[222:225], v[64:67]
	s_barrier
; #define PG8_STAGE(bufoff, gbase, voff) do { _Pragma("unroll") for (int _i = 0; _i < 2; ++_i) \
;         __builtin_amdgcn_global_load_lds((const unsigned*)((const char*)(gbase) + (voff)[_i]), (PG8_LAS unsigned*)(lds + (bufoff) + ldsw + _i * 8192), 16, 0, 0); } while (0)
; #define PG8_LDA(dst, b, h) do { _Pragma("unroll") for (int m = 0; m < 4; ++m) _Pragma("unroll") for (int k = 0; k < 2; ++k) dst[m][k] = *(const PG8_LAS bf16x8*)(lds + PG8_SA(b, h) + aoff + m * 2048 + k * 1024); } while (0)
; #define PG8_MMA(ai, bj, At, Bt) do { __builtin_amdgcn_s_setprio(1); _Pragma("unroll") for (int m = 0; m < 4; ++m) _Pragma("unroll") for (int n = 0; n < 2; ++n) _Pragma("unroll") for (int k = 0; k < 2; ++k) \
;         acc[ai][bj][m][n] = __builtin_amdgcn_mfma_f32_16x16x32_bf16(Bt[n][k], At[m][k], acc[ai][bj][m][n], 0, 0, 0); __builtin_amdgcn_s_setprio(0); } while (0)
; #define PG8_WAIT_V(n) asm volatile("s_waitcnt vmcnt(" #n ")" ::: "memory")
; #define PG8_WAIT_L(n) asm volatile("s_waitcnt lgkmcnt(" #n ")" ::: "memory")
; #define PG8_BAR __builtin_amdgcn_s_barrier()
; #define PG8_SCHED __builtin_amdgcn_sched_barrier(0)
; template <class Epi, class Sched, bool ALIGN_EPI = false, bool SP2 = false>
; __device__ __forceinline__ void gemm_phase(PG8_LAS unsigned char* lds, const Gemm g, const Sched& S, const Epi& E) {
;     ...
;         for (int t = 0; t < nt; t += 2) {
;             const bool last = (t == nt - 2);
;     ...
;             PG8_LDA(At, 1, 1); PG8_STAGE(PG8_SB(1, 0), b3, voffB); PG8_STAGE(PG8_SB(1, 1), b3 + hstepB, voffB); PG8_STAGE(PG8_SA(1, 0), a3, voffA);
;             PG8_WAIT_V(8); PG8_WAIT_L(0); PG8_BAR; PG8_MMA(1, 0, At, B0); PG8_MMA(1, 1, At, B1); PG8_BAR; PG8_SCHED;
	s_setprio 0
	s_add_i32 s58, s64, s6
	v_lshl_add_u64 v[226:227], v[226:227], 0, s[20:21]
	s_mov_b32 m0, s58
	s_nop 0
	global_load_lds_dwordx4 v[226:227], off
	s_add_i32 m0, s58, 0x2000
	s_add_u32 s52, s52, 0x80080
	v_lshl_add_u64 v[226:227], v[228:229], 0, s[20:21]
	s_addc_u32 s53, s53, 0
	s_add_i32 s58, s65, s6
	global_load_lds_dwordx4 v[226:227], off
	v_lshl_add_u64 v[226:227], s[52:53], 0, v[130:131]
	s_mov_b32 m0, s58
	s_nop 0
	global_load_lds_dwordx4 v[226:227], off
	v_lshl_add_u64 v[226:227], s[52:53], 0, v[134:135]
	s_add_i32 m0, s58, 0x2000
	s_nop 0
	global_load_lds_dwordx4 v[226:227], off
	v_lshl_add_u64 v[226:227], v[230:231], 0, s[20:21]
	s_mov_b32 m0, s46
	s_nop 0
	global_load_lds_dwordx4 v[226:227], off
	v_lshl_add_u64 v[226:227], v[232:233], 0, s[20:21]
	s_mov_b32 m0, s47
	s_nop 0
	global_load_lds_dwordx4 v[226:227], off
	ds_read_b128 v[194:197], v154 offset:49152
	ds_read_b128 v[198:201], v154 offset:50176
	ds_read_b128 v[202:205], v154 offset:51200
	ds_read_b128 v[206:209], v154 offset:52224
	ds_read_b128 v[210:213], v154 offset:53248
	ds_read_b128 v[214:217], v154 offset:54272
	ds_read_b128 v[218:221], v154 offset:55296
	ds_read_b128 v[222:225], v154 offset:56320
	s_waitcnt vmcnt(8)
	s_waitcnt lgkmcnt(0)
	s_setprio 1
	s_barrier
	v_mfma_f32_16x16x32_bf16 v[60:63], v[156:159], v[194:197], v[60:63]
	v_mfma_f32_16x16x32_bf16 v[56:59], v[164:167], v[194:197], v[56:59]
	v_mfma_f32_16x16x32_bf16 v[44:47], v[156:159], v[202:205], v[44:47]
	v_mfma_f32_16x16x32_bf16 v[40:43], v[164:167], v[202:205], v[40:43]
	v_mfma_f32_16x16x32_bf16 v[28:31], v[156:159], v[210:213], v[28:31]
	v_mfma_f32_16x16x32_bf16 v[24:27], v[164:167], v[210:213], v[24:27]
	v_mfma_f32_16x16x32_bf16 v[12:15], v[156:159], v[218:221], v[12:15]
	v_mfma_f32_16x16x32_bf16 v[8:11], v[164:167], v[218:221], v[8:11]
	v_mfma_f32_16x16x32_bf16 v[60:63], v[160:163], v[198:201], v[60:63]
	v_mfma_f32_16x16x32_bf16 v[56:59], v[168:171], v[198:201], v[56:59]
	v_mfma_f32_16x16x32_bf16 v[44:47], v[160:163], v[206:209], v[44:47]
	v_mfma_f32_16x16x32_bf16 v[40:43], v[168:171], v[206:209], v[40:43]
	v_mfma_f32_16x16x32_bf16 v[28:31], v[160:163], v[214:217], v[28:31]
	v_mfma_f32_16x16x32_bf16 v[24:27], v[168:171], v[214:217], v[24:27]
	v_mfma_f32_16x16x32_bf16 v[12:15], v[160:163], v[222:225], v[12:15]
	v_mfma_f32_16x16x32_bf16 v[8:11], v[168:171], v[222:225], v[8:11]
	s_setprio 0
	s_setprio 1
	v_mfma_f32_16x16x32_bf16 v[52:55], v[172:175], v[194:197], v[52:55]
	v_mfma_f32_16x16x32_bf16 v[48:51], v[180:183], v[194:197], v[48:51]
	v_mfma_f32_16x16x32_bf16 v[36:39], v[172:175], v[202:205], v[36:39]
	v_mfma_f32_16x16x32_bf16 v[32:35], v[180:183], v[202:205], v[32:35]
	v_mfma_f32_16x16x32_bf16 v[20:23], v[172:175], v[210:213], v[20:23]
	v_mfma_f32_16x16x32_bf16 v[16:19], v[180:183], v[210:213], v[16:19]
	v_mfma_f32_16x16x32_bf16 v[4:7], v[172:175], v[218:221], v[4:7]
	v_mfma_f32_16x16x32_bf16 v[0:3], v[180:183], v[218:221], v[0:3]
	v_mfma_f32_16x16x32_bf16 v[52:55], v[176:179], v[198:201], v[52:55]
	v_mfma_f32_16x16x32_bf16 v[48:51], v[190:193], v[198:201], v[48:51]
	v_mfma_f32_16x16x32_bf16 v[36:39], v[176:179], v[206:209], v[36:39]
	v_mfma_f32_16x16x32_bf16 v[32:35], v[190:193], v[206:209], v[32:35]
	v_mfma_f32_16x16x32_bf16 v[20:23], v[176:179], v[214:217], v[20:23]
	v_mfma_f32_16x16x32_bf16 v[16:19], v[190:193], v[214:217], v[16:19]
	v_mfma_f32_16x16x32_bf16 v[4:7], v[176:179], v[222:225], v[4:7]
	v_mfma_f32_16x16x32_bf16 v[0:3], v[190:193], v[222:225], v[0:3]
	s_barrier
	s_setprio 0
	s_add_i32 s63, s63, 2
	s_add_u32 s50, s50, 0x100
	s_addc_u32 s51, s51, 0
	s_add_u32 s39, s39, 0x100
	s_addc_u32 s41, s41, 0
	s_cmp_gt_u32 s63, 29
	s_cbranch_scc0 .LBB0_1657
	s_and_b64 vcc, exec, s[34:35]
	s_cbranch_vccz .LBB0_1660
	s_barrier

; #define PG8_STAGE(bufoff, gbase, voff) do { _Pragma("unroll") for (int _i = 0; _i < 2; ++_i) \
;         __builtin_amdgcn_global_load_lds((const unsigned*)((const char*)(gbase) + (voff)[_i]), (PG8_LAS unsigned*)(lds + (bufoff) + ldsw + _i * 8192), 16, 0, 0); } while (0)
; #define PG8_LDA(dst, b, h) do { _Pragma("unroll") for (int m = 0; m < 4; ++m) _Pragma("unroll") for (int k = 0; k < 2; ++k) dst[m][k] = *(const PG8_LAS bf16x8*)(lds + PG8_SA(b, h) + aoff + m * 2048 + k * 1024); } while (0)
; #define PG8_LDB(dst, b, h) do { _Pragma("unroll") for (int n = 0; n < 2; ++n) _Pragma("unroll") for (int k = 0; k < 2; ++k) dst[n][k] = *(const PG8_LAS bf16x8*)(lds + PG8_SB(b, h) + boff + n * 2048 + k * 1024); } while (0)
; #define PG8_MMA(ai, bj, At, Bt) do { __builtin_amdgcn_s_setprio(1); _Pragma("unroll") for (int m = 0; m < 4; ++m) _Pragma("unroll") for (int n = 0; n < 2; ++n) _Pragma("unroll") for (int k = 0; k < 2; ++k) \
;         acc[ai][bj][m][n] = __builtin_amdgcn_mfma_f32_16x16x32_bf16(Bt[n][k], At[m][k], acc[ai][bj][m][n], 0, 0, 0); __builtin_amdgcn_s_setprio(0); } while (0)
; #define PG8_WAIT_V(n) asm volatile("s_waitcnt vmcnt(" #n ")" ::: "memory")
; #define PG8_BAR __builtin_amdgcn_s_barrier()
; template <class Epi, class Sched, bool ALIGN_EPI = false, bool SP2 = false>
; __device__ __forceinline__ void gemm_phase(PG8_LAS unsigned char* lds, const Gemm g, const Sched& S, const Epi& E) {
;     ...
;         for (int t = 0; t < nt; t += 2) {
;             const bool last = (t == nt - 2);
;             const char* a1 = cA + (size_t)(t + 1) * kstA;
;             const char* a2 = last ? nA : cA + (size_t)(t + 2) * kstA; const char* b2 = last ? nB : cB + (size_t)(t + 2) * kstep;
;             const char* a3 = a2 + kstA; const char* b3 = b2 + kstep;
;             if (last && has_next) S.a_ready(nxt);
;             if constexpr (SP2) {
;             PG8_LDB(B0, 0, 0); PG8_LDB(B1, 0, 1); PG8_SCHED; PG8_LDA(At, 0, 0); PG8_STAGE(PG8_SA(1, 1), a1 + hstepA, voffA);
;             PG8_WAIT_V(8); PG8_WAIT_L(0); PG8_BAR; PG8_MMA(0, 0, At, B0); PG8_MMA(0, 1, At, B1); PG8_BAR; PG8_SCHED;
;             PG8_LDA(At, 0, 1); PG8_STAGE(PG8_SB(0, 0), b2, voffB); PG8_STAGE(PG8_SB(0, 1), b2 + hstepB, voffB); PG8_STAGE(PG8_SA(0, 0), a2, voffA);
;             PG8_WAIT_V(8); PG8_WAIT_L(0); PG8_BAR; PG8_MMA(1, 0, At, B0); PG8_MMA(1, 1, At, B1); PG8_BAR; PG8_SCHED;
.LBB0_1754:
	s_or_b32 s44, s62, 1
	s_add_i32 s62, s62, 2
	s_mov_b32 s63, s45
	s_lshl_b64 s[4:5], s[44:45], 15
	s_lshl_b64 s[6:7], s[62:63], 15
	s_add_u32 s12, s34, s6
	s_addc_u32 s13, s35, s7
	s_and_b64 s[6:7], s[50:51], exec
	s_cselect_b32 s69, s13, s59
	s_cselect_b32 s68, s12, s58
	s_lshl_b64 s[6:7], s[62:63], 7
	s_add_u32 s12, s40, s6
	s_addc_u32 s13, s41, s7
	s_and_b64 s[6:7], s[50:51], exec
	s_cselect_b32 s53, s13, s61
	s_cselect_b32 s52, s12, s60
	s_add_u32 s50, s68, 0x8000
	s_addc_u32 s51, s69, 0
	s_add_u32 s4, s21, s4
	s_addc_u32 s5, s39, s5
	v_lshl_add_u64 v[174:175], s[4:5], 0, v[128:129]
	s_add_i32 m0, s74, 0xc000
	s_nop 0
	global_load_lds_dwordx4 v[174:175], off
	v_lshl_add_u64 v[174:175], s[4:5], 0, v[132:133]
	s_add_i32 m0, s74, 0xe000
	s_nop 0
	global_load_lds_dwordx4 v[174:175], off
	v_add_u32_e32 v170, s10, v177
	v_add_u32_e32 v174, s11, v177
	ds_read_b128 v[158:161], v170
	ds_read_b128 v[162:165], v170 offset:1024
	ds_read_b128 v[166:169], v170 offset:2048
	ds_read_b128 v[170:173], v170 offset:3072
	ds_read_b128 v[180:183], v174
	ds_read_b128 v[190:193], v174 offset:1024
	ds_read_b128 v[194:197], v174 offset:2048
	ds_read_b128 v[198:201], v174 offset:3072
	ds_read_b128 v[202:205], v179
	ds_read_b128 v[206:209], v179 offset:1024
	ds_read_b128 v[210:213], v179 offset:2048
	ds_read_b128 v[214:217], v179 offset:3072
	ds_read_b128 v[218:221], v179 offset:4096
	ds_read_b128 v[222:225], v179 offset:5120
	ds_read_b128 v[226:229], v179 offset:6144
	ds_read_b128 v[230:233], v179 offset:7168
	s_waitcnt vmcnt(8)
	s_waitcnt lgkmcnt(0)
	s_setprio 1
	s_barrier
	v_mfma_f32_16x16x32_bf16 v[124:127], v[158:161], v[202:205], v[124:127]
	v_mfma_f32_16x16x32_bf16 v[120:123], v[166:169], v[202:205], v[120:123]
	v_mfma_f32_16x16x32_bf16 v[116:119], v[158:161], v[210:213], v[116:119]
	v_mfma_f32_16x16x32_bf16 v[112:115], v[166:169], v[210:213], v[112:115]
	v_mfma_f32_16x16x32_bf16 v[108:111], v[158:161], v[218:221], v[108:111]
	v_mfma_f32_16x16x32_bf16 v[104:107], v[166:169], v[218:221], v[104:107]
	v_mfma_f32_16x16x32_bf16 v[100:103], v[158:161], v[226:229], v[100:103]
	v_mfma_f32_16x16x32_bf16 v[96:99], v[166:169], v[226:229], v[96:99]
	v_mfma_f32_16x16x32_bf16 v[124:127], v[162:165], v[206:209], v[124:127]
	v_mfma_f32_16x16x32_bf16 v[120:123], v[170:173], v[206:209], v[120:123]
	v_mfma_f32_16x16x32_bf16 v[116:119], v[162:165], v[214:217], v[116:119]
	v_mfma_f32_16x16x32_bf16 v[112:115], v[170:173], v[214:217], v[112:115]
	v_mfma_f32_16x16x32_bf16 v[108:111], v[162:165], v[222:225], v[108:111]
	v_mfma_f32_16x16x32_bf16 v[104:107], v[170:173], v[222:225], v[104:107]
	v_mfma_f32_16x16x32_bf16 v[100:103], v[162:165], v[230:233], v[100:103]
	v_mfma_f32_16x16x32_bf16 v[96:99], v[170:173], v[230:233], v[96:99]
	s_setprio 0
	s_setprio 1
	v_mfma_f32_16x16x32_bf16 v[92:95], v[180:183], v[202:205], v[92:95]
	v_mfma_f32_16x16x32_bf16 v[88:91], v[194:197], v[202:205], v[88:91]
	v_mfma_f32_16x16x32_bf16 v[84:87], v[180:183], v[210:213], v[84:87]
	v_mfma_f32_16x16x32_bf16 v[80:83], v[194:197], v[210:213], v[80:83]
	v_mfma_f32_16x16x32_bf16 v[76:79], v[180:183], v[218:221], v[76:79]
	v_mfma_f32_16x16x32_bf16 v[72:75], v[194:197], v[218:221], v[72:75]
	v_mfma_f32_16x16x32_bf16 v[68:71], v[180:183], v[226:229], v[68:71]
	v_mfma_f32_16x16x32_bf16 v[64:67], v[194:197], v[226:229], v[64:67]
	v_mfma_f32_16x16x32_bf16 v[92:95], v[190:193], v[206:209], v[92:95]
	v_mfma_f32_16x16x32_bf16 v[88:91], v[198:201], v[206:209], v[88:91]
	v_mfma_f32_16x16x32_bf16 v[84:87], v[190:193], v[214:217], v[84:87]
	v_mfma_f32_16x16x32_bf16 v[80:83], v[198:201], v[214:217], v[80:83]
	v_mfma_f32_16x16x32_bf16 v[76:79], v[190:193], v[222:225], v[76:79]
	v_mfma_f32_16x16x32_bf16 v[72:75], v[198:201], v[222:225], v[72:75]
	v_mfma_f32_16x16x32_bf16 v[68:71], v[190:193], v[230:233], v[68:71]
	v_mfma_f32_16x16x32_bf16 v[64:67], v[198:201], v[230:233], v[64:67]
	s_barrier
	s_setprio 0
	s_add_i32 s4, s10, s71
	v_lshl_add_u64 v[174:175], s[52:53], 0, v[130:131]
	s_mov_b32 m0, s4
	s_nop 0
	global_load_lds_dwordx4 v[174:175], off
	s_add_i32 m0, s4, 0x2000
	s_add_u32 s4, s52, 0x160000
	v_lshl_add_u64 v[234:235], s[52:53], 0, v[134:135]
	s_addc_u32 s5, s53, 0
	s_add_i32 s6, s11, s71
	global_load_lds_dwordx4 v[234:235], off
	v_lshl_add_u64 v[236:237], s[4:5], 0, v[130:131]
	s_mov_b32 m0, s6
	s_nop 0
	global_load_lds_dwordx4 v[236:237], off
	v_lshl_add_u64 v[236:237], s[4:5], 0, v[134:135]
	s_add_i32 m0, s6, 0x2000
	s_nop 0
	global_load_lds_dwordx4 v[236:237], off
	v_lshl_add_u64 v[236:237], s[68:69], 0, v[128:129]
	s_mov_b32 m0, s74
	s_nop 0
	global_load_lds_dwordx4 v[236:237], off
	v_lshl_add_u64 v[236:237], s[68:69], 0, v[132:133]
	s_mov_b32 m0, s76
	s_nop 0
	global_load_lds_dwordx4 v[236:237], off
	ds_read_b128 v[202:205], v179 offset:16384
	ds_read_b128 v[206:209], v179 offset:17408
	ds_read_b128 v[210:213], v179 offset:18432
	ds_read_b128 v[214:217], v179 offset:19456
	ds_read_b128 v[218:221], v179 offset:20480
	ds_read_b128 v[222:225], v179 offset:21504
	ds_read_b128 v[226:229], v179 offset:22528
	ds_read_b128 v[230:233], v179 offset:23552
	s_waitcnt vmcnt(8)
	s_waitcnt lgkmcnt(0)
	s_setprio 1
	s_barrier
; #define PG8_STAGE(bufoff, gbase, voff) do { _Pragma("unroll") for (int _i = 0; _i < 2; ++_i) \
;         __builtin_amdgcn_global_load_lds((const unsigned*)((const char*)(gbase) + (voff)[_i]), (PG8_LAS unsigned*)(lds + (bufoff) + ldsw + _i * 8192), 16, 0, 0); } while (0)
; #define PG8_LDA(dst, b, h) do { _Pragma("unroll") for (int m = 0; m < 4; ++m) _Pragma("unroll") for (int k = 0; k < 2; ++k) dst[m][k] = *(const PG8_LAS bf16x8*)(lds + PG8_SA(b, h) + aoff + m * 2048 + k * 1024); } while (0)
; #define PG8_LDB(dst, b, h) do { _Pragma("unroll") for (int n = 0; n < 2; ++n) _Pragma("unroll") for (int k = 0; k < 2; ++k) dst[n][k] = *(const PG8_LAS bf16x8*)(lds + PG8_SB(b, h) + boff + n * 2048 + k * 1024); } while (0)
; #define PG8_MMA(ai, bj, At, Bt) do { __builtin_amdgcn_s_setprio(1); _Pragma("unroll") for (int m = 0; m < 4; ++m) _Pragma("unroll") for (int n = 0; n < 2; ++n) _Pragma("unroll") for (int k = 0; k < 2; ++k) \
;         acc[ai][bj][m][n] = __builtin_amdgcn_mfma_f32_16x16x32_bf16(Bt[n][k], At[m][k], acc[ai][bj][m][n], 0, 0, 0); __builtin_amdgcn_s_setprio(0); } while (0)
; #define PG8_WAIT_V(n) asm volatile("s_waitcnt vmcnt(" #n ")" ::: "memory")
; #define PG8_WAIT_L(n) asm volatile("s_waitcnt lgkmcnt(" #n ")" ::: "memory")
; #define PG8_BAR __builtin_amdgcn_s_barrier()
; #define PG8_SCHED __builtin_amdgcn_sched_barrier(0)
; template <class Epi, class Sched, bool ALIGN_EPI = false, bool SP2 = false>
; __device__ __forceinline__ void gemm_phase(PG8_LAS unsigned char* lds, const Gemm g, const Sched& S, const Epi& E) {
;     ...
;             PG8_WAIT_V(8); PG8_WAIT_L(0); PG8_BAR; PG8_MMA(1, 0, At, B0); PG8_MMA(1, 1, At, B1); PG8_BAR; PG8_SCHED;
;             PG8_LDB(B0, 1, 0); PG8_LDB(B1, 1, 1); PG8_SCHED; PG8_LDA(At, 1, 0); PG8_STAGE(PG8_SA(0, 1), a2 + hstepA, voffA);
;             PG8_WAIT_V(8); PG8_WAIT_L(0); PG8_BAR; PG8_MMA(0, 0, At, B0); PG8_MMA(0, 1, At, B1); PG8_BAR; PG8_SCHED;
	v_mfma_f32_16x16x32_bf16 v[60:63], v[158:161], v[202:205], v[60:63]
	v_mfma_f32_16x16x32_bf16 v[56:59], v[166:169], v[202:205], v[56:59]
	v_mfma_f32_16x16x32_bf16 v[52:55], v[158:161], v[210:213], v[52:55]
	v_mfma_f32_16x16x32_bf16 v[48:51], v[166:169], v[210:213], v[48:51]
	v_mfma_f32_16x16x32_bf16 v[44:47], v[158:161], v[218:221], v[44:47]
	v_mfma_f32_16x16x32_bf16 v[40:43], v[166:169], v[218:221], v[40:43]
	v_mfma_f32_16x16x32_bf16 v[36:39], v[158:161], v[226:229], v[36:39]
	v_mfma_f32_16x16x32_bf16 v[32:35], v[166:169], v[226:229], v[32:35]
	v_mfma_f32_16x16x32_bf16 v[60:63], v[162:165], v[206:209], v[60:63]
	v_mfma_f32_16x16x32_bf16 v[56:59], v[170:173], v[206:209], v[56:59]
	v_mfma_f32_16x16x32_bf16 v[52:55], v[162:165], v[214:217], v[52:55]
	v_mfma_f32_16x16x32_bf16 v[48:51], v[170:173], v[214:217], v[48:51]
	v_mfma_f32_16x16x32_bf16 v[44:47], v[162:165], v[222:225], v[44:47]
	v_mfma_f32_16x16x32_bf16 v[40:43], v[170:173], v[222:225], v[40:43]
	v_mfma_f32_16x16x32_bf16 v[36:39], v[162:165], v[230:233], v[36:39]
	v_mfma_f32_16x16x32_bf16 v[32:35], v[170:173], v[230:233], v[32:35]
	s_setprio 0
	s_setprio 1
	v_mfma_f32_16x16x32_bf16 v[28:31], v[180:183], v[202:205], v[28:31]
	v_mfma_f32_16x16x32_bf16 v[24:27], v[194:197], v[202:205], v[24:27]
	v_mfma_f32_16x16x32_bf16 v[20:23], v[180:183], v[210:213], v[20:23]
	v_mfma_f32_16x16x32_bf16 v[16:19], v[194:197], v[210:213], v[16:19]
	v_mfma_f32_16x16x32_bf16 v[12:15], v[180:183], v[218:221], v[12:15]
	v_mfma_f32_16x16x32_bf16 v[8:11], v[194:197], v[218:221], v[8:11]
	v_mfma_f32_16x16x32_bf16 v[4:7], v[180:183], v[226:229], v[4:7]
	v_mfma_f32_16x16x32_bf16 v[0:3], v[194:197], v[226:229], v[0:3]
	v_mfma_f32_16x16x32_bf16 v[28:31], v[190:193], v[206:209], v[28:31]
	v_mfma_f32_16x16x32_bf16 v[24:27], v[198:201], v[206:209], v[24:27]
	v_mfma_f32_16x16x32_bf16 v[20:23], v[190:193], v[214:217], v[20:23]
	v_mfma_f32_16x16x32_bf16 v[16:19], v[198:201], v[214:217], v[16:19]
	v_mfma_f32_16x16x32_bf16 v[12:15], v[190:193], v[222:225], v[12:15]
	v_mfma_f32_16x16x32_bf16 v[8:11], v[198:201], v[222:225], v[8:11]
	v_mfma_f32_16x16x32_bf16 v[4:7], v[190:193], v[230:233], v[4:7]
	v_mfma_f32_16x16x32_bf16 v[0:3], v[198:201], v[230:233], v[0:3]
	s_barrier
	s_setprio 0
	s_add_i32 s6, 0, 0x18000
	s_add_i32 s7, 0, 0x1c000
	s_add_u32 s4, s68, 0x4000
	s_addc_u32 s5, s69, 0
	s_mov_b32 m0, s77
	v_lshl_add_u64 v[236:237], s[4:5], 0, v[128:129]
	global_load_lds_dwordx4 v[236:237], off
	v_lshl_add_u64 v[236:237], s[4:5], 0, v[132:133]
	s_mov_b32 m0, s75
	s_nop 0
	global_load_lds_dwordx4 v[236:237], off
	v_add_u32_e32 v170, s6, v177
	v_add_u32_e32 v198, s7, v177
	ds_read_b128 v[158:161], v170
	ds_read_b128 v[162:165], v170 offset:1024
	ds_read_b128 v[166:169], v170 offset:2048
	ds_read_b128 v[170:173], v170 offset:3072
	ds_read_b128 v[180:183], v198
	ds_read_b128 v[190:193], v198 offset:1024
	ds_read_b128 v[194:197], v198 offset:2048
	ds_read_b128 v[198:201], v198 offset:3072
	ds_read_b128 v[202:205], v179 offset:32768
	ds_read_b128 v[206:209], v179 offset:33792
	ds_read_b128 v[210:213], v179 offset:34816
	ds_read_b128 v[214:217], v179 offset:35840
	ds_read_b128 v[218:221], v179 offset:36864
	ds_read_b128 v[222:225], v179 offset:37888
	ds_read_b128 v[226:229], v179 offset:38912
	ds_read_b128 v[230:233], v179 offset:39936
	s_waitcnt vmcnt(8)
	s_waitcnt lgkmcnt(0)
	s_setprio 1
	s_barrier
	v_mfma_f32_16x16x32_bf16 v[124:127], v[158:161], v[202:205], v[124:127]
	v_mfma_f32_16x16x32_bf16 v[120:123], v[166:169], v[202:205], v[120:123]
	v_mfma_f32_16x16x32_bf16 v[116:119], v[158:161], v[210:213], v[116:119]
	v_mfma_f32_16x16x32_bf16 v[112:115], v[166:169], v[210:213], v[112:115]
	v_mfma_f32_16x16x32_bf16 v[108:111], v[158:161], v[218:221], v[108:111]
	v_mfma_f32_16x16x32_bf16 v[104:107], v[166:169], v[218:221], v[104:107]
	v_mfma_f32_16x16x32_bf16 v[100:103], v[158:161], v[226:229], v[100:103]
	v_mfma_f32_16x16x32_bf16 v[96:99], v[166:169], v[226:229], v[96:99]
	v_mfma_f32_16x16x32_bf16 v[124:127], v[162:165], v[206:209], v[124:127]
	v_mfma_f32_16x16x32_bf16 v[120:123], v[170:173], v[206:209], v[120:123]
	v_mfma_f32_16x16x32_bf16 v[116:119], v[162:165], v[214:217], v[116:119]
	v_mfma_f32_16x16x32_bf16 v[112:115], v[170:173], v[214:217], v[112:115]
	v_mfma_f32_16x16x32_bf16 v[108:111], v[162:165], v[222:225], v[108:111]
	v_mfma_f32_16x16x32_bf16 v[104:107], v[170:173], v[222:225], v[104:107]
	v_mfma_f32_16x16x32_bf16 v[100:103], v[162:165], v[230:233], v[100:103]
	v_mfma_f32_16x16x32_bf16 v[96:99], v[170:173], v[230:233], v[96:99]
	s_setprio 0
	s_setprio 1
	v_mfma_f32_16x16x32_bf16 v[92:95], v[180:183], v[202:205], v[92:95]
	v_mfma_f32_16x16x32_bf16 v[88:91], v[194:197], v[202:205], v[88:91]
	v_mfma_f32_16x16x32_bf16 v[84:87], v[180:183], v[210:213], v[84:87]
	v_mfma_f32_16x16x32_bf16 v[80:83], v[194:197], v[210:213], v[80:83]
	v_mfma_f32_16x16x32_bf16 v[76:79], v[180:183], v[218:221], v[76:79]
	v_mfma_f32_16x16x32_bf16 v[72:75], v[194:197], v[218:221], v[72:75]
	v_mfma_f32_16x16x32_bf16 v[68:71], v[180:183], v[226:229], v[68:71]
	v_mfma_f32_16x16x32_bf16 v[64:67], v[194:197], v[226:229], v[64:67]
	v_mfma_f32_16x16x32_bf16 v[92:95], v[190:193], v[206:209], v[92:95]
	v_mfma_f32_16x16x32_bf16 v[88:91], v[198:201], v[206:209], v[88:91]
	v_mfma_f32_16x16x32_bf16 v[84:87], v[190:193], v[214:217], v[84:87]
	v_mfma_f32_16x16x32_bf16 v[80:83], v[198:201], v[214:217], v[80:83]
	v_mfma_f32_16x16x32_bf16 v[76:79], v[190:193], v[222:225], v[76:79]
	v_mfma_f32_16x16x32_bf16 v[72:75], v[198:201], v[222:225], v[72:75]
	v_mfma_f32_16x16x32_bf16 v[68:71], v[190:193], v[230:233], v[68:71]
	v_mfma_f32_16x16x32_bf16 v[64:67], v[198:201], v[230:233], v[64:67]
	s_barrier
; #define PG8_STAGE(bufoff, gbase, voff) do { _Pragma("unroll") for (int _i = 0; _i < 2; ++_i) \
;         __builtin_amdgcn_global_load_lds((const unsigned*)((const char*)(gbase) + (voff)[_i]), (PG8_LAS unsigned*)(lds + (bufoff) + ldsw + _i * 8192), 16, 0, 0); } while (0)
; #define PG8_LDA(dst, b, h) do { _Pragma("unroll") for (int m = 0; m < 4; ++m) _Pragma("unroll") for (int k = 0; k < 2; ++k) dst[m][k] = *(const PG8_LAS bf16x8*)(lds + PG8_SA(b, h) + aoff + m * 2048 + k * 1024); } while (0)
; #define PG8_MMA(ai, bj, At, Bt) do { __builtin_amdgcn_s_setprio(1); _Pragma("unroll") for (int m = 0; m < 4; ++m) _Pragma("unroll") for (int n = 0; n < 2; ++n) _Pragma("unroll") for (int k = 0; k < 2; ++k) \
;         acc[ai][bj][m][n] = __builtin_amdgcn_mfma_f32_16x16x32_bf16(Bt[n][k], At[m][k], acc[ai][bj][m][n], 0, 0, 0); __builtin_amdgcn_s_setprio(0); } while (0)
; #define PG8_WAIT_V(n) asm volatile("s_waitcnt vmcnt(" #n ")" ::: "memory")
; #define PG8_WAIT_L(n) asm volatile("s_waitcnt lgkmcnt(" #n ")" ::: "memory")
; #define PG8_BAR __builtin_amdgcn_s_barrier()
; #define PG8_SCHED __builtin_amdgcn_sched_barrier(0)
; template <class Epi, class Sched, bool ALIGN_EPI = false, bool SP2 = false>
; __device__ __forceinline__ void gemm_phase(PG8_LAS unsigned char* lds, const Gemm g, const Sched& S, const Epi& E) {
;     ...
;         for (int t = 0; t < nt; t += 2) {
;     ...
;             PG8_LDA(At, 1, 1); PG8_STAGE(PG8_SB(1, 0), b3, voffB); PG8_STAGE(PG8_SB(1, 1), b3 + hstepB, voffB); PG8_STAGE(PG8_SA(1, 0), a3, voffA);
;             PG8_WAIT_V(8); PG8_WAIT_L(0); PG8_BAR; PG8_MMA(1, 0, At, B0); PG8_MMA(1, 1, At, B1); PG8_BAR; PG8_SCHED;
	s_setprio 0
	s_add_i32 s4, s6, s71
	v_lshl_add_u64 v[174:175], v[174:175], 0, s[54:55]
	s_mov_b32 m0, s4
	s_nop 0
	global_load_lds_dwordx4 v[174:175], off
	s_add_i32 m0, s4, 0x2000
	s_add_u32 s4, s52, 0x160080
	v_lshl_add_u64 v[174:175], v[234:235], 0, s[54:55]
	s_addc_u32 s5, s53, 0
	s_add_i32 s6, s7, s71
	global_load_lds_dwordx4 v[174:175], off
	v_lshl_add_u64 v[174:175], s[4:5], 0, v[130:131]
	s_mov_b32 m0, s6
	s_nop 0
	global_load_lds_dwordx4 v[174:175], off
	v_lshl_add_u64 v[174:175], s[4:5], 0, v[134:135]
	s_add_i32 m0, s6, 0x2000
	s_nop 0
	global_load_lds_dwordx4 v[174:175], off
	v_lshl_add_u64 v[174:175], s[50:51], 0, v[128:129]
	s_mov_b32 m0, s95
	s_nop 0
	global_load_lds_dwordx4 v[174:175], off
	v_lshl_add_u64 v[174:175], s[50:51], 0, v[132:133]
	s_mov_b32 m0, s96
	s_nop 0
	global_load_lds_dwordx4 v[174:175], off
	ds_read_b128 v[202:205], v179 offset:49152
	ds_read_b128 v[206:209], v179 offset:50176
	ds_read_b128 v[210:213], v179 offset:51200
	ds_read_b128 v[214:217], v179 offset:52224
	ds_read_b128 v[218:221], v179 offset:53248
	ds_read_b128 v[222:225], v179 offset:54272
	ds_read_b128 v[226:229], v179 offset:55296
	ds_read_b128 v[230:233], v179 offset:56320
	s_waitcnt vmcnt(8)
	s_waitcnt lgkmcnt(0)
	s_setprio 1
	s_barrier
	v_mfma_f32_16x16x32_bf16 v[60:63], v[158:161], v[202:205], v[60:63]
	v_mfma_f32_16x16x32_bf16 v[56:59], v[166:169], v[202:205], v[56:59]
	v_mfma_f32_16x16x32_bf16 v[52:55], v[158:161], v[210:213], v[52:55]
	v_mfma_f32_16x16x32_bf16 v[48:51], v[166:169], v[210:213], v[48:51]
	v_mfma_f32_16x16x32_bf16 v[44:47], v[158:161], v[218:221], v[44:47]
	v_mfma_f32_16x16x32_bf16 v[40:43], v[166:169], v[218:221], v[40:43]
	v_mfma_f32_16x16x32_bf16 v[36:39], v[158:161], v[226:229], v[36:39]
	v_mfma_f32_16x16x32_bf16 v[32:35], v[166:169], v[226:229], v[32:35]
	v_mfma_f32_16x16x32_bf16 v[60:63], v[162:165], v[206:209], v[60:63]
	v_mfma_f32_16x16x32_bf16 v[56:59], v[170:173], v[206:209], v[56:59]
	v_mfma_f32_16x16x32_bf16 v[52:55], v[162:165], v[214:217], v[52:55]
	v_mfma_f32_16x16x32_bf16 v[48:51], v[170:173], v[214:217], v[48:51]
	v_mfma_f32_16x16x32_bf16 v[44:47], v[162:165], v[222:225], v[44:47]
	v_mfma_f32_16x16x32_bf16 v[40:43], v[170:173], v[222:225], v[40:43]
	v_mfma_f32_16x16x32_bf16 v[36:39], v[162:165], v[230:233], v[36:39]
	v_mfma_f32_16x16x32_bf16 v[32:35], v[170:173], v[230:233], v[32:35]
	s_setprio 0
	s_setprio 1
	v_mfma_f32_16x16x32_bf16 v[28:31], v[180:183], v[202:205], v[28:31]
	v_mfma_f32_16x16x32_bf16 v[24:27], v[194:197], v[202:205], v[24:27]
	v_mfma_f32_16x16x32_bf16 v[20:23], v[180:183], v[210:213], v[20:23]
	v_mfma_f32_16x16x32_bf16 v[16:19], v[194:197], v[210:213], v[16:19]
	v_mfma_f32_16x16x32_bf16 v[12:15], v[180:183], v[218:221], v[12:15]
	v_mfma_f32_16x16x32_bf16 v[8:11], v[194:197], v[218:221], v[8:11]
	v_mfma_f32_16x16x32_bf16 v[4:7], v[180:183], v[226:229], v[4:7]
	v_mfma_f32_16x16x32_bf16 v[0:3], v[194:197], v[226:229], v[0:3]
	v_mfma_f32_16x16x32_bf16 v[28:31], v[190:193], v[206:209], v[28:31]
	v_mfma_f32_16x16x32_bf16 v[24:27], v[198:201], v[206:209], v[24:27]
	v_mfma_f32_16x16x32_bf16 v[20:23], v[190:193], v[214:217], v[20:23]
	v_mfma_f32_16x16x32_bf16 v[16:19], v[198:201], v[214:217], v[16:19]
	v_mfma_f32_16x16x32_bf16 v[12:15], v[190:193], v[222:225], v[12:15]
	v_mfma_f32_16x16x32_bf16 v[8:11], v[198:201], v[222:225], v[8:11]
	v_mfma_f32_16x16x32_bf16 v[4:7], v[190:193], v[230:233], v[4:7]
	v_mfma_f32_16x16x32_bf16 v[0:3], v[198:201], v[230:233], v[0:3]
	s_barrier
	s_setprio 0
	s_cmp_ge_i32 s62, s97
	s_cbranch_scc1 .LBB0_1766

; #define PG8_STAGE(bufoff, gbase, voff) do { _Pragma("unroll") for (int _i = 0; _i < 2; ++_i) \
;         __builtin_amdgcn_global_load_lds((const unsigned*)((const char*)(gbase) + (voff)[_i]), (PG8_LAS unsigned*)(lds + (bufoff) + ldsw + _i * 8192), 16, 0, 0); } while (0)
; #define PG8_LDA(dst, b, h) do { _Pragma("unroll") for (int m = 0; m < 4; ++m) _Pragma("unroll") for (int k = 0; k < 2; ++k) dst[m][k] = *(const PG8_LAS bf16x8*)(lds + PG8_SA(b, h) + aoff + m * 2048 + k * 1024); } while (0)
; #define PG8_LDB(dst, b, h) do { _Pragma("unroll") for (int n = 0; n < 2; ++n) _Pragma("unroll") for (int k = 0; k < 2; ++k) dst[n][k] = *(const PG8_LAS bf16x8*)(lds + PG8_SB(b, h) + boff + n * 2048 + k * 1024); } while (0)
; #define PG8_MMA(ai, bj, At, Bt) do { __builtin_amdgcn_s_setprio(1); _Pragma("unroll") for (int m = 0; m < 4; ++m) _Pragma("unroll") for (int n = 0; n < 2; ++n) _Pragma("unroll") for (int k = 0; k < 2; ++k) \
;         acc[ai][bj][m][n] = __builtin_amdgcn_mfma_f32_16x16x32_bf16(Bt[n][k], At[m][k], acc[ai][bj][m][n], 0, 0, 0); __builtin_amdgcn_s_setprio(0); } while (0)
; #define PG8_WAIT_V(n) asm volatile("s_waitcnt vmcnt(" #n ")" ::: "memory")
; #define PG8_BAR __builtin_amdgcn_s_barrier()
; template <class Epi, class Sched, bool ALIGN_EPI = false, bool SP2 = false>
; __device__ __forceinline__ void gemm_phase(PG8_LAS unsigned char* lds, const Gemm g, const Sched& S, const Epi& E) {
;     ...
;         for (int t = 0; t < nt; t += 2) {
;             const bool last = (t == nt - 2);
;             const char* a1 = cA + (size_t)(t + 1) * kstA;
;             const char* a2 = last ? nA : cA + (size_t)(t + 2) * kstA; const char* b2 = last ? nB : cB + (size_t)(t + 2) * kstep;
;             const char* a3 = a2 + kstA; const char* b3 = b2 + kstep;
;             if (last && has_next) S.a_ready(nxt);
;             if constexpr (SP2) {
;             PG8_LDB(B0, 0, 0); PG8_LDB(B1, 0, 1); PG8_SCHED; PG8_LDA(At, 0, 0); PG8_STAGE(PG8_SA(1, 1), a1 + hstepA, voffA);
;             PG8_WAIT_V(8); PG8_WAIT_L(0); PG8_BAR; PG8_MMA(0, 0, At, B0); PG8_MMA(0, 1, At, B1); PG8_BAR; PG8_SCHED;
;             PG8_LDA(At, 0, 1); PG8_STAGE(PG8_SB(0, 0), b2, voffB); PG8_STAGE(PG8_SB(0, 1), b2 + hstepB, voffB); PG8_STAGE(PG8_SA(0, 0), a2, voffA);
;             PG8_WAIT_V(8); PG8_WAIT_L(0); PG8_BAR; PG8_MMA(1, 0, At, B0); PG8_MMA(1, 1, At, B1); PG8_BAR; PG8_SCHED;
.LBB0_2050:
	s_add_u32 s13, s20, 0xfff80080
	s_addc_u32 s33, s21, -1
	s_cmp_eq_u32 s12, 28
	s_cselect_b32 s41, s1, s33
	s_cselect_b32 s40, s3, s13
	s_cselect_b32 s39, s4, s11
	s_cselect_b32 s38, s5, s10
	v_lshl_add_u64 v[226:227], s[20:21], 0, v[148:149]
	s_add_i32 m0, s7, 0xc000
	s_nop 0
	global_load_lds_dwordx4 v[226:227], off
	v_lshl_add_u64 v[226:227], s[20:21], 0, v[150:151]
	s_add_i32 m0, s7, 0xe000
	s_nop 0
	global_load_lds_dwordx4 v[226:227], off
	ds_read_b128 v[128:131], v159
	ds_read_b128 v[132:135], v159 offset:1024
	ds_read_b128 v[164:167], v159 offset:2048
	ds_read_b128 v[168:171], v159 offset:3072
	ds_read_b128 v[172:175], v160
	ds_read_b128 v[176:179], v160 offset:1024
	ds_read_b128 v[180:183], v160 offset:2048
	ds_read_b128 v[190:193], v160 offset:3072
	ds_read_b128 v[194:197], v161
	ds_read_b128 v[198:201], v161 offset:1024
	ds_read_b128 v[202:205], v161 offset:2048
	ds_read_b128 v[206:209], v161 offset:3072
	ds_read_b128 v[210:213], v161 offset:4096
	ds_read_b128 v[214:217], v161 offset:5120
	ds_read_b128 v[218:221], v161 offset:6144
	ds_read_b128 v[222:225], v161 offset:7168
	s_waitcnt vmcnt(8)
	s_waitcnt lgkmcnt(0)
	s_setprio 1
	s_barrier
	v_mfma_f32_16x16x32_bf16 v[124:127], v[128:131], v[194:197], v[124:127]
	v_mfma_f32_16x16x32_bf16 v[120:123], v[164:167], v[194:197], v[120:123]
	v_mfma_f32_16x16x32_bf16 v[108:111], v[128:131], v[202:205], v[108:111]
	v_mfma_f32_16x16x32_bf16 v[104:107], v[164:167], v[202:205], v[104:107]
	v_mfma_f32_16x16x32_bf16 v[92:95], v[128:131], v[210:213], v[92:95]
	v_mfma_f32_16x16x32_bf16 v[88:91], v[164:167], v[210:213], v[88:91]
	v_mfma_f32_16x16x32_bf16 v[76:79], v[128:131], v[218:221], v[76:79]
	v_mfma_f32_16x16x32_bf16 v[72:75], v[164:167], v[218:221], v[72:75]
	v_mfma_f32_16x16x32_bf16 v[124:127], v[132:135], v[198:201], v[124:127]
	v_mfma_f32_16x16x32_bf16 v[120:123], v[168:171], v[198:201], v[120:123]
	v_mfma_f32_16x16x32_bf16 v[108:111], v[132:135], v[206:209], v[108:111]
	v_mfma_f32_16x16x32_bf16 v[104:107], v[168:171], v[206:209], v[104:107]
	v_mfma_f32_16x16x32_bf16 v[92:95], v[132:135], v[214:217], v[92:95]
	v_mfma_f32_16x16x32_bf16 v[88:91], v[168:171], v[214:217], v[88:91]
	v_mfma_f32_16x16x32_bf16 v[76:79], v[132:135], v[222:225], v[76:79]
	v_mfma_f32_16x16x32_bf16 v[72:75], v[168:171], v[222:225], v[72:75]
	s_setprio 0
	s_setprio 1
	v_mfma_f32_16x16x32_bf16 v[116:119], v[172:175], v[194:197], v[116:119]
	v_mfma_f32_16x16x32_bf16 v[112:115], v[180:183], v[194:197], v[112:115]
	v_mfma_f32_16x16x32_bf16 v[100:103], v[172:175], v[202:205], v[100:103]
	v_mfma_f32_16x16x32_bf16 v[96:99], v[180:183], v[202:205], v[96:99]
	v_mfma_f32_16x16x32_bf16 v[84:87], v[172:175], v[210:213], v[84:87]
	v_mfma_f32_16x16x32_bf16 v[80:83], v[180:183], v[210:213], v[80:83]
	v_mfma_f32_16x16x32_bf16 v[68:71], v[172:175], v[218:221], v[68:71]
	v_mfma_f32_16x16x32_bf16 v[64:67], v[180:183], v[218:221], v[64:67]
	v_mfma_f32_16x16x32_bf16 v[116:119], v[176:179], v[198:201], v[116:119]
	v_mfma_f32_16x16x32_bf16 v[112:115], v[190:193], v[198:201], v[112:115]
	v_mfma_f32_16x16x32_bf16 v[100:103], v[176:179], v[206:209], v[100:103]
	v_mfma_f32_16x16x32_bf16 v[96:99], v[190:193], v[206:209], v[96:99]
	v_mfma_f32_16x16x32_bf16 v[84:87], v[176:179], v[214:217], v[84:87]
	v_mfma_f32_16x16x32_bf16 v[80:83], v[190:193], v[214:217], v[80:83]
	v_mfma_f32_16x16x32_bf16 v[68:71], v[176:179], v[222:225], v[68:71]
	v_mfma_f32_16x16x32_bf16 v[64:67], v[190:193], v[222:225], v[64:67]
	s_barrier
	s_setprio 0
	s_add_i32 s13, s69, s6
	v_lshl_add_u64 v[226:227], s[38:39], 0, v[138:139]
	s_mov_b32 m0, s13
	s_nop 0
	global_load_lds_dwordx4 v[226:227], off
	s_add_i32 m0, s13, 0x2000
	s_add_u32 s44, s38, 0x80000
	v_lshl_add_u64 v[228:229], s[38:39], 0, v[142:143]
	s_addc_u32 s45, s39, 0
	s_add_i32 s13, s70, s6
	global_load_lds_dwordx4 v[228:229], off
	v_lshl_add_u64 v[230:231], s[44:45], 0, v[138:139]
	s_mov_b32 m0, s13
	v_lshl_add_u64 v[232:233], s[40:41], 0, v[140:141]
	global_load_lds_dwordx4 v[230:231], off
	v_lshl_add_u64 v[230:231], s[44:45], 0, v[142:143]
	s_add_i32 m0, s13, 0x2000
	s_nop 0
	global_load_lds_dwordx4 v[230:231], off
	v_lshl_add_u64 v[230:231], s[40:41], 0, v[136:137]
	s_mov_b32 m0, s7
	s_nop 0
	global_load_lds_dwordx4 v[230:231], off
	s_mov_b32 m0, s8
	s_nop 0
	global_load_lds_dwordx4 v[232:233], off
	ds_read_b128 v[194:197], v161 offset:16384
	ds_read_b128 v[198:201], v161 offset:17408
	ds_read_b128 v[202:205], v161 offset:18432
	ds_read_b128 v[206:209], v161 offset:19456
	ds_read_b128 v[210:213], v161 offset:20480
	ds_read_b128 v[214:217], v161 offset:21504
	ds_read_b128 v[218:221], v161 offset:22528
	ds_read_b128 v[222:225], v161 offset:23552
	s_waitcnt vmcnt(8)
	s_waitcnt lgkmcnt(0)
	s_setprio 1
	s_barrier
; #define PG8_STAGE(bufoff, gbase, voff) do { _Pragma("unroll") for (int _i = 0; _i < 2; ++_i) \
;         __builtin_amdgcn_global_load_lds((const unsigned*)((const char*)(gbase) + (voff)[_i]), (PG8_LAS unsigned*)(lds + (bufoff) + ldsw + _i * 8192), 16, 0, 0); } while (0)
; #define PG8_LDA(dst, b, h) do { _Pragma("unroll") for (int m = 0; m < 4; ++m) _Pragma("unroll") for (int k = 0; k < 2; ++k) dst[m][k] = *(const PG8_LAS bf16x8*)(lds + PG8_SA(b, h) + aoff + m * 2048 + k * 1024); } while (0)
; #define PG8_LDB(dst, b, h) do { _Pragma("unroll") for (int n = 0; n < 2; ++n) _Pragma("unroll") for (int k = 0; k < 2; ++k) dst[n][k] = *(const PG8_LAS bf16x8*)(lds + PG8_SB(b, h) + boff + n * 2048 + k * 1024); } while (0)
; #define PG8_MMA(ai, bj, At, Bt) do { __builtin_amdgcn_s_setprio(1); _Pragma("unroll") for (int m = 0; m < 4; ++m) _Pragma("unroll") for (int n = 0; n < 2; ++n) _Pragma("unroll") for (int k = 0; k < 2; ++k) \
;         acc[ai][bj][m][n] = __builtin_amdgcn_mfma_f32_16x16x32_bf16(Bt[n][k], At[m][k], acc[ai][bj][m][n], 0, 0, 0); __builtin_amdgcn_s_setprio(0); } while (0)
; #define PG8_WAIT_V(n) asm volatile("s_waitcnt vmcnt(" #n ")" ::: "memory")
; #define PG8_WAIT_L(n) asm volatile("s_waitcnt lgkmcnt(" #n ")" ::: "memory")
; #define PG8_BAR __builtin_amdgcn_s_barrier()
; #define PG8_SCHED __builtin_amdgcn_sched_barrier(0)
; template <class Epi, class Sched, bool ALIGN_EPI = false, bool SP2 = false>
; __device__ __forceinline__ void gemm_phase(PG8_LAS unsigned char* lds, const Gemm g, const Sched& S, const Epi& E) {
;     ...
;             PG8_WAIT_V(8); PG8_WAIT_L(0); PG8_BAR; PG8_MMA(1, 0, At, B0); PG8_MMA(1, 1, At, B1); PG8_BAR; PG8_SCHED;
;             PG8_LDB(B0, 1, 0); PG8_LDB(B1, 1, 1); PG8_SCHED; PG8_LDA(At, 1, 0); PG8_STAGE(PG8_SA(0, 1), a2 + hstepA, voffA);
;             PG8_WAIT_V(8); PG8_WAIT_L(0); PG8_BAR; PG8_MMA(0, 0, At, B0); PG8_MMA(0, 1, At, B1); PG8_BAR; PG8_SCHED;
	v_mfma_f32_16x16x32_bf16 v[60:63], v[128:131], v[194:197], v[60:63]
	v_mfma_f32_16x16x32_bf16 v[56:59], v[164:167], v[194:197], v[56:59]
	v_mfma_f32_16x16x32_bf16 v[44:47], v[128:131], v[202:205], v[44:47]
	v_mfma_f32_16x16x32_bf16 v[40:43], v[164:167], v[202:205], v[40:43]
	v_mfma_f32_16x16x32_bf16 v[28:31], v[128:131], v[210:213], v[28:31]
	v_mfma_f32_16x16x32_bf16 v[24:27], v[164:167], v[210:213], v[24:27]
	v_mfma_f32_16x16x32_bf16 v[12:15], v[128:131], v[218:221], v[12:15]
	v_mfma_f32_16x16x32_bf16 v[8:11], v[164:167], v[218:221], v[8:11]
	v_mfma_f32_16x16x32_bf16 v[60:63], v[132:135], v[198:201], v[60:63]
	v_mfma_f32_16x16x32_bf16 v[56:59], v[168:171], v[198:201], v[56:59]
	v_mfma_f32_16x16x32_bf16 v[44:47], v[132:135], v[206:209], v[44:47]
	v_mfma_f32_16x16x32_bf16 v[40:43], v[168:171], v[206:209], v[40:43]
	v_mfma_f32_16x16x32_bf16 v[28:31], v[132:135], v[214:217], v[28:31]
	v_mfma_f32_16x16x32_bf16 v[24:27], v[168:171], v[214:217], v[24:27]
	v_mfma_f32_16x16x32_bf16 v[12:15], v[132:135], v[222:225], v[12:15]
	v_mfma_f32_16x16x32_bf16 v[8:11], v[168:171], v[222:225], v[8:11]
	s_setprio 0
	s_setprio 1
	v_mfma_f32_16x16x32_bf16 v[52:55], v[172:175], v[194:197], v[52:55]
	v_mfma_f32_16x16x32_bf16 v[48:51], v[180:183], v[194:197], v[48:51]
	v_mfma_f32_16x16x32_bf16 v[36:39], v[172:175], v[202:205], v[36:39]
	v_mfma_f32_16x16x32_bf16 v[32:35], v[180:183], v[202:205], v[32:35]
	v_mfma_f32_16x16x32_bf16 v[20:23], v[172:175], v[210:213], v[20:23]
	v_mfma_f32_16x16x32_bf16 v[16:19], v[180:183], v[210:213], v[16:19]
	v_mfma_f32_16x16x32_bf16 v[4:7], v[172:175], v[218:221], v[4:7]
	v_mfma_f32_16x16x32_bf16 v[0:3], v[180:183], v[218:221], v[0:3]
	v_mfma_f32_16x16x32_bf16 v[52:55], v[176:179], v[198:201], v[52:55]
	v_mfma_f32_16x16x32_bf16 v[48:51], v[190:193], v[198:201], v[48:51]
	v_mfma_f32_16x16x32_bf16 v[36:39], v[176:179], v[206:209], v[36:39]
	v_mfma_f32_16x16x32_bf16 v[32:35], v[190:193], v[206:209], v[32:35]
	v_mfma_f32_16x16x32_bf16 v[20:23], v[176:179], v[214:217], v[20:23]
	v_mfma_f32_16x16x32_bf16 v[16:19], v[190:193], v[214:217], v[16:19]
	v_mfma_f32_16x16x32_bf16 v[4:7], v[176:179], v[222:225], v[4:7]
	v_mfma_f32_16x16x32_bf16 v[0:3], v[190:193], v[222:225], v[0:3]
	s_barrier
	s_setprio 0
	s_add_i32 s13, 0, 0x18000
	s_add_i32 s33, 0, 0x1c000
	s_add_u32 s40, s40, 0x80000
	s_addc_u32 s41, s41, 0
	s_mov_b32 m0, s9
	v_lshl_add_u64 v[234:235], s[40:41], 0, v[136:137]
	global_load_lds_dwordx4 v[234:235], off
	v_lshl_add_u64 v[234:235], s[40:41], 0, v[140:141]
	s_mov_b32 m0, s35
	s_nop 0
	global_load_lds_dwordx4 v[234:235], off
	v_add_u32_e32 v144, s13, v157
	ds_read_b128 v[128:131], v144
	ds_read_b128 v[132:135], v144 offset:1024
	ds_read_b128 v[164:167], v144 offset:2048
	ds_read_b128 v[168:171], v144 offset:3072
	v_add_u32_e32 v144, s33, v157
	ds_read_b128 v[172:175], v144
	ds_read_b128 v[176:179], v144 offset:1024
	ds_read_b128 v[180:183], v144 offset:2048
	ds_read_b128 v[190:193], v144 offset:3072
	ds_read_b128 v[194:197], v161 offset:32768
	ds_read_b128 v[198:201], v161 offset:33792
	ds_read_b128 v[202:205], v161 offset:34816
	ds_read_b128 v[206:209], v161 offset:35840
	ds_read_b128 v[210:213], v161 offset:36864
	ds_read_b128 v[214:217], v161 offset:37888
	ds_read_b128 v[218:221], v161 offset:38912
	ds_read_b128 v[222:225], v161 offset:39936
	s_waitcnt vmcnt(8)
	s_waitcnt lgkmcnt(0)
	s_setprio 1
	s_barrier
	v_mfma_f32_16x16x32_bf16 v[124:127], v[128:131], v[194:197], v[124:127]
	v_mfma_f32_16x16x32_bf16 v[120:123], v[164:167], v[194:197], v[120:123]
	v_mfma_f32_16x16x32_bf16 v[108:111], v[128:131], v[202:205], v[108:111]
	v_mfma_f32_16x16x32_bf16 v[104:107], v[164:167], v[202:205], v[104:107]
	v_mfma_f32_16x16x32_bf16 v[92:95], v[128:131], v[210:213], v[92:95]
	v_mfma_f32_16x16x32_bf16 v[88:91], v[164:167], v[210:213], v[88:91]
	v_mfma_f32_16x16x32_bf16 v[76:79], v[128:131], v[218:221], v[76:79]
	v_mfma_f32_16x16x32_bf16 v[72:75], v[164:167], v[218:221], v[72:75]
	v_mfma_f32_16x16x32_bf16 v[124:127], v[132:135], v[198:201], v[124:127]
	v_mfma_f32_16x16x32_bf16 v[120:123], v[168:171], v[198:201], v[120:123]
	v_mfma_f32_16x16x32_bf16 v[108:111], v[132:135], v[206:209], v[108:111]
	v_mfma_f32_16x16x32_bf16 v[104:107], v[168:171], v[206:209], v[104:107]
	v_mfma_f32_16x16x32_bf16 v[92:95], v[132:135], v[214:217], v[92:95]
	v_mfma_f32_16x16x32_bf16 v[88:91], v[168:171], v[214:217], v[88:91]
	v_mfma_f32_16x16x32_bf16 v[76:79], v[132:135], v[222:225], v[76:79]
	v_mfma_f32_16x16x32_bf16 v[72:75], v[168:171], v[222:225], v[72:75]
	s_setprio 0
	s_setprio 1
	v_mfma_f32_16x16x32_bf16 v[116:119], v[172:175], v[194:197], v[116:119]
	v_mfma_f32_16x16x32_bf16 v[112:115], v[180:183], v[194:197], v[112:115]
	v_mfma_f32_16x16x32_bf16 v[100:103], v[172:175], v[202:205], v[100:103]
	v_mfma_f32_16x16x32_bf16 v[96:99], v[180:183], v[202:205], v[96:99]
	v_mfma_f32_16x16x32_bf16 v[84:87], v[172:175], v[210:213], v[84:87]
	v_mfma_f32_16x16x32_bf16 v[80:83], v[180:183], v[210:213], v[80:83]
	v_mfma_f32_16x16x32_bf16 v[68:71], v[172:175], v[218:221], v[68:71]
	v_mfma_f32_16x16x32_bf16 v[64:67], v[180:183], v[218:221], v[64:67]
	v_mfma_f32_16x16x32_bf16 v[116:119], v[176:179], v[198:201], v[116:119]
	v_mfma_f32_16x16x32_bf16 v[112:115], v[190:193], v[198:201], v[112:115]
	v_mfma_f32_16x16x32_bf16 v[100:103], v[176:179], v[206:209], v[100:103]
	v_mfma_f32_16x16x32_bf16 v[96:99], v[190:193], v[206:209], v[96:99]
	v_mfma_f32_16x16x32_bf16 v[84:87], v[176:179], v[214:217], v[84:87]
	v_mfma_f32_16x16x32_bf16 v[80:83], v[190:193], v[214:217], v[80:83]
	v_mfma_f32_16x16x32_bf16 v[68:71], v[176:179], v[222:225], v[68:71]
	v_mfma_f32_16x16x32_bf16 v[64:67], v[190:193], v[222:225], v[64:67]
	s_barrier
; #define PG8_STAGE(bufoff, gbase, voff) do { _Pragma("unroll") for (int _i = 0; _i < 2; ++_i) \
;         __builtin_amdgcn_global_load_lds((const unsigned*)((const char*)(gbase) + (voff)[_i]), (PG8_LAS unsigned*)(lds + (bufoff) + ldsw + _i * 8192), 16, 0, 0); } while (0)
; #define PG8_LDA(dst, b, h) do { _Pragma("unroll") for (int m = 0; m < 4; ++m) _Pragma("unroll") for (int k = 0; k < 2; ++k) dst[m][k] = *(const PG8_LAS bf16x8*)(lds + PG8_SA(b, h) + aoff + m * 2048 + k * 1024); } while (0)
; #define PG8_MMA(ai, bj, At, Bt) do { __builtin_amdgcn_s_setprio(1); _Pragma("unroll") for (int m = 0; m < 4; ++m) _Pragma("unroll") for (int n = 0; n < 2; ++n) _Pragma("unroll") for (int k = 0; k < 2; ++k) \
;         acc[ai][bj][m][n] = __builtin_amdgcn_mfma_f32_16x16x32_bf16(Bt[n][k], At[m][k], acc[ai][bj][m][n], 0, 0, 0); __builtin_amdgcn_s_setprio(0); } while (0)
; #define PG8_WAIT_V(n) asm volatile("s_waitcnt vmcnt(" #n ")" ::: "memory")
; #define PG8_WAIT_L(n) asm volatile("s_waitcnt lgkmcnt(" #n ")" ::: "memory")
; #define PG8_BAR __builtin_amdgcn_s_barrier()
; #define PG8_SCHED __builtin_amdgcn_sched_barrier(0)
; template <class Epi, class Sched, bool ALIGN_EPI = false, bool SP2 = false>
; __device__ __forceinline__ void gemm_phase(PG8_LAS unsigned char* lds, const Gemm g, const Sched& S, const Epi& E) {
;     ...
;         for (int t = 0; t < nt; t += 2) {
;             const bool last = (t == nt - 2);
;     ...
;             PG8_LDA(At, 1, 1); PG8_STAGE(PG8_SB(1, 0), b3, voffB); PG8_STAGE(PG8_SB(1, 1), b3 + hstepB, voffB); PG8_STAGE(PG8_SA(1, 0), a3, voffA);
;             PG8_WAIT_V(8); PG8_WAIT_L(0); PG8_BAR; PG8_MMA(1, 0, At, B0); PG8_MMA(1, 1, At, B1); PG8_BAR; PG8_SCHED;
	s_setprio 0
	s_add_i32 s13, s13, s6
	v_lshl_add_u64 v[226:227], v[226:227], 0, s[54:55]
	s_mov_b32 m0, s13
	s_nop 0
	global_load_lds_dwordx4 v[226:227], off
	s_add_i32 m0, s13, 0x2000
	s_add_u32 s38, s38, 0x80080
	v_lshl_add_u64 v[226:227], v[228:229], 0, s[54:55]
	s_addc_u32 s39, s39, 0
	s_add_i32 s13, s33, s6
	global_load_lds_dwordx4 v[226:227], off
	v_lshl_add_u64 v[226:227], s[38:39], 0, v[138:139]
	s_mov_b32 m0, s13
	s_nop 0
	global_load_lds_dwordx4 v[226:227], off
	v_lshl_add_u64 v[226:227], s[38:39], 0, v[142:143]
	s_add_i32 m0, s13, 0x2000
	s_nop 0
	global_load_lds_dwordx4 v[226:227], off
	v_lshl_add_u64 v[226:227], v[230:231], 0, s[54:55]
	s_mov_b32 m0, s51
	s_nop 0
	global_load_lds_dwordx4 v[226:227], off
	v_lshl_add_u64 v[226:227], v[232:233], 0, s[54:55]
	s_mov_b32 m0, s68
	s_nop 0
	global_load_lds_dwordx4 v[226:227], off
	ds_read_b128 v[194:197], v161 offset:49152
	ds_read_b128 v[198:201], v161 offset:50176
	ds_read_b128 v[202:205], v161 offset:51200
	ds_read_b128 v[206:209], v161 offset:52224
	ds_read_b128 v[210:213], v161 offset:53248
	ds_read_b128 v[214:217], v161 offset:54272
	ds_read_b128 v[218:221], v161 offset:55296
	ds_read_b128 v[222:225], v161 offset:56320
	s_waitcnt vmcnt(8)
	s_waitcnt lgkmcnt(0)
	s_setprio 1
	s_barrier
	v_mfma_f32_16x16x32_bf16 v[60:63], v[128:131], v[194:197], v[60:63]
	v_mfma_f32_16x16x32_bf16 v[56:59], v[164:167], v[194:197], v[56:59]
	v_mfma_f32_16x16x32_bf16 v[44:47], v[128:131], v[202:205], v[44:47]
	v_mfma_f32_16x16x32_bf16 v[40:43], v[164:167], v[202:205], v[40:43]
	v_mfma_f32_16x16x32_bf16 v[28:31], v[128:131], v[210:213], v[28:31]
	v_mfma_f32_16x16x32_bf16 v[24:27], v[164:167], v[210:213], v[24:27]
	v_mfma_f32_16x16x32_bf16 v[12:15], v[128:131], v[218:221], v[12:15]
	v_mfma_f32_16x16x32_bf16 v[8:11], v[164:167], v[218:221], v[8:11]
	v_mfma_f32_16x16x32_bf16 v[60:63], v[132:135], v[198:201], v[60:63]
	v_mfma_f32_16x16x32_bf16 v[56:59], v[168:171], v[198:201], v[56:59]
	v_mfma_f32_16x16x32_bf16 v[44:47], v[132:135], v[206:209], v[44:47]
	v_mfma_f32_16x16x32_bf16 v[40:43], v[168:171], v[206:209], v[40:43]
	v_mfma_f32_16x16x32_bf16 v[28:31], v[132:135], v[214:217], v[28:31]
	v_mfma_f32_16x16x32_bf16 v[24:27], v[168:171], v[214:217], v[24:27]
	v_mfma_f32_16x16x32_bf16 v[12:15], v[132:135], v[222:225], v[12:15]
	v_mfma_f32_16x16x32_bf16 v[8:11], v[168:171], v[222:225], v[8:11]
	s_setprio 0
	s_setprio 1
	v_mfma_f32_16x16x32_bf16 v[52:55], v[172:175], v[194:197], v[52:55]
	v_mfma_f32_16x16x32_bf16 v[48:51], v[180:183], v[194:197], v[48:51]
	v_mfma_f32_16x16x32_bf16 v[36:39], v[172:175], v[202:205], v[36:39]
	v_mfma_f32_16x16x32_bf16 v[32:35], v[180:183], v[202:205], v[32:35]
	v_mfma_f32_16x16x32_bf16 v[20:23], v[172:175], v[210:213], v[20:23]
	v_mfma_f32_16x16x32_bf16 v[16:19], v[180:183], v[210:213], v[16:19]
	v_mfma_f32_16x16x32_bf16 v[4:7], v[172:175], v[218:221], v[4:7]
	v_mfma_f32_16x16x32_bf16 v[0:3], v[180:183], v[218:221], v[0:3]
	v_mfma_f32_16x16x32_bf16 v[52:55], v[176:179], v[198:201], v[52:55]
	v_mfma_f32_16x16x32_bf16 v[48:51], v[190:193], v[198:201], v[48:51]
	v_mfma_f32_16x16x32_bf16 v[36:39], v[176:179], v[206:209], v[36:39]
	v_mfma_f32_16x16x32_bf16 v[32:35], v[190:193], v[206:209], v[32:35]
	v_mfma_f32_16x16x32_bf16 v[20:23], v[176:179], v[214:217], v[20:23]
	v_mfma_f32_16x16x32_bf16 v[16:19], v[190:193], v[214:217], v[16:19]
	v_mfma_f32_16x16x32_bf16 v[4:7], v[176:179], v[222:225], v[4:7]
	v_mfma_f32_16x16x32_bf16 v[0:3], v[190:193], v[222:225], v[0:3]
	s_barrier
	s_setprio 0
	s_add_i32 s12, s12, 2
	s_add_u32 s20, s20, 0x100
	s_addc_u32 s21, s21, 0
	s_add_u32 s10, s10, 0x100
	s_addc_u32 s11, s11, 0
	s_cmp_gt_u32 s12, 29
	s_cbranch_scc0 .LBB0_2050
	s_and_b64 vcc, exec, s[56:57]
	s_cbranch_vccz .LBB0_2053
	s_barrier

; #define PG8_STAGE(bufoff, gbase, voff) do { _Pragma("unroll") for (int _i = 0; _i < 2; ++_i) \
;         __builtin_amdgcn_global_load_lds((const unsigned*)((const char*)(gbase) + (voff)[_i]), (PG8_LAS unsigned*)(lds + (bufoff) + ldsw + _i * 8192), 16, 0, 0); } while (0)
; #define PG8_LDA(dst, b, h) do { _Pragma("unroll") for (int m = 0; m < 4; ++m) _Pragma("unroll") for (int k = 0; k < 2; ++k) dst[m][k] = *(const PG8_LAS bf16x8*)(lds + PG8_SA(b, h) + aoff + m * 2048 + k * 1024); } while (0)
; #define PG8_LDB(dst, b, h) do { _Pragma("unroll") for (int n = 0; n < 2; ++n) _Pragma("unroll") for (int k = 0; k < 2; ++k) dst[n][k] = *(const PG8_LAS bf16x8*)(lds + PG8_SB(b, h) + boff + n * 2048 + k * 1024); } while (0)
; #define PG8_MMA(ai, bj, At, Bt) do { __builtin_amdgcn_s_setprio(1); _Pragma("unroll") for (int m = 0; m < 4; ++m) _Pragma("unroll") for (int n = 0; n < 2; ++n) _Pragma("unroll") for (int k = 0; k < 2; ++k) \
;         acc[ai][bj][m][n] = __builtin_amdgcn_mfma_f32_16x16x32_bf16(Bt[n][k], At[m][k], acc[ai][bj][m][n], 0, 0, 0); __builtin_amdgcn_s_setprio(0); } while (0)
; #define PG8_WAIT_V(n) asm volatile("s_waitcnt vmcnt(" #n ")" ::: "memory")
; #define PG8_BAR __builtin_amdgcn_s_barrier()
; template <class Epi, class Sched, bool ALIGN_EPI = false, bool SP2 = false>
; __device__ __forceinline__ void gemm_phase(PG8_LAS unsigned char* lds, const Gemm g, const Sched& S, const Epi& E) {
;     ...
;         for (int t = 0; t < nt; t += 2) {
;             const bool last = (t == nt - 2);
;             const char* a1 = cA + (size_t)(t + 1) * kstA;
;             const char* a2 = last ? nA : cA + (size_t)(t + 2) * kstA; const char* b2 = last ? nB : cB + (size_t)(t + 2) * kstep;
;             const char* a3 = a2 + kstA; const char* b3 = b2 + kstep;
;             if (last && has_next) S.a_ready(nxt);
;             if constexpr (SP2) {
;             PG8_LDB(B0, 0, 0); PG8_LDB(B1, 0, 1); PG8_SCHED; PG8_LDA(At, 0, 0); PG8_STAGE(PG8_SA(1, 1), a1 + hstepA, voffA);
;             PG8_WAIT_V(8); PG8_WAIT_L(0); PG8_BAR; PG8_MMA(0, 0, At, B0); PG8_MMA(0, 1, At, B1); PG8_BAR; PG8_SCHED;
;             PG8_LDA(At, 0, 1); PG8_STAGE(PG8_SB(0, 0), b2, voffB); PG8_STAGE(PG8_SB(0, 1), b2 + hstepB, voffB); PG8_STAGE(PG8_SA(0, 0), a2, voffA);
;             PG8_WAIT_V(8); PG8_WAIT_L(0); PG8_BAR; PG8_MMA(1, 0, At, B0); PG8_MMA(1, 1, At, B1); PG8_BAR; PG8_SCHED;
.LBB0_2749:
	s_add_u32 s4, s46, s62
	s_addc_u32 s5, s47, s63
	s_add_u32 s12, s48, s62
	s_addc_u32 s13, s49, s63
	s_cmp_eq_u32 s7, s1
	s_cselect_b32 s67, s59, s5
	s_cselect_b32 s66, s58, s4
	s_cselect_b32 s65, s61, s13
	s_cselect_b32 s64, s60, s12
	v_lshl_add_u64 v[238:239], s[46:47], 0, v[130:131]
	s_add_i32 m0, s9, 0xc000
	s_nop 0
	global_load_lds_dwordx4 v[238:239], off
	v_lshl_add_u64 v[238:239], s[46:47], 0, v[128:129]
	s_add_i32 m0, s9, 0xe000
	s_nop 0
	global_load_lds_dwordx4 v[238:239], off
	v_add_u32_e32 v176, s77, v180
	v_add_u32_e32 v183, s84, v180
	ds_read_b128 v[132:135], v176
	ds_read_b128 v[136:139], v176 offset:1024
	ds_read_b128 v[140:143], v176 offset:2048
	ds_read_b128 v[176:179], v176 offset:3072
	ds_read_b128 v[190:193], v183
	ds_read_b128 v[194:197], v183 offset:1024
	ds_read_b128 v[198:201], v183 offset:2048
	ds_read_b128 v[202:205], v183 offset:3072
	ds_read_b128 v[206:209], v182
	ds_read_b128 v[210:213], v182 offset:1024
	ds_read_b128 v[214:217], v182 offset:2048
	ds_read_b128 v[218:221], v182 offset:3072
	ds_read_b128 v[222:225], v182 offset:4096
	ds_read_b128 v[226:229], v182 offset:5120
	ds_read_b128 v[230:233], v182 offset:6144
	ds_read_b128 v[234:237], v182 offset:7168
	s_waitcnt vmcnt(8)
	s_waitcnt lgkmcnt(0)
	s_setprio 1
	s_barrier
	v_mfma_f32_16x16x32_bf16 v[124:127], v[132:135], v[206:209], v[124:127]
	v_mfma_f32_16x16x32_bf16 v[120:123], v[140:143], v[206:209], v[120:123]
	v_mfma_f32_16x16x32_bf16 v[116:119], v[132:135], v[214:217], v[116:119]
	v_mfma_f32_16x16x32_bf16 v[112:115], v[140:143], v[214:217], v[112:115]
	v_mfma_f32_16x16x32_bf16 v[108:111], v[132:135], v[222:225], v[108:111]
	v_mfma_f32_16x16x32_bf16 v[104:107], v[140:143], v[222:225], v[104:107]
	v_mfma_f32_16x16x32_bf16 v[100:103], v[132:135], v[230:233], v[100:103]
	v_mfma_f32_16x16x32_bf16 v[96:99], v[140:143], v[230:233], v[96:99]
	v_mfma_f32_16x16x32_bf16 v[124:127], v[136:139], v[210:213], v[124:127]
	v_mfma_f32_16x16x32_bf16 v[120:123], v[176:179], v[210:213], v[120:123]
	v_mfma_f32_16x16x32_bf16 v[116:119], v[136:139], v[218:221], v[116:119]
	v_mfma_f32_16x16x32_bf16 v[112:115], v[176:179], v[218:221], v[112:115]
	v_mfma_f32_16x16x32_bf16 v[108:111], v[136:139], v[226:229], v[108:111]
	v_mfma_f32_16x16x32_bf16 v[104:107], v[176:179], v[226:229], v[104:107]
	v_mfma_f32_16x16x32_bf16 v[100:103], v[136:139], v[234:237], v[100:103]
	v_mfma_f32_16x16x32_bf16 v[96:99], v[176:179], v[234:237], v[96:99]
	s_setprio 0
	s_setprio 1
	v_mfma_f32_16x16x32_bf16 v[92:95], v[190:193], v[206:209], v[92:95]
	v_mfma_f32_16x16x32_bf16 v[88:91], v[198:201], v[206:209], v[88:91]
	v_mfma_f32_16x16x32_bf16 v[84:87], v[190:193], v[214:217], v[84:87]
	v_mfma_f32_16x16x32_bf16 v[80:83], v[198:201], v[214:217], v[80:83]
	v_mfma_f32_16x16x32_bf16 v[76:79], v[190:193], v[222:225], v[76:79]
	v_mfma_f32_16x16x32_bf16 v[72:75], v[198:201], v[222:225], v[72:75]
	v_mfma_f32_16x16x32_bf16 v[68:71], v[190:193], v[230:233], v[68:71]
	v_mfma_f32_16x16x32_bf16 v[64:67], v[198:201], v[230:233], v[64:67]
	v_mfma_f32_16x16x32_bf16 v[92:95], v[194:197], v[210:213], v[92:95]
	v_mfma_f32_16x16x32_bf16 v[88:91], v[202:205], v[210:213], v[88:91]
	v_mfma_f32_16x16x32_bf16 v[84:87], v[194:197], v[218:221], v[84:87]
	v_mfma_f32_16x16x32_bf16 v[80:83], v[202:205], v[218:221], v[80:83]
	v_mfma_f32_16x16x32_bf16 v[76:79], v[194:197], v[226:229], v[76:79]
	v_mfma_f32_16x16x32_bf16 v[72:75], v[202:205], v[226:229], v[72:75]
	v_mfma_f32_16x16x32_bf16 v[68:71], v[194:197], v[234:237], v[68:71]
	v_mfma_f32_16x16x32_bf16 v[64:67], v[202:205], v[234:237], v[64:67]
	s_barrier
	s_setprio 0
	s_add_i32 s4, s77, s8
	v_lshl_add_u64 v[238:239], s[64:65], 0, v[146:147]
	s_mov_b32 m0, s4
	s_nop 0
	global_load_lds_dwordx4 v[238:239], off
	s_add_i32 m0, s4, 0x2000
	s_add_u32 s4, s64, 0x80000
	v_lshl_add_u64 v[240:241], s[64:65], 0, v[150:151]
	s_addc_u32 s5, s65, 0
	s_add_i32 s12, s84, s8
	global_load_lds_dwordx4 v[240:241], off
	v_lshl_add_u64 v[242:243], s[4:5], 0, v[146:147]
	s_mov_b32 m0, s12
	v_lshl_add_u64 v[244:245], s[66:67], 0, v[148:149]
	global_load_lds_dwordx4 v[242:243], off
	v_lshl_add_u64 v[242:243], s[4:5], 0, v[150:151]
	s_add_i32 m0, s12, 0x2000
	s_nop 0
	global_load_lds_dwordx4 v[242:243], off
	v_lshl_add_u64 v[242:243], s[66:67], 0, v[144:145]
	s_mov_b32 m0, s9
	s_nop 0
	global_load_lds_dwordx4 v[242:243], off
	s_mov_b32 m0, s37
	s_nop 0
	global_load_lds_dwordx4 v[244:245], off
	ds_read_b128 v[206:209], v182 offset:16384
	ds_read_b128 v[210:213], v182 offset:17408
	ds_read_b128 v[214:217], v182 offset:18432
	ds_read_b128 v[218:221], v182 offset:19456
	ds_read_b128 v[222:225], v182 offset:20480
	ds_read_b128 v[226:229], v182 offset:21504
	ds_read_b128 v[230:233], v182 offset:22528
	ds_read_b128 v[234:237], v182 offset:23552
	s_waitcnt vmcnt(8)
	s_waitcnt lgkmcnt(0)
	s_setprio 1
	s_barrier
; #define PG8_STAGE(bufoff, gbase, voff) do { _Pragma("unroll") for (int _i = 0; _i < 2; ++_i) \
;         __builtin_amdgcn_global_load_lds((const unsigned*)((const char*)(gbase) + (voff)[_i]), (PG8_LAS unsigned*)(lds + (bufoff) + ldsw + _i * 8192), 16, 0, 0); } while (0)
; #define PG8_LDA(dst, b, h) do { _Pragma("unroll") for (int m = 0; m < 4; ++m) _Pragma("unroll") for (int k = 0; k < 2; ++k) dst[m][k] = *(const PG8_LAS bf16x8*)(lds + PG8_SA(b, h) + aoff + m * 2048 + k * 1024); } while (0)
; #define PG8_LDB(dst, b, h) do { _Pragma("unroll") for (int n = 0; n < 2; ++n) _Pragma("unroll") for (int k = 0; k < 2; ++k) dst[n][k] = *(const PG8_LAS bf16x8*)(lds + PG8_SB(b, h) + boff + n * 2048 + k * 1024); } while (0)
; #define PG8_MMA(ai, bj, At, Bt) do { __builtin_amdgcn_s_setprio(1); _Pragma("unroll") for (int m = 0; m < 4; ++m) _Pragma("unroll") for (int n = 0; n < 2; ++n) _Pragma("unroll") for (int k = 0; k < 2; ++k) \
;         acc[ai][bj][m][n] = __builtin_amdgcn_mfma_f32_16x16x32_bf16(Bt[n][k], At[m][k], acc[ai][bj][m][n], 0, 0, 0); __builtin_amdgcn_s_setprio(0); } while (0)
; #define PG8_WAIT_V(n) asm volatile("s_waitcnt vmcnt(" #n ")" ::: "memory")
; #define PG8_WAIT_L(n) asm volatile("s_waitcnt lgkmcnt(" #n ")" ::: "memory")
; #define PG8_BAR __builtin_amdgcn_s_barrier()
; #define PG8_SCHED __builtin_amdgcn_sched_barrier(0)
; template <class Epi, class Sched, bool ALIGN_EPI = false, bool SP2 = false>
; __device__ __forceinline__ void gemm_phase(PG8_LAS unsigned char* lds, const Gemm g, const Sched& S, const Epi& E) {
;     ...
;             PG8_WAIT_V(8); PG8_WAIT_L(0); PG8_BAR; PG8_MMA(1, 0, At, B0); PG8_MMA(1, 1, At, B1); PG8_BAR; PG8_SCHED;
;             PG8_LDB(B0, 1, 0); PG8_LDB(B1, 1, 1); PG8_SCHED; PG8_LDA(At, 1, 0); PG8_STAGE(PG8_SA(0, 1), a2 + hstepA, voffA);
;             PG8_WAIT_V(8); PG8_WAIT_L(0); PG8_BAR; PG8_MMA(0, 0, At, B0); PG8_MMA(0, 1, At, B1); PG8_BAR; PG8_SCHED;
	v_mfma_f32_16x16x32_bf16 v[60:63], v[132:135], v[206:209], v[60:63]
	v_mfma_f32_16x16x32_bf16 v[56:59], v[140:143], v[206:209], v[56:59]
	v_mfma_f32_16x16x32_bf16 v[52:55], v[132:135], v[214:217], v[52:55]
	v_mfma_f32_16x16x32_bf16 v[48:51], v[140:143], v[214:217], v[48:51]
	v_mfma_f32_16x16x32_bf16 v[44:47], v[132:135], v[222:225], v[44:47]
	v_mfma_f32_16x16x32_bf16 v[40:43], v[140:143], v[222:225], v[40:43]
	v_mfma_f32_16x16x32_bf16 v[36:39], v[132:135], v[230:233], v[36:39]
	v_mfma_f32_16x16x32_bf16 v[32:35], v[140:143], v[230:233], v[32:35]
	v_mfma_f32_16x16x32_bf16 v[60:63], v[136:139], v[210:213], v[60:63]
	v_mfma_f32_16x16x32_bf16 v[56:59], v[176:179], v[210:213], v[56:59]
	v_mfma_f32_16x16x32_bf16 v[52:55], v[136:139], v[218:221], v[52:55]
	v_mfma_f32_16x16x32_bf16 v[48:51], v[176:179], v[218:221], v[48:51]
	v_mfma_f32_16x16x32_bf16 v[44:47], v[136:139], v[226:229], v[44:47]
	v_mfma_f32_16x16x32_bf16 v[40:43], v[176:179], v[226:229], v[40:43]
	v_mfma_f32_16x16x32_bf16 v[36:39], v[136:139], v[234:237], v[36:39]
	v_mfma_f32_16x16x32_bf16 v[32:35], v[176:179], v[234:237], v[32:35]
	s_setprio 0
	s_setprio 1
	v_mfma_f32_16x16x32_bf16 v[28:31], v[190:193], v[206:209], v[28:31]
	v_mfma_f32_16x16x32_bf16 v[24:27], v[198:201], v[206:209], v[24:27]
	v_mfma_f32_16x16x32_bf16 v[20:23], v[190:193], v[214:217], v[20:23]
	v_mfma_f32_16x16x32_bf16 v[16:19], v[198:201], v[214:217], v[16:19]
	v_mfma_f32_16x16x32_bf16 v[12:15], v[190:193], v[222:225], v[12:15]
	v_mfma_f32_16x16x32_bf16 v[8:11], v[198:201], v[222:225], v[8:11]
	v_mfma_f32_16x16x32_bf16 v[4:7], v[190:193], v[230:233], v[4:7]
	v_mfma_f32_16x16x32_bf16 v[0:3], v[198:201], v[230:233], v[0:3]
	v_mfma_f32_16x16x32_bf16 v[28:31], v[194:197], v[210:213], v[28:31]
	v_mfma_f32_16x16x32_bf16 v[24:27], v[202:205], v[210:213], v[24:27]
	v_mfma_f32_16x16x32_bf16 v[20:23], v[194:197], v[218:221], v[20:23]
	v_mfma_f32_16x16x32_bf16 v[16:19], v[202:205], v[218:221], v[16:19]
	v_mfma_f32_16x16x32_bf16 v[12:15], v[194:197], v[226:229], v[12:15]
	v_mfma_f32_16x16x32_bf16 v[8:11], v[202:205], v[226:229], v[8:11]
	v_mfma_f32_16x16x32_bf16 v[4:7], v[194:197], v[234:237], v[4:7]
	v_mfma_f32_16x16x32_bf16 v[0:3], v[202:205], v[234:237], v[0:3]
	s_barrier
	s_setprio 0
	s_add_i32 s12, 0, 0x18000
	s_add_i32 s13, 0, 0x1c000
	s_add_u32 s4, s66, 0x80000
	s_addc_u32 s5, s67, 0
	s_mov_b32 m0, s70
	v_lshl_add_u64 v[246:247], s[4:5], 0, v[144:145]
	global_load_lds_dwordx4 v[246:247], off
	v_lshl_add_u64 v[246:247], s[4:5], 0, v[148:149]
	s_mov_b32 m0, s71
	s_nop 0
	global_load_lds_dwordx4 v[246:247], off
	v_add_u32_e32 v176, s12, v180
	v_add_u32_e32 v183, s13, v180
	ds_read_b128 v[132:135], v176
	ds_read_b128 v[136:139], v176 offset:1024
	ds_read_b128 v[140:143], v176 offset:2048
	ds_read_b128 v[176:179], v176 offset:3072
	ds_read_b128 v[190:193], v183
	ds_read_b128 v[194:197], v183 offset:1024
	ds_read_b128 v[198:201], v183 offset:2048
	ds_read_b128 v[202:205], v183 offset:3072
	ds_read_b128 v[206:209], v182 offset:32768
	ds_read_b128 v[210:213], v182 offset:33792
	ds_read_b128 v[214:217], v182 offset:34816
	ds_read_b128 v[218:221], v182 offset:35840
	ds_read_b128 v[222:225], v182 offset:36864
	ds_read_b128 v[226:229], v182 offset:37888
	ds_read_b128 v[230:233], v182 offset:38912
	ds_read_b128 v[234:237], v182 offset:39936
	s_waitcnt vmcnt(8)
	s_waitcnt lgkmcnt(0)
	s_setprio 1
	s_barrier
	v_mfma_f32_16x16x32_bf16 v[124:127], v[132:135], v[206:209], v[124:127]
	v_mfma_f32_16x16x32_bf16 v[120:123], v[140:143], v[206:209], v[120:123]
	v_mfma_f32_16x16x32_bf16 v[116:119], v[132:135], v[214:217], v[116:119]
	v_mfma_f32_16x16x32_bf16 v[112:115], v[140:143], v[214:217], v[112:115]
	v_mfma_f32_16x16x32_bf16 v[108:111], v[132:135], v[222:225], v[108:111]
	v_mfma_f32_16x16x32_bf16 v[104:107], v[140:143], v[222:225], v[104:107]
	v_mfma_f32_16x16x32_bf16 v[100:103], v[132:135], v[230:233], v[100:103]
	v_mfma_f32_16x16x32_bf16 v[96:99], v[140:143], v[230:233], v[96:99]
	v_mfma_f32_16x16x32_bf16 v[124:127], v[136:139], v[210:213], v[124:127]
	v_mfma_f32_16x16x32_bf16 v[120:123], v[176:179], v[210:213], v[120:123]
	v_mfma_f32_16x16x32_bf16 v[116:119], v[136:139], v[218:221], v[116:119]
	v_mfma_f32_16x16x32_bf16 v[112:115], v[176:179], v[218:221], v[112:115]
	v_mfma_f32_16x16x32_bf16 v[108:111], v[136:139], v[226:229], v[108:111]
	v_mfma_f32_16x16x32_bf16 v[104:107], v[176:179], v[226:229], v[104:107]
	v_mfma_f32_16x16x32_bf16 v[100:103], v[136:139], v[234:237], v[100:103]
	v_mfma_f32_16x16x32_bf16 v[96:99], v[176:179], v[234:237], v[96:99]
	s_setprio 0
	s_setprio 1
	v_mfma_f32_16x16x32_bf16 v[92:95], v[190:193], v[206:209], v[92:95]
	v_mfma_f32_16x16x32_bf16 v[88:91], v[198:201], v[206:209], v[88:91]
	v_mfma_f32_16x16x32_bf16 v[84:87], v[190:193], v[214:217], v[84:87]
	v_mfma_f32_16x16x32_bf16 v[80:83], v[198:201], v[214:217], v[80:83]
	v_mfma_f32_16x16x32_bf16 v[76:79], v[190:193], v[222:225], v[76:79]
	v_mfma_f32_16x16x32_bf16 v[72:75], v[198:201], v[222:225], v[72:75]
	v_mfma_f32_16x16x32_bf16 v[68:71], v[190:193], v[230:233], v[68:71]
	v_mfma_f32_16x16x32_bf16 v[64:67], v[198:201], v[230:233], v[64:67]
	v_mfma_f32_16x16x32_bf16 v[92:95], v[194:197], v[210:213], v[92:95]
	v_mfma_f32_16x16x32_bf16 v[88:91], v[202:205], v[210:213], v[88:91]
	v_mfma_f32_16x16x32_bf16 v[84:87], v[194:197], v[218:221], v[84:87]
	v_mfma_f32_16x16x32_bf16 v[80:83], v[202:205], v[218:221], v[80:83]
	v_mfma_f32_16x16x32_bf16 v[76:79], v[194:197], v[226:229], v[76:79]
	v_mfma_f32_16x16x32_bf16 v[72:75], v[202:205], v[226:229], v[72:75]
	v_mfma_f32_16x16x32_bf16 v[68:71], v[194:197], v[234:237], v[68:71]
	v_mfma_f32_16x16x32_bf16 v[64:67], v[202:205], v[234:237], v[64:67]
	s_barrier
; #define PG8_STAGE(bufoff, gbase, voff) do { _Pragma("unroll") for (int _i = 0; _i < 2; ++_i) \
;         __builtin_amdgcn_global_load_lds((const unsigned*)((const char*)(gbase) + (voff)[_i]), (PG8_LAS unsigned*)(lds + (bufoff) + ldsw + _i * 8192), 16, 0, 0); } while (0)
; #define PG8_LDA(dst, b, h) do { _Pragma("unroll") for (int m = 0; m < 4; ++m) _Pragma("unroll") for (int k = 0; k < 2; ++k) dst[m][k] = *(const PG8_LAS bf16x8*)(lds + PG8_SA(b, h) + aoff + m * 2048 + k * 1024); } while (0)
; #define PG8_MMA(ai, bj, At, Bt) do { __builtin_amdgcn_s_setprio(1); _Pragma("unroll") for (int m = 0; m < 4; ++m) _Pragma("unroll") for (int n = 0; n < 2; ++n) _Pragma("unroll") for (int k = 0; k < 2; ++k) \
;         acc[ai][bj][m][n] = __builtin_amdgcn_mfma_f32_16x16x32_bf16(Bt[n][k], At[m][k], acc[ai][bj][m][n], 0, 0, 0); __builtin_amdgcn_s_setprio(0); } while (0)
; #define PG8_WAIT_V(n) asm volatile("s_waitcnt vmcnt(" #n ")" ::: "memory")
; #define PG8_WAIT_L(n) asm volatile("s_waitcnt lgkmcnt(" #n ")" ::: "memory")
; #define PG8_BAR __builtin_amdgcn_s_barrier()
; #define PG8_SCHED __builtin_amdgcn_sched_barrier(0)
; template <class Epi, class Sched, bool ALIGN_EPI = false, bool SP2 = false>
; __device__ __forceinline__ void gemm_phase(PG8_LAS unsigned char* lds, const Gemm g, const Sched& S, const Epi& E) {
;     ...
;         for (int t = 0; t < nt; t += 2) {
;     ...
;             PG8_LDA(At, 1, 1); PG8_STAGE(PG8_SB(1, 0), b3, voffB); PG8_STAGE(PG8_SB(1, 1), b3 + hstepB, voffB); PG8_STAGE(PG8_SA(1, 0), a3, voffA);
;             PG8_WAIT_V(8); PG8_WAIT_L(0); PG8_BAR; PG8_MMA(1, 0, At, B0); PG8_MMA(1, 1, At, B1); PG8_BAR; PG8_SCHED;
	s_setprio 0
	s_add_i32 s4, s12, s8
	v_lshl_add_u64 v[238:239], v[238:239], 0, s[52:53]
	s_mov_b32 m0, s4
	s_nop 0
	global_load_lds_dwordx4 v[238:239], off
	s_add_i32 m0, s4, 0x2000
	s_add_u32 s4, s64, 0x80080
	v_lshl_add_u64 v[238:239], v[240:241], 0, s[52:53]
	s_addc_u32 s5, s65, 0
	s_add_i32 s12, s13, s8
	global_load_lds_dwordx4 v[238:239], off
	v_lshl_add_u64 v[238:239], s[4:5], 0, v[146:147]
	s_mov_b32 m0, s12
	s_nop 0
	global_load_lds_dwordx4 v[238:239], off
	v_lshl_add_u64 v[238:239], s[4:5], 0, v[150:151]
	s_add_i32 m0, s12, 0x2000
	s_nop 0
	global_load_lds_dwordx4 v[238:239], off
	v_lshl_add_u64 v[238:239], v[242:243], 0, s[52:53]
	s_mov_b32 m0, s74
	s_nop 0
	global_load_lds_dwordx4 v[238:239], off
	v_lshl_add_u64 v[238:239], v[244:245], 0, s[52:53]
	s_mov_b32 m0, s75
	s_nop 0
	global_load_lds_dwordx4 v[238:239], off
	ds_read_b128 v[206:209], v182 offset:49152
	ds_read_b128 v[210:213], v182 offset:50176
	ds_read_b128 v[214:217], v182 offset:51200
	ds_read_b128 v[218:221], v182 offset:52224
	ds_read_b128 v[222:225], v182 offset:53248
	ds_read_b128 v[226:229], v182 offset:54272
	ds_read_b128 v[230:233], v182 offset:55296
	ds_read_b128 v[234:237], v182 offset:56320
	s_waitcnt vmcnt(8)
	s_waitcnt lgkmcnt(0)
	s_setprio 1
	s_barrier
	v_mfma_f32_16x16x32_bf16 v[60:63], v[132:135], v[206:209], v[60:63]
	v_mfma_f32_16x16x32_bf16 v[56:59], v[140:143], v[206:209], v[56:59]
	v_mfma_f32_16x16x32_bf16 v[52:55], v[132:135], v[214:217], v[52:55]
	v_mfma_f32_16x16x32_bf16 v[48:51], v[140:143], v[214:217], v[48:51]
	v_mfma_f32_16x16x32_bf16 v[44:47], v[132:135], v[222:225], v[44:47]
	v_mfma_f32_16x16x32_bf16 v[40:43], v[140:143], v[222:225], v[40:43]
	v_mfma_f32_16x16x32_bf16 v[36:39], v[132:135], v[230:233], v[36:39]
	v_mfma_f32_16x16x32_bf16 v[32:35], v[140:143], v[230:233], v[32:35]
	v_mfma_f32_16x16x32_bf16 v[60:63], v[136:139], v[210:213], v[60:63]
	v_mfma_f32_16x16x32_bf16 v[56:59], v[176:179], v[210:213], v[56:59]
	v_mfma_f32_16x16x32_bf16 v[52:55], v[136:139], v[218:221], v[52:55]
	v_mfma_f32_16x16x32_bf16 v[48:51], v[176:179], v[218:221], v[48:51]
	v_mfma_f32_16x16x32_bf16 v[44:47], v[136:139], v[226:229], v[44:47]
	v_mfma_f32_16x16x32_bf16 v[40:43], v[176:179], v[226:229], v[40:43]
	v_mfma_f32_16x16x32_bf16 v[36:39], v[136:139], v[234:237], v[36:39]
	v_mfma_f32_16x16x32_bf16 v[32:35], v[176:179], v[234:237], v[32:35]
	s_setprio 0
	s_setprio 1
	v_mfma_f32_16x16x32_bf16 v[28:31], v[190:193], v[206:209], v[28:31]
	v_mfma_f32_16x16x32_bf16 v[24:27], v[198:201], v[206:209], v[24:27]
	v_mfma_f32_16x16x32_bf16 v[20:23], v[190:193], v[214:217], v[20:23]
	v_mfma_f32_16x16x32_bf16 v[16:19], v[198:201], v[214:217], v[16:19]
	v_mfma_f32_16x16x32_bf16 v[12:15], v[190:193], v[222:225], v[12:15]
	v_mfma_f32_16x16x32_bf16 v[8:11], v[198:201], v[222:225], v[8:11]
	v_mfma_f32_16x16x32_bf16 v[4:7], v[190:193], v[230:233], v[4:7]
	v_mfma_f32_16x16x32_bf16 v[0:3], v[198:201], v[230:233], v[0:3]
	v_mfma_f32_16x16x32_bf16 v[28:31], v[194:197], v[210:213], v[28:31]
	v_mfma_f32_16x16x32_bf16 v[24:27], v[202:205], v[210:213], v[24:27]
	v_mfma_f32_16x16x32_bf16 v[20:23], v[194:197], v[218:221], v[20:23]
	v_mfma_f32_16x16x32_bf16 v[16:19], v[202:205], v[218:221], v[16:19]
	v_mfma_f32_16x16x32_bf16 v[12:15], v[194:197], v[226:229], v[12:15]
	v_mfma_f32_16x16x32_bf16 v[8:11], v[202:205], v[226:229], v[8:11]
	v_mfma_f32_16x16x32_bf16 v[4:7], v[194:197], v[234:237], v[4:7]
	v_mfma_f32_16x16x32_bf16 v[0:3], v[202:205], v[234:237], v[0:3]
	s_barrier
	s_setprio 0
	s_add_i32 s4, s1, 2
	s_add_u32 s62, s62, 0x100
	s_addc_u32 s63, s63, 0
	v_lshl_add_u64 v[130:131], v[130:131], 0, s[34:35]
	v_lshl_add_u64 v[128:129], v[128:129], 0, s[34:35]
	s_cmp_ge_i32 s1, s7
	s_mov_b32 s1, s4
	s_cbranch_scc0 .LBB0_2749
	s_and_b64 vcc, exec, s[54:55]
	s_cbranch_vccz .LBB0_2752
	s_barrier

; #define PG8_STAGE(bufoff, gbase, voff) do { _Pragma("unroll") for (int _i = 0; _i < 2; ++_i) \
;         __builtin_amdgcn_global_load_lds((const unsigned*)((const char*)(gbase) + (voff)[_i]), (PG8_LAS unsigned*)(lds + (bufoff) + ldsw + _i * 8192), 16, 0, 0); } while (0)
; #define PG8_LDA(dst, b, h) do { _Pragma("unroll") for (int m = 0; m < 4; ++m) _Pragma("unroll") for (int k = 0; k < 2; ++k) dst[m][k] = *(const PG8_LAS bf16x8*)(lds + PG8_SA(b, h) + aoff + m * 2048 + k * 1024); } while (0)
; #define PG8_LDB(dst, b, h) do { _Pragma("unroll") for (int n = 0; n < 2; ++n) _Pragma("unroll") for (int k = 0; k < 2; ++k) dst[n][k] = *(const PG8_LAS bf16x8*)(lds + PG8_SB(b, h) + boff + n * 2048 + k * 1024); } while (0)
; #define PG8_MMA(ai, bj, At, Bt) do { __builtin_amdgcn_s_setprio(1); _Pragma("unroll") for (int m = 0; m < 4; ++m) _Pragma("unroll") for (int n = 0; n < 2; ++n) _Pragma("unroll") for (int k = 0; k < 2; ++k) \
;         acc[ai][bj][m][n] = __builtin_amdgcn_mfma_f32_16x16x32_bf16(Bt[n][k], At[m][k], acc[ai][bj][m][n], 0, 0, 0); __builtin_amdgcn_s_setprio(0); } while (0)
; #define PG8_WAIT_V(n) asm volatile("s_waitcnt vmcnt(" #n ")" ::: "memory")
; #define PG8_BAR __builtin_amdgcn_s_barrier()
; template <class Epi, class Sched, bool ALIGN_EPI = false, bool SP2 = false>
; __device__ __forceinline__ void gemm_phase(PG8_LAS unsigned char* lds, const Gemm g, const Sched& S, const Epi& E) {
;     ...
;         for (int t = 0; t < nt; t += 2) {
;             const bool last = (t == nt - 2);
;             const char* a1 = cA + (size_t)(t + 1) * kstA;
;             const char* a2 = last ? nA : cA + (size_t)(t + 2) * kstA; const char* b2 = last ? nB : cB + (size_t)(t + 2) * kstep;
;             const char* a3 = a2 + kstA; const char* b3 = b2 + kstep;
;             if (last && has_next) S.a_ready(nxt);
;             if constexpr (SP2) {
;             PG8_LDB(B0, 0, 0); PG8_LDB(B1, 0, 1); PG8_SCHED; PG8_LDA(At, 0, 0); PG8_STAGE(PG8_SA(1, 1), a1 + hstepA, voffA);
;             PG8_WAIT_V(8); PG8_WAIT_L(0); PG8_BAR; PG8_MMA(0, 0, At, B0); PG8_MMA(0, 1, At, B1); PG8_BAR; PG8_SCHED;
;             PG8_LDA(At, 0, 1); PG8_STAGE(PG8_SB(0, 0), b2, voffB); PG8_STAGE(PG8_SB(0, 1), b2 + hstepB, voffB); PG8_STAGE(PG8_SA(0, 0), a2, voffA);
;             PG8_WAIT_V(8); PG8_WAIT_L(0); PG8_BAR; PG8_MMA(1, 0, At, B0); PG8_MMA(1, 1, At, B1); PG8_BAR; PG8_SCHED;
.LBB0_3058:
	s_add_u32 s42, s40, 0xfff80080
	s_addc_u32 s43, s41, -1
	s_cmp_eq_u32 s35, 28
	s_cselect_b32 s45, s4, s43
	s_cselect_b32 s44, s5, s42
	s_cselect_b32 s43, s12, s23
	s_cselect_b32 s42, s13, s21
	v_lshl_add_u64 v[226:227], s[40:41], 0, v[142:143]
	s_add_i32 m0, s8, 0xc000
	s_nop 0
	global_load_lds_dwordx4 v[226:227], off
	v_lshl_add_u64 v[226:227], s[40:41], 0, v[144:145]
	s_add_i32 m0, s8, 0xe000
	s_nop 0
	global_load_lds_dwordx4 v[226:227], off
	ds_read_b128 v[156:159], v152
	ds_read_b128 v[160:163], v152 offset:1024
	ds_read_b128 v[164:167], v152 offset:2048
	ds_read_b128 v[168:171], v152 offset:3072
	ds_read_b128 v[172:175], v153
	ds_read_b128 v[176:179], v153 offset:1024
	ds_read_b128 v[180:183], v153 offset:2048
	ds_read_b128 v[190:193], v153 offset:3072
	ds_read_b128 v[194:197], v154
	ds_read_b128 v[198:201], v154 offset:1024
	ds_read_b128 v[202:205], v154 offset:2048
	ds_read_b128 v[206:209], v154 offset:3072
	ds_read_b128 v[210:213], v154 offset:4096
	ds_read_b128 v[214:217], v154 offset:5120
	ds_read_b128 v[218:221], v154 offset:6144
	ds_read_b128 v[222:225], v154 offset:7168
	s_waitcnt vmcnt(8)
	s_waitcnt lgkmcnt(0)
	s_setprio 1
	s_barrier
	v_mfma_f32_16x16x32_bf16 v[124:127], v[156:159], v[194:197], v[124:127]
	v_mfma_f32_16x16x32_bf16 v[120:123], v[164:167], v[194:197], v[120:123]
	v_mfma_f32_16x16x32_bf16 v[108:111], v[156:159], v[202:205], v[108:111]
	v_mfma_f32_16x16x32_bf16 v[104:107], v[164:167], v[202:205], v[104:107]
	v_mfma_f32_16x16x32_bf16 v[92:95], v[156:159], v[210:213], v[92:95]
	v_mfma_f32_16x16x32_bf16 v[88:91], v[164:167], v[210:213], v[88:91]
	v_mfma_f32_16x16x32_bf16 v[76:79], v[156:159], v[218:221], v[76:79]
	v_mfma_f32_16x16x32_bf16 v[72:75], v[164:167], v[218:221], v[72:75]
	v_mfma_f32_16x16x32_bf16 v[124:127], v[160:163], v[198:201], v[124:127]
	v_mfma_f32_16x16x32_bf16 v[120:123], v[168:171], v[198:201], v[120:123]
	v_mfma_f32_16x16x32_bf16 v[108:111], v[160:163], v[206:209], v[108:111]
	v_mfma_f32_16x16x32_bf16 v[104:107], v[168:171], v[206:209], v[104:107]
	v_mfma_f32_16x16x32_bf16 v[92:95], v[160:163], v[214:217], v[92:95]
	v_mfma_f32_16x16x32_bf16 v[88:91], v[168:171], v[214:217], v[88:91]
	v_mfma_f32_16x16x32_bf16 v[76:79], v[160:163], v[222:225], v[76:79]
	v_mfma_f32_16x16x32_bf16 v[72:75], v[168:171], v[222:225], v[72:75]
	s_setprio 0
	s_setprio 1
	v_mfma_f32_16x16x32_bf16 v[116:119], v[172:175], v[194:197], v[116:119]
	v_mfma_f32_16x16x32_bf16 v[112:115], v[180:183], v[194:197], v[112:115]
	v_mfma_f32_16x16x32_bf16 v[100:103], v[172:175], v[202:205], v[100:103]
	v_mfma_f32_16x16x32_bf16 v[96:99], v[180:183], v[202:205], v[96:99]
	v_mfma_f32_16x16x32_bf16 v[84:87], v[172:175], v[210:213], v[84:87]
	v_mfma_f32_16x16x32_bf16 v[80:83], v[180:183], v[210:213], v[80:83]
	v_mfma_f32_16x16x32_bf16 v[68:71], v[172:175], v[218:221], v[68:71]
	v_mfma_f32_16x16x32_bf16 v[64:67], v[180:183], v[218:221], v[64:67]
	v_mfma_f32_16x16x32_bf16 v[116:119], v[176:179], v[198:201], v[116:119]
	v_mfma_f32_16x16x32_bf16 v[112:115], v[190:193], v[198:201], v[112:115]
	v_mfma_f32_16x16x32_bf16 v[100:103], v[176:179], v[206:209], v[100:103]
	v_mfma_f32_16x16x32_bf16 v[96:99], v[190:193], v[206:209], v[96:99]
	v_mfma_f32_16x16x32_bf16 v[84:87], v[176:179], v[214:217], v[84:87]
	v_mfma_f32_16x16x32_bf16 v[80:83], v[190:193], v[214:217], v[80:83]
	v_mfma_f32_16x16x32_bf16 v[68:71], v[176:179], v[222:225], v[68:71]
	v_mfma_f32_16x16x32_bf16 v[64:67], v[190:193], v[222:225], v[64:67]
	s_barrier
	s_setprio 0
	s_add_i32 s53, s50, s7
	v_lshl_add_u64 v[226:227], s[42:43], 0, v[130:131]
	s_mov_b32 m0, s53
	s_nop 0
	global_load_lds_dwordx4 v[226:227], off
	s_add_i32 m0, s53, 0x2000
	s_add_u32 s54, s42, 0x80000
	v_lshl_add_u64 v[228:229], s[42:43], 0, v[134:135]
	s_addc_u32 s55, s43, 0
	s_add_i32 s53, s51, s7
	global_load_lds_dwordx4 v[228:229], off
	v_lshl_add_u64 v[230:231], s[54:55], 0, v[130:131]
	s_mov_b32 m0, s53
	v_lshl_add_u64 v[232:233], s[44:45], 0, v[132:133]
	global_load_lds_dwordx4 v[230:231], off
	v_lshl_add_u64 v[230:231], s[54:55], 0, v[134:135]
	s_add_i32 m0, s53, 0x2000
	s_nop 0
	global_load_lds_dwordx4 v[230:231], off
	v_lshl_add_u64 v[230:231], s[44:45], 0, v[128:129]
	s_mov_b32 m0, s8
	s_nop 0
	global_load_lds_dwordx4 v[230:231], off
	s_mov_b32 m0, s9
	s_nop 0
	global_load_lds_dwordx4 v[232:233], off
	ds_read_b128 v[194:197], v154 offset:16384
	ds_read_b128 v[198:201], v154 offset:17408
	ds_read_b128 v[202:205], v154 offset:18432
	ds_read_b128 v[206:209], v154 offset:19456
	ds_read_b128 v[210:213], v154 offset:20480
	ds_read_b128 v[214:217], v154 offset:21504
	ds_read_b128 v[218:221], v154 offset:22528
	ds_read_b128 v[222:225], v154 offset:23552
	s_waitcnt vmcnt(8)
	s_waitcnt lgkmcnt(0)
	s_setprio 1
	s_barrier
; #define PG8_STAGE(bufoff, gbase, voff) do { _Pragma("unroll") for (int _i = 0; _i < 2; ++_i) \
;         __builtin_amdgcn_global_load_lds((const unsigned*)((const char*)(gbase) + (voff)[_i]), (PG8_LAS unsigned*)(lds + (bufoff) + ldsw + _i * 8192), 16, 0, 0); } while (0)
; #define PG8_LDA(dst, b, h) do { _Pragma("unroll") for (int m = 0; m < 4; ++m) _Pragma("unroll") for (int k = 0; k < 2; ++k) dst[m][k] = *(const PG8_LAS bf16x8*)(lds + PG8_SA(b, h) + aoff + m * 2048 + k * 1024); } while (0)
; #define PG8_LDB(dst, b, h) do { _Pragma("unroll") for (int n = 0; n < 2; ++n) _Pragma("unroll") for (int k = 0; k < 2; ++k) dst[n][k] = *(const PG8_LAS bf16x8*)(lds + PG8_SB(b, h) + boff + n * 2048 + k * 1024); } while (0)
; #define PG8_MMA(ai, bj, At, Bt) do { __builtin_amdgcn_s_setprio(1); _Pragma("unroll") for (int m = 0; m < 4; ++m) _Pragma("unroll") for (int n = 0; n < 2; ++n) _Pragma("unroll") for (int k = 0; k < 2; ++k) \
;         acc[ai][bj][m][n] = __builtin_amdgcn_mfma_f32_16x16x32_bf16(Bt[n][k], At[m][k], acc[ai][bj][m][n], 0, 0, 0); __builtin_amdgcn_s_setprio(0); } while (0)
; #define PG8_WAIT_V(n) asm volatile("s_waitcnt vmcnt(" #n ")" ::: "memory")
; #define PG8_WAIT_L(n) asm volatile("s_waitcnt lgkmcnt(" #n ")" ::: "memory")
; #define PG8_BAR __builtin_amdgcn_s_barrier()
; #define PG8_SCHED __builtin_amdgcn_sched_barrier(0)
; template <class Epi, class Sched, bool ALIGN_EPI = false, bool SP2 = false>
; __device__ __forceinline__ void gemm_phase(PG8_LAS unsigned char* lds, const Gemm g, const Sched& S, const Epi& E) {
;     ...
;             PG8_WAIT_V(8); PG8_WAIT_L(0); PG8_BAR; PG8_MMA(1, 0, At, B0); PG8_MMA(1, 1, At, B1); PG8_BAR; PG8_SCHED;
;             PG8_LDB(B0, 1, 0); PG8_LDB(B1, 1, 1); PG8_SCHED; PG8_LDA(At, 1, 0); PG8_STAGE(PG8_SA(0, 1), a2 + hstepA, voffA);
;             PG8_WAIT_V(8); PG8_WAIT_L(0); PG8_BAR; PG8_MMA(0, 0, At, B0); PG8_MMA(0, 1, At, B1); PG8_BAR; PG8_SCHED;
	v_mfma_f32_16x16x32_bf16 v[60:63], v[156:159], v[194:197], v[60:63]
	v_mfma_f32_16x16x32_bf16 v[56:59], v[164:167], v[194:197], v[56:59]
	v_mfma_f32_16x16x32_bf16 v[44:47], v[156:159], v[202:205], v[44:47]
	v_mfma_f32_16x16x32_bf16 v[40:43], v[164:167], v[202:205], v[40:43]
	v_mfma_f32_16x16x32_bf16 v[28:31], v[156:159], v[210:213], v[28:31]
	v_mfma_f32_16x16x32_bf16 v[24:27], v[164:167], v[210:213], v[24:27]
	v_mfma_f32_16x16x32_bf16 v[12:15], v[156:159], v[218:221], v[12:15]
	v_mfma_f32_16x16x32_bf16 v[8:11], v[164:167], v[218:221], v[8:11]
	v_mfma_f32_16x16x32_bf16 v[60:63], v[160:163], v[198:201], v[60:63]
	v_mfma_f32_16x16x32_bf16 v[56:59], v[168:171], v[198:201], v[56:59]
	v_mfma_f32_16x16x32_bf16 v[44:47], v[160:163], v[206:209], v[44:47]
	v_mfma_f32_16x16x32_bf16 v[40:43], v[168:171], v[206:209], v[40:43]
	v_mfma_f32_16x16x32_bf16 v[28:31], v[160:163], v[214:217], v[28:31]
	v_mfma_f32_16x16x32_bf16 v[24:27], v[168:171], v[214:217], v[24:27]
	v_mfma_f32_16x16x32_bf16 v[12:15], v[160:163], v[222:225], v[12:15]
	v_mfma_f32_16x16x32_bf16 v[8:11], v[168:171], v[222:225], v[8:11]
	s_setprio 0
	s_setprio 1
	v_mfma_f32_16x16x32_bf16 v[52:55], v[172:175], v[194:197], v[52:55]
	v_mfma_f32_16x16x32_bf16 v[48:51], v[180:183], v[194:197], v[48:51]
	v_mfma_f32_16x16x32_bf16 v[36:39], v[172:175], v[202:205], v[36:39]
	v_mfma_f32_16x16x32_bf16 v[32:35], v[180:183], v[202:205], v[32:35]
	v_mfma_f32_16x16x32_bf16 v[20:23], v[172:175], v[210:213], v[20:23]
	v_mfma_f32_16x16x32_bf16 v[16:19], v[180:183], v[210:213], v[16:19]
	v_mfma_f32_16x16x32_bf16 v[4:7], v[172:175], v[218:221], v[4:7]
	v_mfma_f32_16x16x32_bf16 v[0:3], v[180:183], v[218:221], v[0:3]
	v_mfma_f32_16x16x32_bf16 v[52:55], v[176:179], v[198:201], v[52:55]
	v_mfma_f32_16x16x32_bf16 v[48:51], v[190:193], v[198:201], v[48:51]
	v_mfma_f32_16x16x32_bf16 v[36:39], v[176:179], v[206:209], v[36:39]
	v_mfma_f32_16x16x32_bf16 v[32:35], v[190:193], v[206:209], v[32:35]
	v_mfma_f32_16x16x32_bf16 v[20:23], v[176:179], v[214:217], v[20:23]
	v_mfma_f32_16x16x32_bf16 v[16:19], v[190:193], v[214:217], v[16:19]
	v_mfma_f32_16x16x32_bf16 v[4:7], v[176:179], v[222:225], v[4:7]
	v_mfma_f32_16x16x32_bf16 v[0:3], v[190:193], v[222:225], v[0:3]
	s_barrier
	s_setprio 0
	s_add_i32 s53, 0, 0x18000
	s_add_i32 s54, 0, 0x1c000
	s_add_u32 s44, s44, 0x80000
	s_addc_u32 s45, s45, 0
	s_mov_b32 m0, s10
	v_lshl_add_u64 v[234:235], s[44:45], 0, v[128:129]
	global_load_lds_dwordx4 v[234:235], off
	v_lshl_add_u64 v[234:235], s[44:45], 0, v[132:133]
	s_mov_b32 m0, s11
	s_nop 0
	global_load_lds_dwordx4 v[234:235], off
	v_add_u32_e32 v155, s53, v150
	ds_read_b128 v[156:159], v155
	ds_read_b128 v[160:163], v155 offset:1024
	ds_read_b128 v[164:167], v155 offset:2048
	ds_read_b128 v[168:171], v155 offset:3072
	v_add_u32_e32 v155, s54, v150
	ds_read_b128 v[172:175], v155
	ds_read_b128 v[176:179], v155 offset:1024
	ds_read_b128 v[180:183], v155 offset:2048
	ds_read_b128 v[190:193], v155 offset:3072
	ds_read_b128 v[194:197], v154 offset:32768
	ds_read_b128 v[198:201], v154 offset:33792
	ds_read_b128 v[202:205], v154 offset:34816
	ds_read_b128 v[206:209], v154 offset:35840
	ds_read_b128 v[210:213], v154 offset:36864
	ds_read_b128 v[214:217], v154 offset:37888
	ds_read_b128 v[218:221], v154 offset:38912
	ds_read_b128 v[222:225], v154 offset:39936
	s_waitcnt vmcnt(8)
	s_waitcnt lgkmcnt(0)
	s_setprio 1
	s_barrier
	v_mfma_f32_16x16x32_bf16 v[124:127], v[156:159], v[194:197], v[124:127]
	v_mfma_f32_16x16x32_bf16 v[120:123], v[164:167], v[194:197], v[120:123]
	v_mfma_f32_16x16x32_bf16 v[108:111], v[156:159], v[202:205], v[108:111]
	v_mfma_f32_16x16x32_bf16 v[104:107], v[164:167], v[202:205], v[104:107]
	v_mfma_f32_16x16x32_bf16 v[92:95], v[156:159], v[210:213], v[92:95]
	v_mfma_f32_16x16x32_bf16 v[88:91], v[164:167], v[210:213], v[88:91]
	v_mfma_f32_16x16x32_bf16 v[76:79], v[156:159], v[218:221], v[76:79]
	v_mfma_f32_16x16x32_bf16 v[72:75], v[164:167], v[218:221], v[72:75]
	v_mfma_f32_16x16x32_bf16 v[124:127], v[160:163], v[198:201], v[124:127]
	v_mfma_f32_16x16x32_bf16 v[120:123], v[168:171], v[198:201], v[120:123]
	v_mfma_f32_16x16x32_bf16 v[108:111], v[160:163], v[206:209], v[108:111]
	v_mfma_f32_16x16x32_bf16 v[104:107], v[168:171], v[206:209], v[104:107]
	v_mfma_f32_16x16x32_bf16 v[92:95], v[160:163], v[214:217], v[92:95]
	v_mfma_f32_16x16x32_bf16 v[88:91], v[168:171], v[214:217], v[88:91]
	v_mfma_f32_16x16x32_bf16 v[76:79], v[160:163], v[222:225], v[76:79]
	v_mfma_f32_16x16x32_bf16 v[72:75], v[168:171], v[222:225], v[72:75]
	s_setprio 0
	s_setprio 1
	v_mfma_f32_16x16x32_bf16 v[116:119], v[172:175], v[194:197], v[116:119]
	v_mfma_f32_16x16x32_bf16 v[112:115], v[180:183], v[194:197], v[112:115]
	v_mfma_f32_16x16x32_bf16 v[100:103], v[172:175], v[202:205], v[100:103]
	v_mfma_f32_16x16x32_bf16 v[96:99], v[180:183], v[202:205], v[96:99]
	v_mfma_f32_16x16x32_bf16 v[84:87], v[172:175], v[210:213], v[84:87]
	v_mfma_f32_16x16x32_bf16 v[80:83], v[180:183], v[210:213], v[80:83]
	v_mfma_f32_16x16x32_bf16 v[68:71], v[172:175], v[218:221], v[68:71]
	v_mfma_f32_16x16x32_bf16 v[64:67], v[180:183], v[218:221], v[64:67]
	v_mfma_f32_16x16x32_bf16 v[116:119], v[176:179], v[198:201], v[116:119]
	v_mfma_f32_16x16x32_bf16 v[112:115], v[190:193], v[198:201], v[112:115]
	v_mfma_f32_16x16x32_bf16 v[100:103], v[176:179], v[206:209], v[100:103]
	v_mfma_f32_16x16x32_bf16 v[96:99], v[190:193], v[206:209], v[96:99]
	v_mfma_f32_16x16x32_bf16 v[84:87], v[176:179], v[214:217], v[84:87]
	v_mfma_f32_16x16x32_bf16 v[80:83], v[190:193], v[214:217], v[80:83]
	v_mfma_f32_16x16x32_bf16 v[68:71], v[176:179], v[222:225], v[68:71]
	v_mfma_f32_16x16x32_bf16 v[64:67], v[190:193], v[222:225], v[64:67]
	s_barrier
; #define PG8_STAGE(bufoff, gbase, voff) do { _Pragma("unroll") for (int _i = 0; _i < 2; ++_i) \
;         __builtin_amdgcn_global_load_lds((const unsigned*)((const char*)(gbase) + (voff)[_i]), (PG8_LAS unsigned*)(lds + (bufoff) + ldsw + _i * 8192), 16, 0, 0); } while (0)
; #define PG8_LDA(dst, b, h) do { _Pragma("unroll") for (int m = 0; m < 4; ++m) _Pragma("unroll") for (int k = 0; k < 2; ++k) dst[m][k] = *(const PG8_LAS bf16x8*)(lds + PG8_SA(b, h) + aoff + m * 2048 + k * 1024); } while (0)
; #define PG8_MMA(ai, bj, At, Bt) do { __builtin_amdgcn_s_setprio(1); _Pragma("unroll") for (int m = 0; m < 4; ++m) _Pragma("unroll") for (int n = 0; n < 2; ++n) _Pragma("unroll") for (int k = 0; k < 2; ++k) \
;         acc[ai][bj][m][n] = __builtin_amdgcn_mfma_f32_16x16x32_bf16(Bt[n][k], At[m][k], acc[ai][bj][m][n], 0, 0, 0); __builtin_amdgcn_s_setprio(0); } while (0)
; #define PG8_WAIT_V(n) asm volatile("s_waitcnt vmcnt(" #n ")" ::: "memory")
; #define PG8_WAIT_L(n) asm volatile("s_waitcnt lgkmcnt(" #n ")" ::: "memory")
; #define PG8_BAR __builtin_amdgcn_s_barrier()
; #define PG8_SCHED __builtin_amdgcn_sched_barrier(0)
; template <class Epi, class Sched, bool ALIGN_EPI = false, bool SP2 = false>
; __device__ __forceinline__ void gemm_phase(PG8_LAS unsigned char* lds, const Gemm g, const Sched& S, const Epi& E) {
;     ...
;         for (int t = 0; t < nt; t += 2) {
;             const bool last = (t == nt - 2);
;     ...
;             PG8_LDA(At, 1, 1); PG8_STAGE(PG8_SB(1, 0), b3, voffB); PG8_STAGE(PG8_SB(1, 1), b3 + hstepB, voffB); PG8_STAGE(PG8_SA(1, 0), a3, voffA);
;             PG8_WAIT_V(8); PG8_WAIT_L(0); PG8_BAR; PG8_MMA(1, 0, At, B0); PG8_MMA(1, 1, At, B1); PG8_BAR; PG8_SCHED;
	s_setprio 0
	s_add_i32 s44, s53, s7
	v_lshl_add_u64 v[226:227], v[226:227], 0, s[16:17]
	s_mov_b32 m0, s44
	s_nop 0
	global_load_lds_dwordx4 v[226:227], off
	s_add_i32 m0, s44, 0x2000
	s_add_u32 s42, s42, 0x80080
	v_lshl_add_u64 v[226:227], v[228:229], 0, s[16:17]
	s_addc_u32 s43, s43, 0
	s_add_i32 s44, s54, s7
	global_load_lds_dwordx4 v[226:227], off
	v_lshl_add_u64 v[226:227], s[42:43], 0, v[130:131]
	s_mov_b32 m0, s44
	s_nop 0
	global_load_lds_dwordx4 v[226:227], off
	v_lshl_add_u64 v[226:227], s[42:43], 0, v[134:135]
	s_add_i32 m0, s44, 0x2000
	s_nop 0
	global_load_lds_dwordx4 v[226:227], off
	v_lshl_add_u64 v[226:227], v[230:231], 0, s[16:17]
	s_mov_b32 m0, s48
	s_nop 0
	global_load_lds_dwordx4 v[226:227], off
	v_lshl_add_u64 v[226:227], v[232:233], 0, s[16:17]
	s_mov_b32 m0, s49
	s_nop 0
	global_load_lds_dwordx4 v[226:227], off
	ds_read_b128 v[194:197], v154 offset:49152
	ds_read_b128 v[198:201], v154 offset:50176
	ds_read_b128 v[202:205], v154 offset:51200
	ds_read_b128 v[206:209], v154 offset:52224
	ds_read_b128 v[210:213], v154 offset:53248
	ds_read_b128 v[214:217], v154 offset:54272
	ds_read_b128 v[218:221], v154 offset:55296
	ds_read_b128 v[222:225], v154 offset:56320
	s_waitcnt vmcnt(8)
	s_waitcnt lgkmcnt(0)
	s_setprio 1
	s_barrier
	v_mfma_f32_16x16x32_bf16 v[60:63], v[156:159], v[194:197], v[60:63]
	v_mfma_f32_16x16x32_bf16 v[56:59], v[164:167], v[194:197], v[56:59]
	v_mfma_f32_16x16x32_bf16 v[44:47], v[156:159], v[202:205], v[44:47]
	v_mfma_f32_16x16x32_bf16 v[40:43], v[164:167], v[202:205], v[40:43]
	v_mfma_f32_16x16x32_bf16 v[28:31], v[156:159], v[210:213], v[28:31]
	v_mfma_f32_16x16x32_bf16 v[24:27], v[164:167], v[210:213], v[24:27]
	v_mfma_f32_16x16x32_bf16 v[12:15], v[156:159], v[218:221], v[12:15]
	v_mfma_f32_16x16x32_bf16 v[8:11], v[164:167], v[218:221], v[8:11]
	v_mfma_f32_16x16x32_bf16 v[60:63], v[160:163], v[198:201], v[60:63]
	v_mfma_f32_16x16x32_bf16 v[56:59], v[168:171], v[198:201], v[56:59]
	v_mfma_f32_16x16x32_bf16 v[44:47], v[160:163], v[206:209], v[44:47]
	v_mfma_f32_16x16x32_bf16 v[40:43], v[168:171], v[206:209], v[40:43]
	v_mfma_f32_16x16x32_bf16 v[28:31], v[160:163], v[214:217], v[28:31]
	v_mfma_f32_16x16x32_bf16 v[24:27], v[168:171], v[214:217], v[24:27]
	v_mfma_f32_16x16x32_bf16 v[12:15], v[160:163], v[222:225], v[12:15]
	v_mfma_f32_16x16x32_bf16 v[8:11], v[168:171], v[222:225], v[8:11]
	s_setprio 0
	s_setprio 1
	v_mfma_f32_16x16x32_bf16 v[52:55], v[172:175], v[194:197], v[52:55]
	v_mfma_f32_16x16x32_bf16 v[48:51], v[180:183], v[194:197], v[48:51]
	v_mfma_f32_16x16x32_bf16 v[36:39], v[172:175], v[202:205], v[36:39]
	v_mfma_f32_16x16x32_bf16 v[32:35], v[180:183], v[202:205], v[32:35]
	v_mfma_f32_16x16x32_bf16 v[20:23], v[172:175], v[210:213], v[20:23]
	v_mfma_f32_16x16x32_bf16 v[16:19], v[180:183], v[210:213], v[16:19]
	v_mfma_f32_16x16x32_bf16 v[4:7], v[172:175], v[218:221], v[4:7]
	v_mfma_f32_16x16x32_bf16 v[0:3], v[180:183], v[218:221], v[0:3]
	v_mfma_f32_16x16x32_bf16 v[52:55], v[176:179], v[198:201], v[52:55]
	v_mfma_f32_16x16x32_bf16 v[48:51], v[190:193], v[198:201], v[48:51]
	v_mfma_f32_16x16x32_bf16 v[36:39], v[176:179], v[206:209], v[36:39]
	v_mfma_f32_16x16x32_bf16 v[32:35], v[190:193], v[206:209], v[32:35]
	v_mfma_f32_16x16x32_bf16 v[20:23], v[176:179], v[214:217], v[20:23]
	v_mfma_f32_16x16x32_bf16 v[16:19], v[190:193], v[214:217], v[16:19]
	v_mfma_f32_16x16x32_bf16 v[4:7], v[176:179], v[222:225], v[4:7]
	v_mfma_f32_16x16x32_bf16 v[0:3], v[190:193], v[222:225], v[0:3]
	s_barrier
	s_setprio 0
	s_add_i32 s35, s35, 2
	s_add_u32 s40, s40, 0x100
	s_addc_u32 s41, s41, 0
	s_add_u32 s21, s21, 0x100
	s_addc_u32 s23, s23, 0
	s_cmp_gt_u32 s35, 29
	s_cbranch_scc0 .LBB0_3058
	s_and_b64 vcc, exec, s[18:19]
	s_cbranch_vccz .LBB0_3061
	s_barrier

; #define PG8_STAGE(bufoff, gbase, voff) do { _Pragma("unroll") for (int _i = 0; _i < 2; ++_i) \
;         __builtin_amdgcn_global_load_lds((const unsigned*)((const char*)(gbase) + (voff)[_i]), (PG8_LAS unsigned*)(lds + (bufoff) + ldsw + _i * 8192), 16, 0, 0); } while (0)
; #define PG8_LDA(dst, b, h) do { _Pragma("unroll") for (int m = 0; m < 4; ++m) _Pragma("unroll") for (int k = 0; k < 2; ++k) dst[m][k] = *(const PG8_LAS bf16x8*)(lds + PG8_SA(b, h) + aoff + m * 2048 + k * 1024); } while (0)
; #define PG8_LDB(dst, b, h) do { _Pragma("unroll") for (int n = 0; n < 2; ++n) _Pragma("unroll") for (int k = 0; k < 2; ++k) dst[n][k] = *(const PG8_LAS bf16x8*)(lds + PG8_SB(b, h) + boff + n * 2048 + k * 1024); } while (0)
; #define PG8_MMA(ai, bj, At, Bt) do { __builtin_amdgcn_s_setprio(1); _Pragma("unroll") for (int m = 0; m < 4; ++m) _Pragma("unroll") for (int n = 0; n < 2; ++n) _Pragma("unroll") for (int k = 0; k < 2; ++k) \
;         acc[ai][bj][m][n] = __builtin_amdgcn_mfma_f32_16x16x32_bf16(Bt[n][k], At[m][k], acc[ai][bj][m][n], 0, 0, 0); __builtin_amdgcn_s_setprio(0); } while (0)
; #define PG8_WAIT_V(n) asm volatile("s_waitcnt vmcnt(" #n ")" ::: "memory")
; #define PG8_BAR __builtin_amdgcn_s_barrier()
; template <class Epi, class Sched, bool ALIGN_EPI = false, bool SP2 = false>
; __device__ __forceinline__ void gemm_phase(PG8_LAS unsigned char* lds, const Gemm g, const Sched& S, const Epi& E) {
;     ...
;         for (int t = 0; t < nt; t += 2) {
;             const bool last = (t == nt - 2);
;             const char* a1 = cA + (size_t)(t + 1) * kstA;
;             const char* a2 = last ? nA : cA + (size_t)(t + 2) * kstA; const char* b2 = last ? nB : cB + (size_t)(t + 2) * kstep;
;             const char* a3 = a2 + kstA; const char* b3 = b2 + kstep;
;             if (last && has_next) S.a_ready(nxt);
;             if constexpr (SP2) {
;             PG8_LDB(B0, 0, 0); PG8_LDB(B1, 0, 1); PG8_SCHED; PG8_LDA(At, 0, 0); PG8_STAGE(PG8_SA(1, 1), a1 + hstepA, voffA);
;             PG8_WAIT_V(8); PG8_WAIT_L(0); PG8_BAR; PG8_MMA(0, 0, At, B0); PG8_MMA(0, 1, At, B1); PG8_BAR; PG8_SCHED;
;             PG8_LDA(At, 0, 1); PG8_STAGE(PG8_SB(0, 0), b2, voffB); PG8_STAGE(PG8_SB(0, 1), b2 + hstepB, voffB); PG8_STAGE(PG8_SA(0, 0), a2, voffA);
;             PG8_WAIT_V(8); PG8_WAIT_L(0); PG8_BAR; PG8_MMA(1, 0, At, B0); PG8_MMA(1, 1, At, B1); PG8_BAR; PG8_SCHED;
.LBB0_3147:
	s_add_u32 s12, s20, s46
	s_addc_u32 s13, s21, s47
	s_cmp_eq_u32 s7, s5
	s_cselect_b32 s52, s42, s12
	s_cselect_b32 s53, s43, s13
	s_cselect_b32 s51, s45, s4
	s_cselect_b32 s50, s44, s1
	s_add_u32 s48, s52, 0x8000
	s_addc_u32 s49, s53, 0
	v_lshl_add_u64 v[176:177], s[20:21], 0, v[162:163]
	s_add_i32 m0, s55, 0xc000
	s_nop 0
	global_load_lds_dwordx4 v[176:177], off
	v_lshl_add_u64 v[176:177], s[20:21], 0, v[160:161]
	s_add_i32 m0, s55, 0xe000
	s_nop 0
	global_load_lds_dwordx4 v[176:177], off
	v_add_u32_e32 v176, s64, v178
	ds_read_b128 v[164:167], v176
	ds_read_b128 v[168:171], v176 offset:1024
	ds_read_b128 v[172:175], v176 offset:2048
	ds_read_b128 v[190:193], v176 offset:3072
	v_add_u32_e32 v176, s65, v178
	ds_read_b128 v[194:197], v176
	ds_read_b128 v[198:201], v176 offset:1024
	ds_read_b128 v[202:205], v176 offset:2048
	ds_read_b128 v[206:209], v176 offset:3072
	ds_read_b128 v[210:213], v180
	ds_read_b128 v[214:217], v180 offset:1024
	ds_read_b128 v[218:221], v180 offset:2048
	ds_read_b128 v[222:225], v180 offset:3072
	ds_read_b128 v[226:229], v180 offset:4096
	ds_read_b128 v[230:233], v180 offset:5120
	ds_read_b128 v[234:237], v180 offset:6144
	ds_read_b128 v[238:241], v180 offset:7168
	s_waitcnt vmcnt(8)
	s_waitcnt lgkmcnt(0)
	s_setprio 1
	s_barrier
	v_mfma_f32_16x16x32_bf16 v[124:127], v[164:167], v[210:213], v[124:127]
	v_mfma_f32_16x16x32_bf16 v[120:123], v[172:175], v[210:213], v[120:123]
	v_mfma_f32_16x16x32_bf16 v[116:119], v[164:167], v[218:221], v[116:119]
	v_mfma_f32_16x16x32_bf16 v[112:115], v[172:175], v[218:221], v[112:115]
	v_mfma_f32_16x16x32_bf16 v[108:111], v[164:167], v[226:229], v[108:111]
	v_mfma_f32_16x16x32_bf16 v[104:107], v[172:175], v[226:229], v[104:107]
	v_mfma_f32_16x16x32_bf16 v[100:103], v[164:167], v[234:237], v[100:103]
	v_mfma_f32_16x16x32_bf16 v[96:99], v[172:175], v[234:237], v[96:99]
	v_mfma_f32_16x16x32_bf16 v[124:127], v[168:171], v[214:217], v[124:127]
	v_mfma_f32_16x16x32_bf16 v[120:123], v[190:193], v[214:217], v[120:123]
	v_mfma_f32_16x16x32_bf16 v[116:119], v[168:171], v[222:225], v[116:119]
	v_mfma_f32_16x16x32_bf16 v[112:115], v[190:193], v[222:225], v[112:115]
	v_mfma_f32_16x16x32_bf16 v[108:111], v[168:171], v[230:233], v[108:111]
	v_mfma_f32_16x16x32_bf16 v[104:107], v[190:193], v[230:233], v[104:107]
	v_mfma_f32_16x16x32_bf16 v[100:103], v[168:171], v[238:241], v[100:103]
	v_mfma_f32_16x16x32_bf16 v[96:99], v[190:193], v[238:241], v[96:99]
	s_setprio 0
	s_setprio 1
	v_mfma_f32_16x16x32_bf16 v[92:95], v[194:197], v[210:213], v[92:95]
	v_mfma_f32_16x16x32_bf16 v[88:91], v[202:205], v[210:213], v[88:91]
	v_mfma_f32_16x16x32_bf16 v[84:87], v[194:197], v[218:221], v[84:87]
	v_mfma_f32_16x16x32_bf16 v[80:83], v[202:205], v[218:221], v[80:83]
	v_mfma_f32_16x16x32_bf16 v[76:79], v[194:197], v[226:229], v[76:79]
	v_mfma_f32_16x16x32_bf16 v[72:75], v[202:205], v[226:229], v[72:75]
	v_mfma_f32_16x16x32_bf16 v[68:71], v[194:197], v[234:237], v[68:71]
	v_mfma_f32_16x16x32_bf16 v[64:67], v[202:205], v[234:237], v[64:67]
	v_mfma_f32_16x16x32_bf16 v[92:95], v[198:201], v[214:217], v[92:95]
	v_mfma_f32_16x16x32_bf16 v[88:91], v[206:209], v[214:217], v[88:91]
	v_mfma_f32_16x16x32_bf16 v[84:87], v[198:201], v[222:225], v[84:87]
	v_mfma_f32_16x16x32_bf16 v[80:83], v[206:209], v[222:225], v[80:83]
	v_mfma_f32_16x16x32_bf16 v[76:79], v[198:201], v[230:233], v[76:79]
	v_mfma_f32_16x16x32_bf16 v[72:75], v[206:209], v[230:233], v[72:75]
	v_mfma_f32_16x16x32_bf16 v[68:71], v[198:201], v[238:241], v[68:71]
	v_mfma_f32_16x16x32_bf16 v[64:67], v[206:209], v[238:241], v[64:67]
	s_barrier
	s_setprio 0
	s_add_i32 s12, s64, s54
	v_lshl_add_u64 v[176:177], s[50:51], 0, v[130:131]
	s_mov_b32 m0, s12
	s_nop 0
	global_load_lds_dwordx4 v[176:177], off
	s_add_i32 m0, s12, 0x2000
	s_add_u32 s12, s50, 0x160000
	v_lshl_add_u64 v[182:183], s[50:51], 0, v[134:135]
	s_addc_u32 s13, s51, 0
	s_add_i32 s17, s65, s54
	global_load_lds_dwordx4 v[182:183], off
	v_lshl_add_u64 v[242:243], s[12:13], 0, v[130:131]
	s_mov_b32 m0, s17
	s_nop 0
	global_load_lds_dwordx4 v[242:243], off
	v_lshl_add_u64 v[242:243], s[12:13], 0, v[134:135]
	s_add_i32 m0, s17, 0x2000
	s_nop 0
	global_load_lds_dwordx4 v[242:243], off
	v_lshl_add_u64 v[242:243], s[52:53], 0, v[128:129]
	s_mov_b32 m0, s55
	s_nop 0
	global_load_lds_dwordx4 v[242:243], off
	v_lshl_add_u64 v[242:243], s[52:53], 0, v[132:133]
	s_mov_b32 m0, s56
	s_nop 0
	global_load_lds_dwordx4 v[242:243], off
	ds_read_b128 v[210:213], v180 offset:16384
	ds_read_b128 v[214:217], v180 offset:17408
	ds_read_b128 v[218:221], v180 offset:18432
	ds_read_b128 v[222:225], v180 offset:19456
	ds_read_b128 v[226:229], v180 offset:20480
	ds_read_b128 v[230:233], v180 offset:21504
	ds_read_b128 v[234:237], v180 offset:22528
	ds_read_b128 v[238:241], v180 offset:23552
	s_waitcnt vmcnt(8)
	s_waitcnt lgkmcnt(0)
	s_setprio 1
	s_barrier
; #define PG8_STAGE(bufoff, gbase, voff) do { _Pragma("unroll") for (int _i = 0; _i < 2; ++_i) \
;         __builtin_amdgcn_global_load_lds((const unsigned*)((const char*)(gbase) + (voff)[_i]), (PG8_LAS unsigned*)(lds + (bufoff) + ldsw + _i * 8192), 16, 0, 0); } while (0)
; #define PG8_LDA(dst, b, h) do { _Pragma("unroll") for (int m = 0; m < 4; ++m) _Pragma("unroll") for (int k = 0; k < 2; ++k) dst[m][k] = *(const PG8_LAS bf16x8*)(lds + PG8_SA(b, h) + aoff + m * 2048 + k * 1024); } while (0)
; #define PG8_LDB(dst, b, h) do { _Pragma("unroll") for (int n = 0; n < 2; ++n) _Pragma("unroll") for (int k = 0; k < 2; ++k) dst[n][k] = *(const PG8_LAS bf16x8*)(lds + PG8_SB(b, h) + boff + n * 2048 + k * 1024); } while (0)
; #define PG8_MMA(ai, bj, At, Bt) do { __builtin_amdgcn_s_setprio(1); _Pragma("unroll") for (int m = 0; m < 4; ++m) _Pragma("unroll") for (int n = 0; n < 2; ++n) _Pragma("unroll") for (int k = 0; k < 2; ++k) \
;         acc[ai][bj][m][n] = __builtin_amdgcn_mfma_f32_16x16x32_bf16(Bt[n][k], At[m][k], acc[ai][bj][m][n], 0, 0, 0); __builtin_amdgcn_s_setprio(0); } while (0)
; #define PG8_WAIT_V(n) asm volatile("s_waitcnt vmcnt(" #n ")" ::: "memory")
; #define PG8_WAIT_L(n) asm volatile("s_waitcnt lgkmcnt(" #n ")" ::: "memory")
; #define PG8_BAR __builtin_amdgcn_s_barrier()
; #define PG8_SCHED __builtin_amdgcn_sched_barrier(0)
; template <class Epi, class Sched, bool ALIGN_EPI = false, bool SP2 = false>
; __device__ __forceinline__ void gemm_phase(PG8_LAS unsigned char* lds, const Gemm g, const Sched& S, const Epi& E) {
;     ...
;             PG8_WAIT_V(8); PG8_WAIT_L(0); PG8_BAR; PG8_MMA(1, 0, At, B0); PG8_MMA(1, 1, At, B1); PG8_BAR; PG8_SCHED;
;             PG8_LDB(B0, 1, 0); PG8_LDB(B1, 1, 1); PG8_SCHED; PG8_LDA(At, 1, 0); PG8_STAGE(PG8_SA(0, 1), a2 + hstepA, voffA);
;             PG8_WAIT_V(8); PG8_WAIT_L(0); PG8_BAR; PG8_MMA(0, 0, At, B0); PG8_MMA(0, 1, At, B1); PG8_BAR; PG8_SCHED;
	v_mfma_f32_16x16x32_bf16 v[60:63], v[164:167], v[210:213], v[60:63]
	v_mfma_f32_16x16x32_bf16 v[56:59], v[172:175], v[210:213], v[56:59]
	v_mfma_f32_16x16x32_bf16 v[52:55], v[164:167], v[218:221], v[52:55]
	v_mfma_f32_16x16x32_bf16 v[48:51], v[172:175], v[218:221], v[48:51]
	v_mfma_f32_16x16x32_bf16 v[44:47], v[164:167], v[226:229], v[44:47]
	v_mfma_f32_16x16x32_bf16 v[40:43], v[172:175], v[226:229], v[40:43]
	v_mfma_f32_16x16x32_bf16 v[36:39], v[164:167], v[234:237], v[36:39]
	v_mfma_f32_16x16x32_bf16 v[32:35], v[172:175], v[234:237], v[32:35]
	v_mfma_f32_16x16x32_bf16 v[60:63], v[168:171], v[214:217], v[60:63]
	v_mfma_f32_16x16x32_bf16 v[56:59], v[190:193], v[214:217], v[56:59]
	v_mfma_f32_16x16x32_bf16 v[52:55], v[168:171], v[222:225], v[52:55]
	v_mfma_f32_16x16x32_bf16 v[48:51], v[190:193], v[222:225], v[48:51]
	v_mfma_f32_16x16x32_bf16 v[44:47], v[168:171], v[230:233], v[44:47]
	v_mfma_f32_16x16x32_bf16 v[40:43], v[190:193], v[230:233], v[40:43]
	v_mfma_f32_16x16x32_bf16 v[36:39], v[168:171], v[238:241], v[36:39]
	v_mfma_f32_16x16x32_bf16 v[32:35], v[190:193], v[238:241], v[32:35]
	s_setprio 0
	s_setprio 1
	v_mfma_f32_16x16x32_bf16 v[28:31], v[194:197], v[210:213], v[28:31]
	v_mfma_f32_16x16x32_bf16 v[24:27], v[202:205], v[210:213], v[24:27]
	v_mfma_f32_16x16x32_bf16 v[20:23], v[194:197], v[218:221], v[20:23]
	v_mfma_f32_16x16x32_bf16 v[16:19], v[202:205], v[218:221], v[16:19]
	v_mfma_f32_16x16x32_bf16 v[12:15], v[194:197], v[226:229], v[12:15]
	v_mfma_f32_16x16x32_bf16 v[8:11], v[202:205], v[226:229], v[8:11]
	v_mfma_f32_16x16x32_bf16 v[4:7], v[194:197], v[234:237], v[4:7]
	v_mfma_f32_16x16x32_bf16 v[0:3], v[202:205], v[234:237], v[0:3]
	v_mfma_f32_16x16x32_bf16 v[28:31], v[198:201], v[214:217], v[28:31]
	v_mfma_f32_16x16x32_bf16 v[24:27], v[206:209], v[214:217], v[24:27]
	v_mfma_f32_16x16x32_bf16 v[20:23], v[198:201], v[222:225], v[20:23]
	v_mfma_f32_16x16x32_bf16 v[16:19], v[206:209], v[222:225], v[16:19]
	v_mfma_f32_16x16x32_bf16 v[12:15], v[198:201], v[230:233], v[12:15]
	v_mfma_f32_16x16x32_bf16 v[8:11], v[206:209], v[230:233], v[8:11]
	v_mfma_f32_16x16x32_bf16 v[4:7], v[198:201], v[238:241], v[4:7]
	v_mfma_f32_16x16x32_bf16 v[0:3], v[206:209], v[238:241], v[0:3]
	s_barrier
	s_setprio 0
	s_add_i32 s17, 0, 0x18000
	s_add_i32 s19, 0, 0x1c000
	s_add_u32 s12, s52, 0x4000
	s_addc_u32 s13, s53, 0
	s_mov_b32 m0, s57
	v_lshl_add_u64 v[242:243], s[12:13], 0, v[128:129]
	global_load_lds_dwordx4 v[242:243], off
	v_lshl_add_u64 v[242:243], s[12:13], 0, v[132:133]
	s_mov_b32 m0, s58
	s_nop 0
	global_load_lds_dwordx4 v[242:243], off
	v_add_u32_e32 v181, s17, v178
	ds_read_b128 v[164:167], v181
	ds_read_b128 v[168:171], v181 offset:1024
	ds_read_b128 v[172:175], v181 offset:2048
	ds_read_b128 v[190:193], v181 offset:3072
	v_add_u32_e32 v181, s19, v178
	ds_read_b128 v[194:197], v181
	ds_read_b128 v[198:201], v181 offset:1024
	ds_read_b128 v[202:205], v181 offset:2048
	ds_read_b128 v[206:209], v181 offset:3072
	ds_read_b128 v[210:213], v180 offset:32768
	ds_read_b128 v[214:217], v180 offset:33792
	ds_read_b128 v[218:221], v180 offset:34816
	ds_read_b128 v[222:225], v180 offset:35840
	ds_read_b128 v[226:229], v180 offset:36864
	ds_read_b128 v[230:233], v180 offset:37888
	ds_read_b128 v[234:237], v180 offset:38912
	ds_read_b128 v[238:241], v180 offset:39936
	s_waitcnt vmcnt(8)
	s_waitcnt lgkmcnt(0)
	s_setprio 1
	s_barrier
	v_mfma_f32_16x16x32_bf16 v[124:127], v[164:167], v[210:213], v[124:127]
	v_mfma_f32_16x16x32_bf16 v[120:123], v[172:175], v[210:213], v[120:123]
	v_mfma_f32_16x16x32_bf16 v[116:119], v[164:167], v[218:221], v[116:119]
	v_mfma_f32_16x16x32_bf16 v[112:115], v[172:175], v[218:221], v[112:115]
	v_mfma_f32_16x16x32_bf16 v[108:111], v[164:167], v[226:229], v[108:111]
	v_mfma_f32_16x16x32_bf16 v[104:107], v[172:175], v[226:229], v[104:107]
	v_mfma_f32_16x16x32_bf16 v[100:103], v[164:167], v[234:237], v[100:103]
	v_mfma_f32_16x16x32_bf16 v[96:99], v[172:175], v[234:237], v[96:99]
	v_mfma_f32_16x16x32_bf16 v[124:127], v[168:171], v[214:217], v[124:127]
	v_mfma_f32_16x16x32_bf16 v[120:123], v[190:193], v[214:217], v[120:123]
	v_mfma_f32_16x16x32_bf16 v[116:119], v[168:171], v[222:225], v[116:119]
	v_mfma_f32_16x16x32_bf16 v[112:115], v[190:193], v[222:225], v[112:115]
	v_mfma_f32_16x16x32_bf16 v[108:111], v[168:171], v[230:233], v[108:111]
	v_mfma_f32_16x16x32_bf16 v[104:107], v[190:193], v[230:233], v[104:107]
	v_mfma_f32_16x16x32_bf16 v[100:103], v[168:171], v[238:241], v[100:103]
	v_mfma_f32_16x16x32_bf16 v[96:99], v[190:193], v[238:241], v[96:99]
	s_setprio 0
	s_setprio 1
	v_mfma_f32_16x16x32_bf16 v[92:95], v[194:197], v[210:213], v[92:95]
	v_mfma_f32_16x16x32_bf16 v[88:91], v[202:205], v[210:213], v[88:91]
	v_mfma_f32_16x16x32_bf16 v[84:87], v[194:197], v[218:221], v[84:87]
	v_mfma_f32_16x16x32_bf16 v[80:83], v[202:205], v[218:221], v[80:83]
	v_mfma_f32_16x16x32_bf16 v[76:79], v[194:197], v[226:229], v[76:79]
	v_mfma_f32_16x16x32_bf16 v[72:75], v[202:205], v[226:229], v[72:75]
	v_mfma_f32_16x16x32_bf16 v[68:71], v[194:197], v[234:237], v[68:71]
	v_mfma_f32_16x16x32_bf16 v[64:67], v[202:205], v[234:237], v[64:67]
	v_mfma_f32_16x16x32_bf16 v[92:95], v[198:201], v[214:217], v[92:95]
	v_mfma_f32_16x16x32_bf16 v[88:91], v[206:209], v[214:217], v[88:91]
	v_mfma_f32_16x16x32_bf16 v[84:87], v[198:201], v[222:225], v[84:87]
	v_mfma_f32_16x16x32_bf16 v[80:83], v[206:209], v[222:225], v[80:83]
	v_mfma_f32_16x16x32_bf16 v[76:79], v[198:201], v[230:233], v[76:79]
	v_mfma_f32_16x16x32_bf16 v[72:75], v[206:209], v[230:233], v[72:75]
	v_mfma_f32_16x16x32_bf16 v[68:71], v[198:201], v[238:241], v[68:71]
	v_mfma_f32_16x16x32_bf16 v[64:67], v[206:209], v[238:241], v[64:67]
	s_barrier
; #define PG8_STAGE(bufoff, gbase, voff) do { _Pragma("unroll") for (int _i = 0; _i < 2; ++_i) \
;         __builtin_amdgcn_global_load_lds((const unsigned*)((const char*)(gbase) + (voff)[_i]), (PG8_LAS unsigned*)(lds + (bufoff) + ldsw + _i * 8192), 16, 0, 0); } while (0)
; #define PG8_LDA(dst, b, h) do { _Pragma("unroll") for (int m = 0; m < 4; ++m) _Pragma("unroll") for (int k = 0; k < 2; ++k) dst[m][k] = *(const PG8_LAS bf16x8*)(lds + PG8_SA(b, h) + aoff + m * 2048 + k * 1024); } while (0)
; #define PG8_MMA(ai, bj, At, Bt) do { __builtin_amdgcn_s_setprio(1); _Pragma("unroll") for (int m = 0; m < 4; ++m) _Pragma("unroll") for (int n = 0; n < 2; ++n) _Pragma("unroll") for (int k = 0; k < 2; ++k) \
;         acc[ai][bj][m][n] = __builtin_amdgcn_mfma_f32_16x16x32_bf16(Bt[n][k], At[m][k], acc[ai][bj][m][n], 0, 0, 0); __builtin_amdgcn_s_setprio(0); } while (0)
; #define PG8_WAIT_V(n) asm volatile("s_waitcnt vmcnt(" #n ")" ::: "memory")
; #define PG8_WAIT_L(n) asm volatile("s_waitcnt lgkmcnt(" #n ")" ::: "memory")
; #define PG8_BAR __builtin_amdgcn_s_barrier()
; #define PG8_SCHED __builtin_amdgcn_sched_barrier(0)
; template <class Epi, class Sched, bool ALIGN_EPI = false, bool SP2 = false>
; __device__ __forceinline__ void gemm_phase(PG8_LAS unsigned char* lds, const Gemm g, const Sched& S, const Epi& E) {
;     ...
;         for (int t = 0; t < nt; t += 2) {
;     ...
;             PG8_LDA(At, 1, 1); PG8_STAGE(PG8_SB(1, 0), b3, voffB); PG8_STAGE(PG8_SB(1, 1), b3 + hstepB, voffB); PG8_STAGE(PG8_SA(1, 0), a3, voffA);
;             PG8_WAIT_V(8); PG8_WAIT_L(0); PG8_BAR; PG8_MMA(1, 0, At, B0); PG8_MMA(1, 1, At, B1); PG8_BAR; PG8_SCHED;
	s_setprio 0
	s_add_i32 s12, s17, s54
	v_lshl_add_u64 v[176:177], v[176:177], 0, s[30:31]
	s_mov_b32 m0, s12
	s_nop 0
	global_load_lds_dwordx4 v[176:177], off
	s_add_i32 m0, s12, 0x2000
	s_add_u32 s12, s50, 0x160080
	v_lshl_add_u64 v[176:177], v[182:183], 0, s[30:31]
	s_addc_u32 s13, s51, 0
	s_add_i32 s17, s19, s54
	global_load_lds_dwordx4 v[176:177], off
	v_lshl_add_u64 v[176:177], s[12:13], 0, v[130:131]
	s_mov_b32 m0, s17
	s_nop 0
	global_load_lds_dwordx4 v[176:177], off
	v_lshl_add_u64 v[176:177], s[12:13], 0, v[134:135]
	s_add_i32 m0, s17, 0x2000
	s_nop 0
	global_load_lds_dwordx4 v[176:177], off
	v_lshl_add_u64 v[176:177], s[48:49], 0, v[128:129]
	s_mov_b32 m0, s62
	s_nop 0
	global_load_lds_dwordx4 v[176:177], off
	v_lshl_add_u64 v[176:177], s[48:49], 0, v[132:133]
	s_mov_b32 m0, s63
	s_nop 0
	global_load_lds_dwordx4 v[176:177], off
	ds_read_b128 v[210:213], v180 offset:49152
	ds_read_b128 v[214:217], v180 offset:50176
	ds_read_b128 v[218:221], v180 offset:51200
	ds_read_b128 v[222:225], v180 offset:52224
	ds_read_b128 v[226:229], v180 offset:53248
	ds_read_b128 v[230:233], v180 offset:54272
	ds_read_b128 v[234:237], v180 offset:55296
	ds_read_b128 v[238:241], v180 offset:56320
	s_waitcnt vmcnt(8)
	s_waitcnt lgkmcnt(0)
	s_setprio 1
	s_barrier
	v_mfma_f32_16x16x32_bf16 v[60:63], v[164:167], v[210:213], v[60:63]
	v_mfma_f32_16x16x32_bf16 v[56:59], v[172:175], v[210:213], v[56:59]
	v_mfma_f32_16x16x32_bf16 v[52:55], v[164:167], v[218:221], v[52:55]
	v_mfma_f32_16x16x32_bf16 v[48:51], v[172:175], v[218:221], v[48:51]
	v_mfma_f32_16x16x32_bf16 v[44:47], v[164:167], v[226:229], v[44:47]
	v_mfma_f32_16x16x32_bf16 v[40:43], v[172:175], v[226:229], v[40:43]
	v_mfma_f32_16x16x32_bf16 v[36:39], v[164:167], v[234:237], v[36:39]
	v_mfma_f32_16x16x32_bf16 v[32:35], v[172:175], v[234:237], v[32:35]
	v_mfma_f32_16x16x32_bf16 v[60:63], v[168:171], v[214:217], v[60:63]
	v_mfma_f32_16x16x32_bf16 v[56:59], v[190:193], v[214:217], v[56:59]
	v_mfma_f32_16x16x32_bf16 v[52:55], v[168:171], v[222:225], v[52:55]
	v_mfma_f32_16x16x32_bf16 v[48:51], v[190:193], v[222:225], v[48:51]
	v_mfma_f32_16x16x32_bf16 v[44:47], v[168:171], v[230:233], v[44:47]
	v_mfma_f32_16x16x32_bf16 v[40:43], v[190:193], v[230:233], v[40:43]
	v_mfma_f32_16x16x32_bf16 v[36:39], v[168:171], v[238:241], v[36:39]
	v_mfma_f32_16x16x32_bf16 v[32:35], v[190:193], v[238:241], v[32:35]
	s_setprio 0
	s_setprio 1
	v_mfma_f32_16x16x32_bf16 v[28:31], v[194:197], v[210:213], v[28:31]
	v_mfma_f32_16x16x32_bf16 v[24:27], v[202:205], v[210:213], v[24:27]
	v_mfma_f32_16x16x32_bf16 v[20:23], v[194:197], v[218:221], v[20:23]
	v_mfma_f32_16x16x32_bf16 v[16:19], v[202:205], v[218:221], v[16:19]
	v_mfma_f32_16x16x32_bf16 v[12:15], v[194:197], v[226:229], v[12:15]
	v_mfma_f32_16x16x32_bf16 v[8:11], v[202:205], v[226:229], v[8:11]
	v_mfma_f32_16x16x32_bf16 v[4:7], v[194:197], v[234:237], v[4:7]
	v_mfma_f32_16x16x32_bf16 v[0:3], v[202:205], v[234:237], v[0:3]
	v_mfma_f32_16x16x32_bf16 v[28:31], v[198:201], v[214:217], v[28:31]
	v_mfma_f32_16x16x32_bf16 v[24:27], v[206:209], v[214:217], v[24:27]
	v_mfma_f32_16x16x32_bf16 v[20:23], v[198:201], v[222:225], v[20:23]
	v_mfma_f32_16x16x32_bf16 v[16:19], v[206:209], v[222:225], v[16:19]
	v_mfma_f32_16x16x32_bf16 v[12:15], v[198:201], v[230:233], v[12:15]
	v_mfma_f32_16x16x32_bf16 v[8:11], v[206:209], v[230:233], v[8:11]
	v_mfma_f32_16x16x32_bf16 v[4:7], v[198:201], v[238:241], v[4:7]
	v_mfma_f32_16x16x32_bf16 v[0:3], v[206:209], v[238:241], v[0:3]
	s_barrier
	s_setprio 0
	s_add_i32 s12, s5, 2
	s_add_u32 s46, s46, 0x10000
	s_addc_u32 s47, s47, 0
	s_add_u32 s1, s1, 0x100
	s_addc_u32 s4, s4, 0
	v_lshl_add_u64 v[162:163], v[162:163], 0, s[38:39]
	v_lshl_add_u64 v[160:161], v[160:161], 0, s[38:39]
	s_cmp_ge_i32 s5, s7
	s_mov_b32 s5, s12
	s_cbranch_scc0 .LBB0_3147
	s_and_b64 vcc, exec, s[36:37]
	s_cbranch_vccz .LBB0_3150
	s_barrier
